# v33 + leading half-workgroup defers its K-loop vmcnt wait to the end of its next MFMA block (one more interval of LDS-DMA flight time)
# baseline (speedup 1.0000x reference)
; #define PG8_STAGE(bufoff, gbase, voff) do { _Pragma("unroll") for (int _i = 0; _i < 2; ++_i) \
;         __builtin_amdgcn_global_load_lds((const unsigned*)((const char*)(gbase) + (voff)[_i]), (PG8_LAS unsigned*)(lds + (bufoff) + ldsw + _i * 8192), 16, 0, 0); } while (0)
; #define PG8_LDA(dst, b, h) do { _Pragma("unroll") for (int m = 0; m < 4; ++m) _Pragma("unroll") for (int k = 0; k < 2; ++k) dst[m][k] = *(const PG8_LAS bf16x8*)(lds + PG8_SA(b, h) + aoff + m * 2048 + k * 1024); } while (0)
; #define PG8_LDB(dst, b, h) do { _Pragma("unroll") for (int n = 0; n < 2; ++n) _Pragma("unroll") for (int k = 0; k < 2; ++k) dst[n][k] = *(const PG8_LAS bf16x8*)(lds + PG8_SB(b, h) + boff + n * 2048 + k * 1024); } while (0)
; #define PG8_WAIT_V(n) asm volatile("s_waitcnt vmcnt(" #n ")" ::: "memory")
; #define PG8_WAIT_L(n) asm volatile("s_waitcnt lgkmcnt(" #n ")" ::: "memory")
; #define PG8_BAR __builtin_amdgcn_s_barrier()
; #define PG8_SCHED __builtin_amdgcn_sched_barrier(0)
; template <class Epi, class Sched, bool ALIGN_EPI = false, bool SP2 = false, bool A_TILED = false>
; __device__ __forceinline__ void gemm_phase(PG8_LAS unsigned char* lds, const Gemm g, const Sched& S, const Epi& E) {
;     ...
;         const bool has_next = S.next(ui + 1, nxt);
;         const char* nA = has_next ? (const char*)g.A + (size_t)nxt.pm * tstepA : cA; const char* nB = has_next ? (const char*)g.Bt + (size_t)nxt.pn * tstepB : cB;
;         for (int t = 0; t < nt; t += 2) {
;             const bool last = (t == nt - 2);
;             const char* a1 = cA + (size_t)(t + 1) * kstepA;
;             const char* a2 = last ? nA : cA + (size_t)(t + 2) * kstepA; const char* b2 = last ? nB : cB + (size_t)(t + 2) * kstepB;
;             const char* a3 = a2 + kstepA; const char* b3 = b2 + kstepB;
;             if (last && has_next) S.a_ready(nxt);
;             if constexpr (SP2) {
;             PG8_LDB(B0, 0, 0); PG8_LDB(B1, 0, 1); PG8_SCHED; PG8_LDA(At, 0, 0); PG8_STAGE(PG8_SA(1, 1), a1 + hstepA, voffA);
;             PG8_WAIT_V(8); PG8_WAIT_L(0); PG8_BAR; PG8_MMA(0, 0, At, B0); PG8_MMA(0, 1, At, B1); PG8_BAR; PG8_SCHED;
;             PG8_LDA(At, 0, 1); PG8_STAGE(PG8_SB(0, 0), b2, voffB); PG8_STAGE(PG8_SB(0, 1), b2 + hstepB, voffB); PG8_STAGE(PG8_SA(0, 0), a2, voffA);
;             PG8_WAIT_V(8); PG8_WAIT_L(0); PG8_BAR; PG8_MMA(1, 0, At, B0); PG8_MMA(1, 1, At, B1); PG8_BAR; PG8_SCHED;
.LBB0_194:
	s_ashr_i32 s15, s14, 31
	s_lshl_b64 s[16:17], s[14:15], 21
	s_add_u32 s16, s78, s16
	s_addc_u32 s17, s79, s17
	s_and_b64 s[18:19], s[0:1], exec
	s_cselect_b32 s15, s17, s23
	s_cselect_b32 s59, s16, s22
	s_ashr_i32 s13, s12, 31
	s_lshl_b64 s[18:19], s[12:13], 21
	s_add_u32 s18, s3, s18
	s_addc_u32 s19, s33, s19
	s_and_b64 s[28:29], s[0:1], exec
	s_cselect_b32 s13, s19, s27
	s_cselect_b32 s62, s18, s26
	s_add_u32 s22, s22, 0xc000
	s_addc_u32 s23, s23, 0
	s_add_u32 s63, s26, 0x10000
	v_mov_b32_e32 v2, 0
	s_addc_u32 s69, s27, 0
	s_mov_b32 s70, -2
	ds_read_b128 v[168:171], v164
	ds_read_b128 v[172:175], v164 offset:1024
	ds_read_b128 v[176:179], v164 offset:2048
	ds_read_b128 v[180:183], v164 offset:3072
	ds_read_b128 v[184:187], v165
	ds_read_b128 v[188:191], v165 offset:1024
	ds_read_b128 v[192:195], v165 offset:2048
	ds_read_b128 v[196:199], v165 offset:3072
	s_add_u32 s26, s22, 0x4000
	s_addc_u32 s27, s23, 0
	s_cmp_eq_u32 s70, 60
	s_cselect_b32 s30, s59, s26
	s_cselect_b32 s31, s15, s27
	s_cselect_b32 s28, s62, s63
	s_cselect_b32 s29, s13, s69
	s_add_u32 s26, s30, 0x8000
	s_addc_u32 s27, s31, 0
	s_add_i32 m0, s36, 0xc000
	ds_read_b128 v[200:203], v166
	ds_read_b128 v[204:207], v166 offset:1024
	ds_read_b128 v[208:211], v166 offset:2048
	ds_read_b128 v[212:215], v166 offset:3072
	ds_read_b128 v[216:219], v166 offset:4096
	ds_read_b128 v[220:223], v166 offset:5120
	ds_read_b128 v[224:227], v166 offset:6144
	ds_read_b128 v[228:231], v166 offset:7168
	global_load_lds_dwordx4 v156, s[22:23]
	s_add_i32 m0, s36, 0xe000
	s_nop 0
	global_load_lds_dwordx4 v158, s[22:23]
	s_and_b64 vcc, exec, s[10:11]
	s_cbranch_vccnz .Lmy_skipw_1
	s_waitcnt vmcnt(8)
.Lmy_skipw_1:
	s_waitcnt lgkmcnt(0)
	s_setprio 1
	s_barrier
	v_mfma_f32_16x16x32_bf16 v[126:129], v[168:171], v[200:203], 0
	v_mfma_f32_16x16x32_bf16 v[126:129], v[172:175], v[204:207], v[126:129]
	v_mfma_f32_16x16x32_bf16 v[118:121], v[176:179], v[200:203], 0
	v_mfma_f32_16x16x32_bf16 v[118:121], v[180:183], v[204:207], v[118:121]
	v_mfma_f32_16x16x32_bf16 v[122:125], v[184:187], v[200:203], 0
	v_mfma_f32_16x16x32_bf16 v[122:125], v[188:191], v[204:207], v[122:125]
	v_mfma_f32_16x16x32_bf16 v[114:117], v[192:195], v[200:203], 0
	v_mfma_f32_16x16x32_bf16 v[114:117], v[196:199], v[204:207], v[114:117]
	v_mfma_f32_16x16x32_bf16 v[110:113], v[168:171], v[208:211], 0
	v_mfma_f32_16x16x32_bf16 v[110:113], v[172:175], v[212:215], v[110:113]
	v_mfma_f32_16x16x32_bf16 v[102:105], v[176:179], v[208:211], 0
	v_mfma_f32_16x16x32_bf16 v[102:105], v[180:183], v[212:215], v[102:105]
	v_mfma_f32_16x16x32_bf16 v[106:109], v[184:187], v[208:211], 0
	v_mfma_f32_16x16x32_bf16 v[106:109], v[188:191], v[212:215], v[106:109]
	v_mfma_f32_16x16x32_bf16 v[98:101], v[192:195], v[208:211], 0
	v_mfma_f32_16x16x32_bf16 v[98:101], v[196:199], v[212:215], v[98:101]
	v_mfma_f32_16x16x32_bf16 v[94:97], v[168:171], v[216:219], 0
	v_mfma_f32_16x16x32_bf16 v[94:97], v[172:175], v[220:223], v[94:97]
	v_mfma_f32_16x16x32_bf16 v[86:89], v[176:179], v[216:219], 0
	v_mfma_f32_16x16x32_bf16 v[86:89], v[180:183], v[220:223], v[86:89]
	v_mfma_f32_16x16x32_bf16 v[90:93], v[184:187], v[216:219], 0
	v_mfma_f32_16x16x32_bf16 v[90:93], v[188:191], v[220:223], v[90:93]
	v_mfma_f32_16x16x32_bf16 v[82:85], v[192:195], v[216:219], 0
	v_mfma_f32_16x16x32_bf16 v[82:85], v[196:199], v[220:223], v[82:85]
	v_mfma_f32_16x16x32_bf16 v[78:81], v[168:171], v[224:227], 0
	v_mfma_f32_16x16x32_bf16 v[78:81], v[172:175], v[228:231], v[78:81]
	v_mfma_f32_16x16x32_bf16 v[70:73], v[176:179], v[224:227], 0
	v_mfma_f32_16x16x32_bf16 v[70:73], v[180:183], v[228:231], v[70:73]
	v_mfma_f32_16x16x32_bf16 v[74:77], v[184:187], v[224:227], 0
	v_mfma_f32_16x16x32_bf16 v[74:77], v[188:191], v[228:231], v[74:77]
	v_mfma_f32_16x16x32_bf16 v[66:69], v[192:195], v[224:227], 0
	v_mfma_f32_16x16x32_bf16 v[66:69], v[196:199], v[228:231], v[66:69]
	s_waitcnt vmcnt(8)
	s_barrier
	s_setprio 0
	s_add_i32 s71, s45, s34
	s_mov_b32 m0, s71
	ds_read_b128 v[200:203], v166 offset:16384
	ds_read_b128 v[204:207], v166 offset:17408
	ds_read_b128 v[208:211], v166 offset:18432
	ds_read_b128 v[212:215], v166 offset:19456
	ds_read_b128 v[216:219], v166 offset:20480
	ds_read_b128 v[220:223], v166 offset:21504
	ds_read_b128 v[224:227], v166 offset:22528
	ds_read_b128 v[228:231], v166 offset:23552
	global_load_lds_dwordx4 v132, s[28:29]
	s_add_i32 m0, s71, 0x2000
	s_add_u32 s72, s28, 0x4000
	s_addc_u32 s73, s29, 0
	s_add_i32 s71, s58, s34
	global_load_lds_dwordx4 v136, s[28:29]
	s_mov_b32 m0, s71
	s_nop 0
	global_load_lds_dwordx4 v132, s[72:73]
	s_add_i32 m0, s71, 0x2000
	s_nop 0
	global_load_lds_dwordx4 v136, s[72:73]
	s_mov_b32 m0, s36
	s_nop 0
	global_load_lds_dwordx4 v130, s[30:31]
	s_mov_b32 m0, s37
	s_nop 0
	global_load_lds_dwordx4 v134, s[30:31]
	s_and_b64 vcc, exec, s[10:11]
	s_cbranch_vccnz .Lmy_skipw_2
	s_waitcnt vmcnt(8)
; #define PG8_STAGE(bufoff, gbase, voff) do { _Pragma("unroll") for (int _i = 0; _i < 2; ++_i) \
;         __builtin_amdgcn_global_load_lds((const unsigned*)((const char*)(gbase) + (voff)[_i]), (PG8_LAS unsigned*)(lds + (bufoff) + ldsw + _i * 8192), 16, 0, 0); } while (0)
; #define PG8_LDA(dst, b, h) do { _Pragma("unroll") for (int m = 0; m < 4; ++m) _Pragma("unroll") for (int k = 0; k < 2; ++k) dst[m][k] = *(const PG8_LAS bf16x8*)(lds + PG8_SA(b, h) + aoff + m * 2048 + k * 1024); } while (0)
; #define PG8_LDB(dst, b, h) do { _Pragma("unroll") for (int n = 0; n < 2; ++n) _Pragma("unroll") for (int k = 0; k < 2; ++k) dst[n][k] = *(const PG8_LAS bf16x8*)(lds + PG8_SB(b, h) + boff + n * 2048 + k * 1024); } while (0)
; #define PG8_MMA(ai, bj, At, Bt) do { __builtin_amdgcn_s_setprio(1); _Pragma("unroll") for (int m = 0; m < 4; ++m) _Pragma("unroll") for (int n = 0; n < 2; ++n) _Pragma("unroll") for (int k = 0; k < 2; ++k) \
;         acc[ai][bj][m][n] = __builtin_amdgcn_mfma_f32_16x16x32_bf16(Bt[n][k], At[m][k], acc[ai][bj][m][n], 0, 0, 0); __builtin_amdgcn_s_setprio(0); } while (0)
; #define PG8_WAIT_V(n) asm volatile("s_waitcnt vmcnt(" #n ")" ::: "memory")
; #define PG8_WAIT_L(n) asm volatile("s_waitcnt lgkmcnt(" #n ")" ::: "memory")
; #define PG8_BAR __builtin_amdgcn_s_barrier()
; #define PG8_SCHED __builtin_amdgcn_sched_barrier(0)
; template <class Epi, class Sched, bool ALIGN_EPI = false, bool SP2 = false, bool A_TILED = false>
; __device__ __forceinline__ void gemm_phase(PG8_LAS unsigned char* lds, const Gemm g, const Sched& S, const Epi& E) {
;     ...
;             PG8_WAIT_V(8); PG8_WAIT_L(0); PG8_BAR; PG8_MMA(1, 0, At, B0); PG8_MMA(1, 1, At, B1); PG8_BAR; PG8_SCHED;
;             PG8_LDB(B0, 1, 0); PG8_LDB(B1, 1, 1); PG8_SCHED; PG8_LDA(At, 1, 0); PG8_STAGE(PG8_SA(0, 1), a2 + hstepA, voffA);
;             PG8_WAIT_V(8); PG8_WAIT_L(0); PG8_BAR; PG8_MMA(0, 0, At, B0); PG8_MMA(0, 1, At, B1); PG8_BAR; PG8_SCHED;
;             PG8_LDA(At, 1, 1); PG8_STAGE(PG8_SB(1, 0), b3, voffB); PG8_STAGE(PG8_SB(1, 1), b3 + hstepB, voffB); PG8_STAGE(PG8_SA(1, 0), a3, voffA);
;             PG8_WAIT_V(8); PG8_WAIT_L(0); PG8_BAR; PG8_MMA(1, 0, At, B0); PG8_MMA(1, 1, At, B1); PG8_BAR; PG8_SCHED;
.Lmy_skipw_2:
	s_waitcnt lgkmcnt(0)
	s_setprio 1
	s_barrier
	v_mfma_f32_16x16x32_bf16 v[62:65], v[168:171], v[200:203], 0
	v_mfma_f32_16x16x32_bf16 v[62:65], v[172:175], v[204:207], v[62:65]
	v_mfma_f32_16x16x32_bf16 v[54:57], v[176:179], v[200:203], 0
	v_mfma_f32_16x16x32_bf16 v[54:57], v[180:183], v[204:207], v[54:57]
	v_mfma_f32_16x16x32_bf16 v[58:61], v[184:187], v[200:203], 0
	v_mfma_f32_16x16x32_bf16 v[58:61], v[188:191], v[204:207], v[58:61]
	v_mfma_f32_16x16x32_bf16 v[50:53], v[192:195], v[200:203], 0
	v_mfma_f32_16x16x32_bf16 v[50:53], v[196:199], v[204:207], v[50:53]
	v_mfma_f32_16x16x32_bf16 v[46:49], v[168:171], v[208:211], 0
	v_mfma_f32_16x16x32_bf16 v[46:49], v[172:175], v[212:215], v[46:49]
	v_mfma_f32_16x16x32_bf16 v[38:41], v[176:179], v[208:211], 0
	v_mfma_f32_16x16x32_bf16 v[38:41], v[180:183], v[212:215], v[38:41]
	v_mfma_f32_16x16x32_bf16 v[42:45], v[184:187], v[208:211], 0
	v_mfma_f32_16x16x32_bf16 v[42:45], v[188:191], v[212:215], v[42:45]
	v_mfma_f32_16x16x32_bf16 v[34:37], v[192:195], v[208:211], 0
	v_mfma_f32_16x16x32_bf16 v[34:37], v[196:199], v[212:215], v[34:37]
	v_mfma_f32_16x16x32_bf16 v[30:33], v[168:171], v[216:219], 0
	v_mfma_f32_16x16x32_bf16 v[30:33], v[172:175], v[220:223], v[30:33]
	v_mfma_f32_16x16x32_bf16 v[22:25], v[176:179], v[216:219], 0
	v_mfma_f32_16x16x32_bf16 v[22:25], v[180:183], v[220:223], v[22:25]
	v_mfma_f32_16x16x32_bf16 v[26:29], v[184:187], v[216:219], 0
	v_mfma_f32_16x16x32_bf16 v[26:29], v[188:191], v[220:223], v[26:29]
	v_mfma_f32_16x16x32_bf16 v[18:21], v[192:195], v[216:219], 0
	v_mfma_f32_16x16x32_bf16 v[18:21], v[196:199], v[220:223], v[18:21]
	v_mfma_f32_16x16x32_bf16 v[14:17], v[168:171], v[224:227], 0
	v_mfma_f32_16x16x32_bf16 v[14:17], v[172:175], v[228:231], v[14:17]
	v_mfma_f32_16x16x32_bf16 v[6:9], v[176:179], v[224:227], 0
	v_mfma_f32_16x16x32_bf16 v[6:9], v[180:183], v[228:231], v[6:9]
	v_mfma_f32_16x16x32_bf16 v[10:13], v[184:187], v[224:227], 0
	v_mfma_f32_16x16x32_bf16 v[10:13], v[188:191], v[228:231], v[10:13]
	v_mfma_f32_16x16x32_bf16 v[2:5], v[192:195], v[224:227], 0
	v_mfma_f32_16x16x32_bf16 v[2:5], v[196:199], v[228:231], v[2:5]
	s_waitcnt vmcnt(8)
	s_barrier
	s_setprio 0
	s_add_i32 s71, 0, 0x18000
	s_add_i32 s72, 0, 0x1c000
	ds_read_b128 v[168:171], v164 offset:32768
	ds_read_b128 v[172:175], v164 offset:33792
	ds_read_b128 v[176:179], v164 offset:34816
	ds_read_b128 v[180:183], v164 offset:35840
	ds_read_b128 v[184:187], v164 offset:49152
	ds_read_b128 v[188:191], v164 offset:50176
	ds_read_b128 v[192:195], v164 offset:51200
	ds_read_b128 v[196:199], v164 offset:52224
	s_add_u32 s30, s30, 0x4000
	s_addc_u32 s31, s31, 0
	s_mov_b32 m0, s38
	ds_read_b128 v[200:203], v166 offset:32768
	ds_read_b128 v[204:207], v166 offset:33792
	ds_read_b128 v[208:211], v166 offset:34816
	ds_read_b128 v[212:215], v166 offset:35840
	ds_read_b128 v[216:219], v166 offset:36864
	ds_read_b128 v[220:223], v166 offset:37888
	ds_read_b128 v[224:227], v166 offset:38912
	ds_read_b128 v[228:231], v166 offset:39936
	global_load_lds_dwordx4 v130, s[30:31]
	s_mov_b32 m0, s39
	s_nop 0
	global_load_lds_dwordx4 v134, s[30:31]
	s_and_b64 vcc, exec, s[10:11]
	s_cbranch_vccnz .Lmy_skipw_3
	s_waitcnt vmcnt(8)
.Lmy_skipw_3:
	s_waitcnt lgkmcnt(0)
	s_setprio 1
	s_barrier
	v_mfma_f32_16x16x32_bf16 v[126:129], v[168:171], v[200:203], v[126:129]
	v_mfma_f32_16x16x32_bf16 v[126:129], v[172:175], v[204:207], v[126:129]
	v_mfma_f32_16x16x32_bf16 v[118:121], v[176:179], v[200:203], v[118:121]
	v_mfma_f32_16x16x32_bf16 v[118:121], v[180:183], v[204:207], v[118:121]
	v_mfma_f32_16x16x32_bf16 v[122:125], v[184:187], v[200:203], v[122:125]
	v_mfma_f32_16x16x32_bf16 v[122:125], v[188:191], v[204:207], v[122:125]
	v_mfma_f32_16x16x32_bf16 v[114:117], v[192:195], v[200:203], v[114:117]
	v_mfma_f32_16x16x32_bf16 v[114:117], v[196:199], v[204:207], v[114:117]
	v_mfma_f32_16x16x32_bf16 v[110:113], v[168:171], v[208:211], v[110:113]
	v_mfma_f32_16x16x32_bf16 v[110:113], v[172:175], v[212:215], v[110:113]
	v_mfma_f32_16x16x32_bf16 v[102:105], v[176:179], v[208:211], v[102:105]
	v_mfma_f32_16x16x32_bf16 v[102:105], v[180:183], v[212:215], v[102:105]
	v_mfma_f32_16x16x32_bf16 v[106:109], v[184:187], v[208:211], v[106:109]
	v_mfma_f32_16x16x32_bf16 v[106:109], v[188:191], v[212:215], v[106:109]
	v_mfma_f32_16x16x32_bf16 v[98:101], v[192:195], v[208:211], v[98:101]
	v_mfma_f32_16x16x32_bf16 v[98:101], v[196:199], v[212:215], v[98:101]
	v_mfma_f32_16x16x32_bf16 v[94:97], v[168:171], v[216:219], v[94:97]
	v_mfma_f32_16x16x32_bf16 v[94:97], v[172:175], v[220:223], v[94:97]
	v_mfma_f32_16x16x32_bf16 v[86:89], v[176:179], v[216:219], v[86:89]
	v_mfma_f32_16x16x32_bf16 v[86:89], v[180:183], v[220:223], v[86:89]
	v_mfma_f32_16x16x32_bf16 v[90:93], v[184:187], v[216:219], v[90:93]
	v_mfma_f32_16x16x32_bf16 v[90:93], v[188:191], v[220:223], v[90:93]
	v_mfma_f32_16x16x32_bf16 v[82:85], v[192:195], v[216:219], v[82:85]
	v_mfma_f32_16x16x32_bf16 v[82:85], v[196:199], v[220:223], v[82:85]
	v_mfma_f32_16x16x32_bf16 v[78:81], v[168:171], v[224:227], v[78:81]
	v_mfma_f32_16x16x32_bf16 v[78:81], v[172:175], v[228:231], v[78:81]
	v_mfma_f32_16x16x32_bf16 v[70:73], v[176:179], v[224:227], v[70:73]
	v_mfma_f32_16x16x32_bf16 v[70:73], v[180:183], v[228:231], v[70:73]
	v_mfma_f32_16x16x32_bf16 v[74:77], v[184:187], v[224:227], v[74:77]
	v_mfma_f32_16x16x32_bf16 v[74:77], v[188:191], v[228:231], v[74:77]
	v_mfma_f32_16x16x32_bf16 v[66:69], v[192:195], v[224:227], v[66:69]
	v_mfma_f32_16x16x32_bf16 v[66:69], v[196:199], v[228:231], v[66:69]
	s_waitcnt vmcnt(8)
	s_barrier
	s_setprio 0
	s_add_u32 s30, s28, 0x8000
	s_addc_u32 s31, s29, 0
	s_add_i32 s71, s71, s34
	s_mov_b32 m0, s71
	ds_read_b128 v[200:203], v166 offset:49152
	ds_read_b128 v[204:207], v166 offset:50176
	ds_read_b128 v[208:211], v166 offset:51200
	ds_read_b128 v[212:215], v166 offset:52224
	ds_read_b128 v[216:219], v166 offset:53248
	ds_read_b128 v[220:223], v166 offset:54272
	ds_read_b128 v[224:227], v166 offset:55296
	ds_read_b128 v[228:231], v166 offset:56320
	global_load_lds_dwordx4 v132, s[30:31]
	s_add_i32 m0, s71, 0x2000
	s_add_u32 s28, s28, 0xc000
	v_lshl_add_u64 v[232:233], s[30:31], 0, v[136:137]
	s_addc_u32 s29, s29, 0
	s_add_i32 s30, s72, s34
	global_load_lds_dwordx4 v[232:233], off
	s_mov_b32 m0, s30
	s_nop 0
	global_load_lds_dwordx4 v132, s[28:29]
	s_add_i32 m0, s30, 0x2000
	s_nop 0
	global_load_lds_dwordx4 v136, s[28:29]
	s_mov_b32 m0, s43
	s_nop 0
	global_load_lds_dwordx4 v130, s[26:27]
	s_mov_b32 m0, s44
	s_nop 0
	global_load_lds_dwordx4 v134, s[26:27]
	s_and_b64 vcc, exec, s[10:11]
	s_cbranch_vccnz .Lmy_skipw_4
	s_waitcnt vmcnt(8)
; #define PG8_STAGE(bufoff, gbase, voff) do { _Pragma("unroll") for (int _i = 0; _i < 2; ++_i) \
;         __builtin_amdgcn_global_load_lds((const unsigned*)((const char*)(gbase) + (voff)[_i]), (PG8_LAS unsigned*)(lds + (bufoff) + ldsw + _i * 8192), 16, 0, 0); } while (0)
; #define PG8_LDA(dst, b, h) do { _Pragma("unroll") for (int m = 0; m < 4; ++m) _Pragma("unroll") for (int k = 0; k < 2; ++k) dst[m][k] = *(const PG8_LAS bf16x8*)(lds + PG8_SA(b, h) + aoff + m * 2048 + k * 1024); } while (0)
; #define PG8_LDB(dst, b, h) do { _Pragma("unroll") for (int n = 0; n < 2; ++n) _Pragma("unroll") for (int k = 0; k < 2; ++k) dst[n][k] = *(const PG8_LAS bf16x8*)(lds + PG8_SB(b, h) + boff + n * 2048 + k * 1024); } while (0)
; #define PG8_MMA(ai, bj, At, Bt) do { __builtin_amdgcn_s_setprio(1); _Pragma("unroll") for (int m = 0; m < 4; ++m) _Pragma("unroll") for (int n = 0; n < 2; ++n) _Pragma("unroll") for (int k = 0; k < 2; ++k) \
;         acc[ai][bj][m][n] = __builtin_amdgcn_mfma_f32_16x16x32_bf16(Bt[n][k], At[m][k], acc[ai][bj][m][n], 0, 0, 0); __builtin_amdgcn_s_setprio(0); } while (0)
; #define PG8_WAIT_V(n) asm volatile("s_waitcnt vmcnt(" #n ")" ::: "memory")
; #define PG8_WAIT_L(n) asm volatile("s_waitcnt lgkmcnt(" #n ")" ::: "memory")
; #define PG8_BAR __builtin_amdgcn_s_barrier()
; #define PG8_SCHED __builtin_amdgcn_sched_barrier(0)
; template <class Epi, class Sched, bool ALIGN_EPI = false, bool SP2 = false, bool A_TILED = false>
; __device__ __forceinline__ void gemm_phase(PG8_LAS unsigned char* lds, const Gemm g, const Sched& S, const Epi& E) {
;     ...
;             PG8_LDB(B0, 0, 0); PG8_LDB(B1, 0, 1); PG8_SCHED; PG8_LDA(At, 0, 0); PG8_STAGE(PG8_SA(1, 1), a1 + hstepA, voffA);
;             PG8_WAIT_V(8); PG8_WAIT_L(0); PG8_BAR; PG8_MMA(0, 0, At, B0); PG8_MMA(0, 1, At, B1); PG8_BAR; PG8_SCHED;
;             PG8_LDA(At, 0, 1); PG8_STAGE(PG8_SB(0, 0), b2, voffB); PG8_STAGE(PG8_SB(0, 1), b2 + hstepB, voffB); PG8_STAGE(PG8_SA(0, 0), a2, voffA);
;             PG8_WAIT_V(8); PG8_WAIT_L(0); PG8_BAR; PG8_MMA(1, 0, At, B0); PG8_MMA(1, 1, At, B1); PG8_BAR; PG8_SCHED;
;     ...
;             PG8_LDA(At, 1, 1); PG8_STAGE(PG8_SB(1, 0), b3, voffB); PG8_STAGE(PG8_SB(1, 1), b3 + hstepB, voffB); PG8_STAGE(PG8_SA(1, 0), a3, voffA);
;             PG8_WAIT_V(8); PG8_WAIT_L(0); PG8_BAR; PG8_MMA(1, 0, At, B0); PG8_MMA(1, 1, At, B1); PG8_BAR; PG8_SCHED;
.Lmy_skipw_4:
	s_waitcnt lgkmcnt(0)
	s_setprio 1
	s_barrier
	v_mfma_f32_16x16x32_bf16 v[62:65], v[168:171], v[200:203], v[62:65]
	v_mfma_f32_16x16x32_bf16 v[62:65], v[172:175], v[204:207], v[62:65]
	v_mfma_f32_16x16x32_bf16 v[54:57], v[176:179], v[200:203], v[54:57]
	v_mfma_f32_16x16x32_bf16 v[54:57], v[180:183], v[204:207], v[54:57]
	v_mfma_f32_16x16x32_bf16 v[58:61], v[184:187], v[200:203], v[58:61]
	v_mfma_f32_16x16x32_bf16 v[58:61], v[188:191], v[204:207], v[58:61]
	v_mfma_f32_16x16x32_bf16 v[50:53], v[192:195], v[200:203], v[50:53]
	v_mfma_f32_16x16x32_bf16 v[50:53], v[196:199], v[204:207], v[50:53]
	v_mfma_f32_16x16x32_bf16 v[46:49], v[168:171], v[208:211], v[46:49]
	v_mfma_f32_16x16x32_bf16 v[46:49], v[172:175], v[212:215], v[46:49]
	v_mfma_f32_16x16x32_bf16 v[38:41], v[176:179], v[208:211], v[38:41]
	v_mfma_f32_16x16x32_bf16 v[38:41], v[180:183], v[212:215], v[38:41]
	v_mfma_f32_16x16x32_bf16 v[42:45], v[184:187], v[208:211], v[42:45]
	v_mfma_f32_16x16x32_bf16 v[42:45], v[188:191], v[212:215], v[42:45]
	v_mfma_f32_16x16x32_bf16 v[34:37], v[192:195], v[208:211], v[34:37]
	v_mfma_f32_16x16x32_bf16 v[34:37], v[196:199], v[212:215], v[34:37]
	v_mfma_f32_16x16x32_bf16 v[30:33], v[168:171], v[216:219], v[30:33]
	v_mfma_f32_16x16x32_bf16 v[30:33], v[172:175], v[220:223], v[30:33]
	v_mfma_f32_16x16x32_bf16 v[22:25], v[176:179], v[216:219], v[22:25]
	v_mfma_f32_16x16x32_bf16 v[22:25], v[180:183], v[220:223], v[22:25]
	v_mfma_f32_16x16x32_bf16 v[26:29], v[184:187], v[216:219], v[26:29]
	v_mfma_f32_16x16x32_bf16 v[26:29], v[188:191], v[220:223], v[26:29]
	v_mfma_f32_16x16x32_bf16 v[18:21], v[192:195], v[216:219], v[18:21]
	v_mfma_f32_16x16x32_bf16 v[18:21], v[196:199], v[220:223], v[18:21]
	v_mfma_f32_16x16x32_bf16 v[14:17], v[168:171], v[224:227], v[14:17]
	v_mfma_f32_16x16x32_bf16 v[14:17], v[172:175], v[228:231], v[14:17]
	v_mfma_f32_16x16x32_bf16 v[6:9], v[176:179], v[224:227], v[6:9]
	v_mfma_f32_16x16x32_bf16 v[6:9], v[180:183], v[228:231], v[6:9]
	v_mfma_f32_16x16x32_bf16 v[10:13], v[184:187], v[224:227], v[10:13]
	v_mfma_f32_16x16x32_bf16 v[10:13], v[188:191], v[228:231], v[10:13]
	v_mfma_f32_16x16x32_bf16 v[2:5], v[192:195], v[224:227], v[2:5]
	v_mfma_f32_16x16x32_bf16 v[2:5], v[196:199], v[228:231], v[2:5]
	s_waitcnt vmcnt(8)
	s_barrier
	s_setprio 0
	s_add_i32 s70, s70, 2
	s_add_u32 s22, s22, 0x10000
	s_addc_u32 s23, s23, 0
	s_add_u32 s63, s63, 0x10000
	s_addc_u32 s69, s69, 0
.LBB0_195:
	ds_read_b128 v[168:171], v164
	ds_read_b128 v[172:175], v164 offset:1024
	ds_read_b128 v[176:179], v164 offset:2048
	ds_read_b128 v[180:183], v164 offset:3072
	ds_read_b128 v[184:187], v165
	ds_read_b128 v[188:191], v165 offset:1024
	ds_read_b128 v[192:195], v165 offset:2048
	ds_read_b128 v[196:199], v165 offset:3072
	s_add_u32 s26, s22, 0x4000
	s_addc_u32 s27, s23, 0
	s_cmp_eq_u32 s70, 60
	s_cselect_b32 s30, s59, s26
	s_cselect_b32 s31, s15, s27
	s_cselect_b32 s28, s62, s63
	s_cselect_b32 s29, s13, s69
	s_add_u32 s26, s30, 0x8000
	s_addc_u32 s27, s31, 0
	s_add_i32 m0, s36, 0xc000
	ds_read_b128 v[200:203], v166
	ds_read_b128 v[204:207], v166 offset:1024
	ds_read_b128 v[208:211], v166 offset:2048
	ds_read_b128 v[212:215], v166 offset:3072
	ds_read_b128 v[216:219], v166 offset:4096
	ds_read_b128 v[220:223], v166 offset:5120
	ds_read_b128 v[224:227], v166 offset:6144
	ds_read_b128 v[228:231], v166 offset:7168
	global_load_lds_dwordx4 v156, s[22:23]
	s_add_i32 m0, s36, 0xe000
	s_nop 0
	global_load_lds_dwordx4 v158, s[22:23]
	s_and_b64 vcc, exec, s[10:11]
	s_cbranch_vccnz .Lmy_skipw_5
	s_waitcnt vmcnt(8)
; #define PG8_STAGE(bufoff, gbase, voff) do { _Pragma("unroll") for (int _i = 0; _i < 2; ++_i) \
;         __builtin_amdgcn_global_load_lds((const unsigned*)((const char*)(gbase) + (voff)[_i]), (PG8_LAS unsigned*)(lds + (bufoff) + ldsw + _i * 8192), 16, 0, 0); } while (0)
; #define PG8_LDA(dst, b, h) do { _Pragma("unroll") for (int m = 0; m < 4; ++m) _Pragma("unroll") for (int k = 0; k < 2; ++k) dst[m][k] = *(const PG8_LAS bf16x8*)(lds + PG8_SA(b, h) + aoff + m * 2048 + k * 1024); } while (0)
; #define PG8_LDB(dst, b, h) do { _Pragma("unroll") for (int n = 0; n < 2; ++n) _Pragma("unroll") for (int k = 0; k < 2; ++k) dst[n][k] = *(const PG8_LAS bf16x8*)(lds + PG8_SB(b, h) + boff + n * 2048 + k * 1024); } while (0)
; #define PG8_MMA(ai, bj, At, Bt) do { __builtin_amdgcn_s_setprio(1); _Pragma("unroll") for (int m = 0; m < 4; ++m) _Pragma("unroll") for (int n = 0; n < 2; ++n) _Pragma("unroll") for (int k = 0; k < 2; ++k) \
;         acc[ai][bj][m][n] = __builtin_amdgcn_mfma_f32_16x16x32_bf16(Bt[n][k], At[m][k], acc[ai][bj][m][n], 0, 0, 0); __builtin_amdgcn_s_setprio(0); } while (0)
; #define PG8_WAIT_V(n) asm volatile("s_waitcnt vmcnt(" #n ")" ::: "memory")
; #define PG8_WAIT_L(n) asm volatile("s_waitcnt lgkmcnt(" #n ")" ::: "memory")
; template <class Epi, class Sched, bool ALIGN_EPI = false, bool SP2 = false, bool A_TILED = false>
; __device__ __forceinline__ void gemm_phase(PG8_LAS unsigned char* lds, const Gemm g, const Sched& S, const Epi& E) {
;     ...
;             PG8_LDB(B0, 0, 0); PG8_LDB(B1, 0, 1); PG8_SCHED; PG8_LDA(At, 0, 0); PG8_STAGE(PG8_SA(1, 1), a1 + hstepA, voffA);
;             PG8_WAIT_V(8); PG8_WAIT_L(0); PG8_BAR; PG8_MMA(0, 0, At, B0); PG8_MMA(0, 1, At, B1); PG8_BAR; PG8_SCHED;
;             PG8_LDA(At, 0, 1); PG8_STAGE(PG8_SB(0, 0), b2, voffB); PG8_STAGE(PG8_SB(0, 1), b2 + hstepB, voffB); PG8_STAGE(PG8_SA(0, 0), a2, voffA);
;             PG8_WAIT_V(8); PG8_WAIT_L(0); PG8_BAR; PG8_MMA(1, 0, At, B0); PG8_MMA(1, 1, At, B1); PG8_BAR; PG8_SCHED;
;             PG8_LDB(B0, 1, 0); PG8_LDB(B1, 1, 1); PG8_SCHED; PG8_LDA(At, 1, 0); PG8_STAGE(PG8_SA(0, 1), a2 + hstepA, voffA);
;             PG8_WAIT_V(8); PG8_WAIT_L(0); PG8_BAR; PG8_MMA(0, 0, At, B0); PG8_MMA(0, 1, At, B1); PG8_BAR; PG8_SCHED;
;             PG8_LDA(At, 1, 1); PG8_STAGE(PG8_SB(1, 0), b3, voffB); PG8_STAGE(PG8_SB(1, 1), b3 + hstepB, voffB); PG8_STAGE(PG8_SA(1, 0), a3, voffA);
.Lmy_skipw_5:
	s_waitcnt lgkmcnt(0)
	s_setprio 1
	s_barrier
	v_mfma_f32_16x16x32_bf16 v[126:129], v[168:171], v[200:203], v[126:129]
	v_mfma_f32_16x16x32_bf16 v[126:129], v[172:175], v[204:207], v[126:129]
	v_mfma_f32_16x16x32_bf16 v[118:121], v[176:179], v[200:203], v[118:121]
	v_mfma_f32_16x16x32_bf16 v[118:121], v[180:183], v[204:207], v[118:121]
	v_mfma_f32_16x16x32_bf16 v[122:125], v[184:187], v[200:203], v[122:125]
	v_mfma_f32_16x16x32_bf16 v[122:125], v[188:191], v[204:207], v[122:125]
	v_mfma_f32_16x16x32_bf16 v[114:117], v[192:195], v[200:203], v[114:117]
	v_mfma_f32_16x16x32_bf16 v[114:117], v[196:199], v[204:207], v[114:117]
	v_mfma_f32_16x16x32_bf16 v[110:113], v[168:171], v[208:211], v[110:113]
	v_mfma_f32_16x16x32_bf16 v[110:113], v[172:175], v[212:215], v[110:113]
	v_mfma_f32_16x16x32_bf16 v[102:105], v[176:179], v[208:211], v[102:105]
	v_mfma_f32_16x16x32_bf16 v[102:105], v[180:183], v[212:215], v[102:105]
	v_mfma_f32_16x16x32_bf16 v[106:109], v[184:187], v[208:211], v[106:109]
	v_mfma_f32_16x16x32_bf16 v[106:109], v[188:191], v[212:215], v[106:109]
	v_mfma_f32_16x16x32_bf16 v[98:101], v[192:195], v[208:211], v[98:101]
	v_mfma_f32_16x16x32_bf16 v[98:101], v[196:199], v[212:215], v[98:101]
	v_mfma_f32_16x16x32_bf16 v[94:97], v[168:171], v[216:219], v[94:97]
	v_mfma_f32_16x16x32_bf16 v[94:97], v[172:175], v[220:223], v[94:97]
	v_mfma_f32_16x16x32_bf16 v[86:89], v[176:179], v[216:219], v[86:89]
	v_mfma_f32_16x16x32_bf16 v[86:89], v[180:183], v[220:223], v[86:89]
	v_mfma_f32_16x16x32_bf16 v[90:93], v[184:187], v[216:219], v[90:93]
	v_mfma_f32_16x16x32_bf16 v[90:93], v[188:191], v[220:223], v[90:93]
	v_mfma_f32_16x16x32_bf16 v[82:85], v[192:195], v[216:219], v[82:85]
	v_mfma_f32_16x16x32_bf16 v[82:85], v[196:199], v[220:223], v[82:85]
	v_mfma_f32_16x16x32_bf16 v[78:81], v[168:171], v[224:227], v[78:81]
	v_mfma_f32_16x16x32_bf16 v[78:81], v[172:175], v[228:231], v[78:81]
	v_mfma_f32_16x16x32_bf16 v[70:73], v[176:179], v[224:227], v[70:73]
	v_mfma_f32_16x16x32_bf16 v[70:73], v[180:183], v[228:231], v[70:73]
	v_mfma_f32_16x16x32_bf16 v[74:77], v[184:187], v[224:227], v[74:77]
	v_mfma_f32_16x16x32_bf16 v[74:77], v[188:191], v[228:231], v[74:77]
	v_mfma_f32_16x16x32_bf16 v[66:69], v[192:195], v[224:227], v[66:69]
	v_mfma_f32_16x16x32_bf16 v[66:69], v[196:199], v[228:231], v[66:69]
	s_waitcnt vmcnt(8)
	s_barrier
	s_setprio 0
	s_add_i32 s71, s45, s34
	s_mov_b32 m0, s71
	ds_read_b128 v[200:203], v166 offset:16384
	ds_read_b128 v[204:207], v166 offset:17408
	ds_read_b128 v[208:211], v166 offset:18432
	ds_read_b128 v[212:215], v166 offset:19456
	ds_read_b128 v[216:219], v166 offset:20480
	ds_read_b128 v[220:223], v166 offset:21504
	ds_read_b128 v[224:227], v166 offset:22528
	ds_read_b128 v[228:231], v166 offset:23552
	global_load_lds_dwordx4 v132, s[28:29]
	s_add_i32 m0, s71, 0x2000
	s_add_u32 s72, s28, 0x4000
	s_addc_u32 s73, s29, 0
	s_add_i32 s71, s58, s34
	global_load_lds_dwordx4 v136, s[28:29]
	s_mov_b32 m0, s71
	s_nop 0
	global_load_lds_dwordx4 v132, s[72:73]
	s_add_i32 m0, s71, 0x2000
	s_nop 0
	global_load_lds_dwordx4 v136, s[72:73]
	s_mov_b32 m0, s36
	s_nop 0
	global_load_lds_dwordx4 v130, s[30:31]
	s_mov_b32 m0, s37
	s_nop 0
	global_load_lds_dwordx4 v134, s[30:31]
	s_and_b64 vcc, exec, s[10:11]
	s_cbranch_vccnz .Lmy_skipw_6
	s_waitcnt vmcnt(8)
.Lmy_skipw_6:
	s_waitcnt lgkmcnt(0)
	s_setprio 1
	s_barrier
	v_mfma_f32_16x16x32_bf16 v[62:65], v[168:171], v[200:203], v[62:65]
	v_mfma_f32_16x16x32_bf16 v[62:65], v[172:175], v[204:207], v[62:65]
	v_mfma_f32_16x16x32_bf16 v[54:57], v[176:179], v[200:203], v[54:57]
	v_mfma_f32_16x16x32_bf16 v[54:57], v[180:183], v[204:207], v[54:57]
	v_mfma_f32_16x16x32_bf16 v[58:61], v[184:187], v[200:203], v[58:61]
	v_mfma_f32_16x16x32_bf16 v[58:61], v[188:191], v[204:207], v[58:61]
	v_mfma_f32_16x16x32_bf16 v[50:53], v[192:195], v[200:203], v[50:53]
	v_mfma_f32_16x16x32_bf16 v[50:53], v[196:199], v[204:207], v[50:53]
	v_mfma_f32_16x16x32_bf16 v[46:49], v[168:171], v[208:211], v[46:49]
	v_mfma_f32_16x16x32_bf16 v[46:49], v[172:175], v[212:215], v[46:49]
	v_mfma_f32_16x16x32_bf16 v[38:41], v[176:179], v[208:211], v[38:41]
	v_mfma_f32_16x16x32_bf16 v[38:41], v[180:183], v[212:215], v[38:41]
	v_mfma_f32_16x16x32_bf16 v[42:45], v[184:187], v[208:211], v[42:45]
	v_mfma_f32_16x16x32_bf16 v[42:45], v[188:191], v[212:215], v[42:45]
	v_mfma_f32_16x16x32_bf16 v[34:37], v[192:195], v[208:211], v[34:37]
	v_mfma_f32_16x16x32_bf16 v[34:37], v[196:199], v[212:215], v[34:37]
	v_mfma_f32_16x16x32_bf16 v[30:33], v[168:171], v[216:219], v[30:33]
	v_mfma_f32_16x16x32_bf16 v[30:33], v[172:175], v[220:223], v[30:33]
	v_mfma_f32_16x16x32_bf16 v[22:25], v[176:179], v[216:219], v[22:25]
	v_mfma_f32_16x16x32_bf16 v[22:25], v[180:183], v[220:223], v[22:25]
	v_mfma_f32_16x16x32_bf16 v[26:29], v[184:187], v[216:219], v[26:29]
	v_mfma_f32_16x16x32_bf16 v[26:29], v[188:191], v[220:223], v[26:29]
	v_mfma_f32_16x16x32_bf16 v[18:21], v[192:195], v[216:219], v[18:21]
	v_mfma_f32_16x16x32_bf16 v[18:21], v[196:199], v[220:223], v[18:21]
	v_mfma_f32_16x16x32_bf16 v[14:17], v[168:171], v[224:227], v[14:17]
	v_mfma_f32_16x16x32_bf16 v[14:17], v[172:175], v[228:231], v[14:17]
	v_mfma_f32_16x16x32_bf16 v[6:9], v[176:179], v[224:227], v[6:9]
	v_mfma_f32_16x16x32_bf16 v[6:9], v[180:183], v[228:231], v[6:9]
	v_mfma_f32_16x16x32_bf16 v[10:13], v[184:187], v[224:227], v[10:13]
	v_mfma_f32_16x16x32_bf16 v[10:13], v[188:191], v[228:231], v[10:13]
	v_mfma_f32_16x16x32_bf16 v[2:5], v[192:195], v[224:227], v[2:5]
	v_mfma_f32_16x16x32_bf16 v[2:5], v[196:199], v[228:231], v[2:5]
	s_waitcnt vmcnt(8)
	s_barrier
	s_setprio 0
	s_add_i32 s71, 0, 0x18000
	s_add_i32 s72, 0, 0x1c000
	ds_read_b128 v[168:171], v164 offset:32768
	ds_read_b128 v[172:175], v164 offset:33792
	ds_read_b128 v[176:179], v164 offset:34816
	ds_read_b128 v[180:183], v164 offset:35840
	ds_read_b128 v[184:187], v164 offset:49152
	ds_read_b128 v[188:191], v164 offset:50176
	ds_read_b128 v[192:195], v164 offset:51200
	ds_read_b128 v[196:199], v164 offset:52224
	s_add_u32 s30, s30, 0x4000
	s_addc_u32 s31, s31, 0
	s_mov_b32 m0, s38
	ds_read_b128 v[200:203], v166 offset:32768
	ds_read_b128 v[204:207], v166 offset:33792
	ds_read_b128 v[208:211], v166 offset:34816
	ds_read_b128 v[212:215], v166 offset:35840
	ds_read_b128 v[216:219], v166 offset:36864
	ds_read_b128 v[220:223], v166 offset:37888
	ds_read_b128 v[224:227], v166 offset:38912
	ds_read_b128 v[228:231], v166 offset:39936
	global_load_lds_dwordx4 v130, s[30:31]
	s_mov_b32 m0, s39
	s_nop 0
	global_load_lds_dwordx4 v134, s[30:31]
	s_and_b64 vcc, exec, s[10:11]
	s_cbranch_vccnz .Lmy_skipw_7
	s_waitcnt vmcnt(8)

; #define PG8_STAGE(bufoff, gbase, voff) do { _Pragma("unroll") for (int _i = 0; _i < 2; ++_i) \
;         __builtin_amdgcn_global_load_lds((const unsigned*)((const char*)(gbase) + (voff)[_i]), (PG8_LAS unsigned*)(lds + (bufoff) + ldsw + _i * 8192), 16, 0, 0); } while (0)
; #define PG8_LDA(dst, b, h) do { _Pragma("unroll") for (int m = 0; m < 4; ++m) _Pragma("unroll") for (int k = 0; k < 2; ++k) dst[m][k] = *(const PG8_LAS bf16x8*)(lds + PG8_SA(b, h) + aoff + m * 2048 + k * 1024); } while (0)
; #define PG8_MMA(ai, bj, At, Bt) do { __builtin_amdgcn_s_setprio(1); _Pragma("unroll") for (int m = 0; m < 4; ++m) _Pragma("unroll") for (int n = 0; n < 2; ++n) _Pragma("unroll") for (int k = 0; k < 2; ++k) \
;         acc[ai][bj][m][n] = __builtin_amdgcn_mfma_f32_16x16x32_bf16(Bt[n][k], At[m][k], acc[ai][bj][m][n], 0, 0, 0); __builtin_amdgcn_s_setprio(0); } while (0)
; #define PG8_WAIT_V(n) asm volatile("s_waitcnt vmcnt(" #n ")" ::: "memory")
; #define PG8_WAIT_L(n) asm volatile("s_waitcnt lgkmcnt(" #n ")" ::: "memory")
; #define PG8_BAR __builtin_amdgcn_s_barrier()
; #define PG8_SCHED __builtin_amdgcn_sched_barrier(0)
; template <class Epi, class Sched, bool ALIGN_EPI = false, bool SP2 = false, bool A_TILED = false>
; __device__ __forceinline__ void gemm_phase(PG8_LAS unsigned char* lds, const Gemm g, const Sched& S, const Epi& E) {
;     ...
;             PG8_LDA(At, 1, 1); PG8_STAGE(PG8_SB(1, 0), b3, voffB); PG8_STAGE(PG8_SB(1, 1), b3 + hstepB, voffB); PG8_STAGE(PG8_SA(1, 0), a3, voffA);
;             PG8_WAIT_V(8); PG8_WAIT_L(0); PG8_BAR; PG8_MMA(1, 0, At, B0); PG8_MMA(1, 1, At, B1); PG8_BAR; PG8_SCHED;
.Lmy_skipw_8:
	s_waitcnt lgkmcnt(0)
	s_setprio 1
	s_barrier
	v_mfma_f32_16x16x32_bf16 v[62:65], v[168:171], v[200:203], v[62:65]
	v_mfma_f32_16x16x32_bf16 v[62:65], v[172:175], v[204:207], v[62:65]
	v_mfma_f32_16x16x32_bf16 v[54:57], v[176:179], v[200:203], v[54:57]
	v_mfma_f32_16x16x32_bf16 v[54:57], v[180:183], v[204:207], v[54:57]
	v_mfma_f32_16x16x32_bf16 v[58:61], v[184:187], v[200:203], v[58:61]
	v_mfma_f32_16x16x32_bf16 v[58:61], v[188:191], v[204:207], v[58:61]
	v_mfma_f32_16x16x32_bf16 v[50:53], v[192:195], v[200:203], v[50:53]
	v_mfma_f32_16x16x32_bf16 v[50:53], v[196:199], v[204:207], v[50:53]
	v_mfma_f32_16x16x32_bf16 v[46:49], v[168:171], v[208:211], v[46:49]
	v_mfma_f32_16x16x32_bf16 v[46:49], v[172:175], v[212:215], v[46:49]
	v_mfma_f32_16x16x32_bf16 v[38:41], v[176:179], v[208:211], v[38:41]
	v_mfma_f32_16x16x32_bf16 v[38:41], v[180:183], v[212:215], v[38:41]
	v_mfma_f32_16x16x32_bf16 v[42:45], v[184:187], v[208:211], v[42:45]
	v_mfma_f32_16x16x32_bf16 v[42:45], v[188:191], v[212:215], v[42:45]
	v_mfma_f32_16x16x32_bf16 v[34:37], v[192:195], v[208:211], v[34:37]
	v_mfma_f32_16x16x32_bf16 v[34:37], v[196:199], v[212:215], v[34:37]
	v_mfma_f32_16x16x32_bf16 v[30:33], v[168:171], v[216:219], v[30:33]
	v_mfma_f32_16x16x32_bf16 v[30:33], v[172:175], v[220:223], v[30:33]
	v_mfma_f32_16x16x32_bf16 v[22:25], v[176:179], v[216:219], v[22:25]
	v_mfma_f32_16x16x32_bf16 v[22:25], v[180:183], v[220:223], v[22:25]
	v_mfma_f32_16x16x32_bf16 v[26:29], v[184:187], v[216:219], v[26:29]
	v_mfma_f32_16x16x32_bf16 v[26:29], v[188:191], v[220:223], v[26:29]
	v_mfma_f32_16x16x32_bf16 v[18:21], v[192:195], v[216:219], v[18:21]
	v_mfma_f32_16x16x32_bf16 v[18:21], v[196:199], v[220:223], v[18:21]
	v_mfma_f32_16x16x32_bf16 v[14:17], v[168:171], v[224:227], v[14:17]
	v_mfma_f32_16x16x32_bf16 v[14:17], v[172:175], v[228:231], v[14:17]
	v_mfma_f32_16x16x32_bf16 v[6:9], v[176:179], v[224:227], v[6:9]
	v_mfma_f32_16x16x32_bf16 v[6:9], v[180:183], v[228:231], v[6:9]
	v_mfma_f32_16x16x32_bf16 v[10:13], v[184:187], v[224:227], v[10:13]
	v_mfma_f32_16x16x32_bf16 v[10:13], v[188:191], v[228:231], v[10:13]
	v_mfma_f32_16x16x32_bf16 v[2:5], v[192:195], v[224:227], v[2:5]
	v_mfma_f32_16x16x32_bf16 v[2:5], v[196:199], v[228:231], v[2:5]
	s_waitcnt vmcnt(8)
	s_barrier
	s_setprio 0
	s_add_i32 s70, s70, 2
	s_add_u32 s22, s22, 0x10000
	s_addc_u32 s23, s23, 0
	s_add_u32 s63, s63, 0x10000
	s_addc_u32 s69, s69, 0
	s_cmp_gt_u32 s70, 61
	s_cbranch_scc0 .LBB0_195
	s_and_b64 vcc, exec, s[10:11]
	s_cbranch_vccz .LBB0_198
	s_barrier

; #define PG8_STAGE(bufoff, gbase, voff) do { _Pragma("unroll") for (int _i = 0; _i < 2; ++_i) \
;         __builtin_amdgcn_global_load_lds((const unsigned*)((const char*)(gbase) + (voff)[_i]), (PG8_LAS unsigned*)(lds + (bufoff) + ldsw + _i * 8192), 16, 0, 0); } while (0)
; #define PG8_LDA(dst, b, h) do { _Pragma("unroll") for (int m = 0; m < 4; ++m) _Pragma("unroll") for (int k = 0; k < 2; ++k) dst[m][k] = *(const PG8_LAS bf16x8*)(lds + PG8_SA(b, h) + aoff + m * 2048 + k * 1024); } while (0)
; #define PG8_LDB(dst, b, h) do { _Pragma("unroll") for (int n = 0; n < 2; ++n) _Pragma("unroll") for (int k = 0; k < 2; ++k) dst[n][k] = *(const PG8_LAS bf16x8*)(lds + PG8_SB(b, h) + boff + n * 2048 + k * 1024); } while (0)
; #define PG8_WAIT_V(n) asm volatile("s_waitcnt vmcnt(" #n ")" ::: "memory")
; #define PG8_WAIT_L(n) asm volatile("s_waitcnt lgkmcnt(" #n ")" ::: "memory")
; #define PG8_BAR __builtin_amdgcn_s_barrier()
; #define PG8_SCHED __builtin_amdgcn_sched_barrier(0)
; template <class Epi, class Sched, bool ALIGN_EPI = false, bool SP2 = false, bool A_TILED = false>
; __device__ __forceinline__ void gemm_phase(PG8_LAS unsigned char* lds, const Gemm g, const Sched& S, const Epi& E) {
;     ...
;         const bool has_next = S.next(ui + 1, nxt);
;         const char* nA = has_next ? (const char*)g.A + (size_t)nxt.pm * tstepA : cA; const char* nB = has_next ? (const char*)g.Bt + (size_t)nxt.pn * tstepB : cB;
;         for (int t = 0; t < nt; t += 2) {
;             const bool last = (t == nt - 2);
;             const char* a1 = cA + (size_t)(t + 1) * kstepA;
;             const char* a2 = last ? nA : cA + (size_t)(t + 2) * kstepA; const char* b2 = last ? nB : cB + (size_t)(t + 2) * kstepB;
;             const char* a3 = a2 + kstepA; const char* b3 = b2 + kstepB;
;             if (last && has_next) S.a_ready(nxt);
;             if constexpr (SP2) {
;             PG8_LDB(B0, 0, 0); PG8_LDB(B1, 0, 1); PG8_SCHED; PG8_LDA(At, 0, 0); PG8_STAGE(PG8_SA(1, 1), a1 + hstepA, voffA);
;             PG8_WAIT_V(8); PG8_WAIT_L(0); PG8_BAR; PG8_MMA(0, 0, At, B0); PG8_MMA(0, 1, At, B1); PG8_BAR; PG8_SCHED;
;             PG8_LDA(At, 0, 1); PG8_STAGE(PG8_SB(0, 0), b2, voffB); PG8_STAGE(PG8_SB(0, 1), b2 + hstepB, voffB); PG8_STAGE(PG8_SA(0, 0), a2, voffA);
;             PG8_WAIT_V(8); PG8_WAIT_L(0); PG8_BAR; PG8_MMA(1, 0, At, B0); PG8_MMA(1, 1, At, B1); PG8_BAR; PG8_SCHED;
.LBB0_273:
	s_add_u32 s36, s36, 0xc000
	s_addc_u32 s37, s37, 0
	s_add_u32 s33, s38, 0x10000
	v_mov_b32_e32 v2, 0
	s_addc_u32 s35, s39, 0
	s_mov_b32 s70, -2
	s_waitcnt lgkmcnt(0)
	ds_read_b128 v[130:133], v197
	ds_read_b128 v[134:137], v197 offset:1024
	ds_read_b128 v[138:141], v197 offset:2048
	ds_read_b128 v[142:145], v197 offset:3072
	ds_read_b128 v[146:149], v240
	ds_read_b128 v[150:153], v240 offset:1024
	ds_read_b128 v[154:157], v240 offset:2048
	ds_read_b128 v[158:161], v240 offset:3072
	s_add_u32 s38, s36, 0x4000
	s_addc_u32 s39, s37, 0
	s_cmpk_eq_i32 s70, 0xa8
	s_cselect_b32 s42, s4, s38
	s_cselect_b32 s43, s5, s39
	s_cselect_b32 s40, s30, s33
	s_cselect_b32 s41, s31, s35
	s_add_u32 s38, s42, 0x8000
	s_addc_u32 s39, s43, 0
	s_add_i32 m0, s62, 0xc000
	ds_read_b128 v[162:165], v241
	ds_read_b128 v[166:169], v241 offset:1024
	ds_read_b128 v[170:173], v241 offset:2048
	ds_read_b128 v[174:177], v241 offset:3072
	ds_read_b128 v[178:181], v241 offset:4096
	ds_read_b128 v[182:185], v241 offset:5120
	ds_read_b128 v[186:189], v241 offset:6144
	ds_read_b128 v[222:225], v241 offset:7168
	global_load_lds_dwordx4 v214, s[36:37]
	s_add_i32 m0, s62, 0xe000
	s_nop 0
	global_load_lds_dwordx4 v216, s[36:37]
	s_and_b64 vcc, exec, s[16:17]
	s_cbranch_vccnz .Lmy_skipw_9
	s_waitcnt vmcnt(8)
.Lmy_skipw_9:
	s_waitcnt lgkmcnt(0)
	s_setprio 1
	s_barrier
	v_mfma_f32_16x16x32_bf16 v[90:93], v[130:133], v[162:165], 0
	v_mfma_f32_16x16x32_bf16 v[90:93], v[134:137], v[166:169], v[90:93]
	v_mfma_f32_16x16x32_bf16 v[98:101], v[138:141], v[162:165], 0
	v_mfma_f32_16x16x32_bf16 v[98:101], v[142:145], v[166:169], v[98:101]
	v_mfma_f32_16x16x32_bf16 v[106:109], v[146:149], v[162:165], 0
	v_mfma_f32_16x16x32_bf16 v[106:109], v[150:153], v[166:169], v[106:109]
	v_mfma_f32_16x16x32_bf16 v[114:117], v[154:157], v[162:165], 0
	v_mfma_f32_16x16x32_bf16 v[114:117], v[158:161], v[166:169], v[114:117]
	v_mfma_f32_16x16x32_bf16 v[122:125], v[130:133], v[170:173], 0
	v_mfma_f32_16x16x32_bf16 v[122:125], v[134:137], v[174:177], v[122:125]
	v_mfma_f32_16x16x32_bf16 v[126:129], v[138:141], v[170:173], 0
	v_mfma_f32_16x16x32_bf16 v[126:129], v[142:145], v[174:177], v[126:129]
	v_mfma_f32_16x16x32_bf16 v[118:121], v[146:149], v[170:173], 0
	v_mfma_f32_16x16x32_bf16 v[118:121], v[150:153], v[174:177], v[118:121]
	v_mfma_f32_16x16x32_bf16 v[110:113], v[154:157], v[170:173], 0
	v_mfma_f32_16x16x32_bf16 v[110:113], v[158:161], v[174:177], v[110:113]
	v_mfma_f32_16x16x32_bf16 v[102:105], v[130:133], v[178:181], 0
	v_mfma_f32_16x16x32_bf16 v[102:105], v[134:137], v[182:185], v[102:105]
	v_mfma_f32_16x16x32_bf16 v[94:97], v[138:141], v[178:181], 0
	v_mfma_f32_16x16x32_bf16 v[94:97], v[142:145], v[182:185], v[94:97]
	v_mfma_f32_16x16x32_bf16 v[86:89], v[146:149], v[178:181], 0
	v_mfma_f32_16x16x32_bf16 v[86:89], v[150:153], v[182:185], v[86:89]
	v_mfma_f32_16x16x32_bf16 v[82:85], v[154:157], v[178:181], 0
	v_mfma_f32_16x16x32_bf16 v[82:85], v[158:161], v[182:185], v[82:85]
	v_mfma_f32_16x16x32_bf16 v[78:81], v[130:133], v[186:189], 0
	v_mfma_f32_16x16x32_bf16 v[78:81], v[134:137], v[222:225], v[78:81]
	v_mfma_f32_16x16x32_bf16 v[74:77], v[138:141], v[186:189], 0
	v_mfma_f32_16x16x32_bf16 v[74:77], v[142:145], v[222:225], v[74:77]
	v_mfma_f32_16x16x32_bf16 v[70:73], v[146:149], v[186:189], 0
	v_mfma_f32_16x16x32_bf16 v[70:73], v[150:153], v[222:225], v[70:73]
	v_mfma_f32_16x16x32_bf16 v[66:69], v[154:157], v[186:189], 0
	v_mfma_f32_16x16x32_bf16 v[66:69], v[158:161], v[222:225], v[66:69]
	s_waitcnt vmcnt(8)
	s_barrier
	s_setprio 0
	s_add_i32 s72, s83, s59
	s_mov_b32 m0, s72
	ds_read_b128 v[162:165], v241 offset:16384
	ds_read_b128 v[166:169], v241 offset:17408
	ds_read_b128 v[170:173], v241 offset:18432
	ds_read_b128 v[174:177], v241 offset:19456
	ds_read_b128 v[178:181], v241 offset:20480
	ds_read_b128 v[182:185], v241 offset:21504
	ds_read_b128 v[186:189], v241 offset:22528
	ds_read_b128 v[222:225], v241 offset:23552
	global_load_lds_dwordx4 v190, s[40:41]
	s_add_i32 m0, s72, 0x2000
	s_add_u32 s72, s40, 0x4000
	s_addc_u32 s73, s41, 0
	s_add_i32 s74, s84, s59
	global_load_lds_dwordx4 v192, s[40:41]
	s_mov_b32 m0, s74
	s_nop 0
	global_load_lds_dwordx4 v190, s[72:73]
	s_add_i32 m0, s74, 0x2000
	s_nop 0
	global_load_lds_dwordx4 v192, s[72:73]
	s_mov_b32 m0, s62
	s_nop 0
	global_load_lds_dwordx4 v190, s[42:43]
	s_mov_b32 m0, s63
	s_nop 0
	global_load_lds_dwordx4 v192, s[42:43]
	s_and_b64 vcc, exec, s[16:17]
	s_cbranch_vccnz .Lmy_skipw_10
	s_waitcnt vmcnt(8)
; #define PG8_STAGE(bufoff, gbase, voff) do { _Pragma("unroll") for (int _i = 0; _i < 2; ++_i) \
;         __builtin_amdgcn_global_load_lds((const unsigned*)((const char*)(gbase) + (voff)[_i]), (PG8_LAS unsigned*)(lds + (bufoff) + ldsw + _i * 8192), 16, 0, 0); } while (0)
; #define PG8_LDA(dst, b, h) do { _Pragma("unroll") for (int m = 0; m < 4; ++m) _Pragma("unroll") for (int k = 0; k < 2; ++k) dst[m][k] = *(const PG8_LAS bf16x8*)(lds + PG8_SA(b, h) + aoff + m * 2048 + k * 1024); } while (0)
; #define PG8_LDB(dst, b, h) do { _Pragma("unroll") for (int n = 0; n < 2; ++n) _Pragma("unroll") for (int k = 0; k < 2; ++k) dst[n][k] = *(const PG8_LAS bf16x8*)(lds + PG8_SB(b, h) + boff + n * 2048 + k * 1024); } while (0)
; #define PG8_MMA(ai, bj, At, Bt) do { __builtin_amdgcn_s_setprio(1); _Pragma("unroll") for (int m = 0; m < 4; ++m) _Pragma("unroll") for (int n = 0; n < 2; ++n) _Pragma("unroll") for (int k = 0; k < 2; ++k) \
;         acc[ai][bj][m][n] = __builtin_amdgcn_mfma_f32_16x16x32_bf16(Bt[n][k], At[m][k], acc[ai][bj][m][n], 0, 0, 0); __builtin_amdgcn_s_setprio(0); } while (0)
; #define PG8_WAIT_V(n) asm volatile("s_waitcnt vmcnt(" #n ")" ::: "memory")
; #define PG8_WAIT_L(n) asm volatile("s_waitcnt lgkmcnt(" #n ")" ::: "memory")
; #define PG8_BAR __builtin_amdgcn_s_barrier()
; #define PG8_SCHED __builtin_amdgcn_sched_barrier(0)
; template <class Epi, class Sched, bool ALIGN_EPI = false, bool SP2 = false, bool A_TILED = false>
; __device__ __forceinline__ void gemm_phase(PG8_LAS unsigned char* lds, const Gemm g, const Sched& S, const Epi& E) {
;     ...
;             PG8_WAIT_V(8); PG8_WAIT_L(0); PG8_BAR; PG8_MMA(1, 0, At, B0); PG8_MMA(1, 1, At, B1); PG8_BAR; PG8_SCHED;
;             PG8_LDB(B0, 1, 0); PG8_LDB(B1, 1, 1); PG8_SCHED; PG8_LDA(At, 1, 0); PG8_STAGE(PG8_SA(0, 1), a2 + hstepA, voffA);
;             PG8_WAIT_V(8); PG8_WAIT_L(0); PG8_BAR; PG8_MMA(0, 0, At, B0); PG8_MMA(0, 1, At, B1); PG8_BAR; PG8_SCHED;
;             PG8_LDA(At, 1, 1); PG8_STAGE(PG8_SB(1, 0), b3, voffB); PG8_STAGE(PG8_SB(1, 1), b3 + hstepB, voffB); PG8_STAGE(PG8_SA(1, 0), a3, voffA);
.Lmy_skipw_10:
	s_waitcnt lgkmcnt(0)
	s_setprio 1
	s_barrier
	v_mfma_f32_16x16x32_bf16 v[62:65], v[130:133], v[162:165], 0
	v_mfma_f32_16x16x32_bf16 v[62:65], v[134:137], v[166:169], v[62:65]
	v_mfma_f32_16x16x32_bf16 v[58:61], v[138:141], v[162:165], 0
	v_mfma_f32_16x16x32_bf16 v[58:61], v[142:145], v[166:169], v[58:61]
	v_mfma_f32_16x16x32_bf16 v[54:57], v[146:149], v[162:165], 0
	v_mfma_f32_16x16x32_bf16 v[54:57], v[150:153], v[166:169], v[54:57]
	v_mfma_f32_16x16x32_bf16 v[50:53], v[154:157], v[162:165], 0
	v_mfma_f32_16x16x32_bf16 v[50:53], v[158:161], v[166:169], v[50:53]
	v_mfma_f32_16x16x32_bf16 v[46:49], v[130:133], v[170:173], 0
	v_mfma_f32_16x16x32_bf16 v[46:49], v[134:137], v[174:177], v[46:49]
	v_mfma_f32_16x16x32_bf16 v[42:45], v[138:141], v[170:173], 0
	v_mfma_f32_16x16x32_bf16 v[42:45], v[142:145], v[174:177], v[42:45]
	v_mfma_f32_16x16x32_bf16 v[38:41], v[146:149], v[170:173], 0
	v_mfma_f32_16x16x32_bf16 v[38:41], v[150:153], v[174:177], v[38:41]
	v_mfma_f32_16x16x32_bf16 v[34:37], v[154:157], v[170:173], 0
	v_mfma_f32_16x16x32_bf16 v[34:37], v[158:161], v[174:177], v[34:37]
	v_mfma_f32_16x16x32_bf16 v[30:33], v[130:133], v[178:181], 0
	v_mfma_f32_16x16x32_bf16 v[30:33], v[134:137], v[182:185], v[30:33]
	v_mfma_f32_16x16x32_bf16 v[26:29], v[138:141], v[178:181], 0
	v_mfma_f32_16x16x32_bf16 v[26:29], v[142:145], v[182:185], v[26:29]
	v_mfma_f32_16x16x32_bf16 v[22:25], v[146:149], v[178:181], 0
	v_mfma_f32_16x16x32_bf16 v[22:25], v[150:153], v[182:185], v[22:25]
	v_mfma_f32_16x16x32_bf16 v[18:21], v[154:157], v[178:181], 0
	v_mfma_f32_16x16x32_bf16 v[18:21], v[158:161], v[182:185], v[18:21]
	v_mfma_f32_16x16x32_bf16 v[14:17], v[130:133], v[186:189], 0
	v_mfma_f32_16x16x32_bf16 v[14:17], v[134:137], v[222:225], v[14:17]
	v_mfma_f32_16x16x32_bf16 v[10:13], v[138:141], v[186:189], 0
	v_mfma_f32_16x16x32_bf16 v[10:13], v[142:145], v[222:225], v[10:13]
	v_mfma_f32_16x16x32_bf16 v[6:9], v[146:149], v[186:189], 0
	v_mfma_f32_16x16x32_bf16 v[6:9], v[150:153], v[222:225], v[6:9]
	v_mfma_f32_16x16x32_bf16 v[2:5], v[154:157], v[186:189], 0
	v_mfma_f32_16x16x32_bf16 v[2:5], v[158:161], v[222:225], v[2:5]
	s_waitcnt vmcnt(8)
	s_barrier
	s_setprio 0
	s_add_i32 s72, 0, 0x18000
	s_add_i32 s73, 0, 0x1c000
	ds_read_b128 v[130:133], v197 offset:32768
	ds_read_b128 v[134:137], v197 offset:33792
	ds_read_b128 v[138:141], v197 offset:34816
	ds_read_b128 v[142:145], v197 offset:35840
	ds_read_b128 v[146:149], v197 offset:49152
	ds_read_b128 v[150:153], v197 offset:50176
	ds_read_b128 v[154:157], v197 offset:51200
	ds_read_b128 v[158:161], v197 offset:52224
	s_add_u32 s42, s42, 0x4000
	s_addc_u32 s43, s43, 0
	s_mov_b32 m0, s69
	ds_read_b128 v[162:165], v241 offset:32768
	ds_read_b128 v[166:169], v241 offset:33792
	ds_read_b128 v[170:173], v241 offset:34816
	ds_read_b128 v[174:177], v241 offset:35840
	ds_read_b128 v[178:181], v241 offset:36864
	ds_read_b128 v[182:185], v241 offset:37888
	ds_read_b128 v[186:189], v241 offset:38912
	ds_read_b128 v[222:225], v241 offset:39936
	global_load_lds_dwordx4 v190, s[42:43]
	s_mov_b32 m0, s71
	s_nop 0
	global_load_lds_dwordx4 v192, s[42:43]
	s_and_b64 vcc, exec, s[16:17]
	s_cbranch_vccnz .Lmy_skipw_11
	s_waitcnt vmcnt(8)
.Lmy_skipw_11:
	s_waitcnt lgkmcnt(0)
	s_setprio 1
	s_barrier
	v_mfma_f32_16x16x32_bf16 v[90:93], v[130:133], v[162:165], v[90:93]
	v_mfma_f32_16x16x32_bf16 v[90:93], v[134:137], v[166:169], v[90:93]
	v_mfma_f32_16x16x32_bf16 v[98:101], v[138:141], v[162:165], v[98:101]
	v_mfma_f32_16x16x32_bf16 v[98:101], v[142:145], v[166:169], v[98:101]
	v_mfma_f32_16x16x32_bf16 v[106:109], v[146:149], v[162:165], v[106:109]
	v_mfma_f32_16x16x32_bf16 v[106:109], v[150:153], v[166:169], v[106:109]
	v_mfma_f32_16x16x32_bf16 v[114:117], v[154:157], v[162:165], v[114:117]
	v_mfma_f32_16x16x32_bf16 v[114:117], v[158:161], v[166:169], v[114:117]
	v_mfma_f32_16x16x32_bf16 v[122:125], v[130:133], v[170:173], v[122:125]
	v_mfma_f32_16x16x32_bf16 v[122:125], v[134:137], v[174:177], v[122:125]
	v_mfma_f32_16x16x32_bf16 v[126:129], v[138:141], v[170:173], v[126:129]
	v_mfma_f32_16x16x32_bf16 v[126:129], v[142:145], v[174:177], v[126:129]
	v_mfma_f32_16x16x32_bf16 v[118:121], v[146:149], v[170:173], v[118:121]
	v_mfma_f32_16x16x32_bf16 v[118:121], v[150:153], v[174:177], v[118:121]
	v_mfma_f32_16x16x32_bf16 v[110:113], v[154:157], v[170:173], v[110:113]
	v_mfma_f32_16x16x32_bf16 v[110:113], v[158:161], v[174:177], v[110:113]
	v_mfma_f32_16x16x32_bf16 v[102:105], v[130:133], v[178:181], v[102:105]
	v_mfma_f32_16x16x32_bf16 v[102:105], v[134:137], v[182:185], v[102:105]
	v_mfma_f32_16x16x32_bf16 v[94:97], v[138:141], v[178:181], v[94:97]
	v_mfma_f32_16x16x32_bf16 v[94:97], v[142:145], v[182:185], v[94:97]
	v_mfma_f32_16x16x32_bf16 v[86:89], v[146:149], v[178:181], v[86:89]
	v_mfma_f32_16x16x32_bf16 v[86:89], v[150:153], v[182:185], v[86:89]
	v_mfma_f32_16x16x32_bf16 v[82:85], v[154:157], v[178:181], v[82:85]
	v_mfma_f32_16x16x32_bf16 v[82:85], v[158:161], v[182:185], v[82:85]
	v_mfma_f32_16x16x32_bf16 v[78:81], v[130:133], v[186:189], v[78:81]
	v_mfma_f32_16x16x32_bf16 v[78:81], v[134:137], v[222:225], v[78:81]
	v_mfma_f32_16x16x32_bf16 v[74:77], v[138:141], v[186:189], v[74:77]
	v_mfma_f32_16x16x32_bf16 v[74:77], v[142:145], v[222:225], v[74:77]
	v_mfma_f32_16x16x32_bf16 v[70:73], v[146:149], v[186:189], v[70:73]
	v_mfma_f32_16x16x32_bf16 v[70:73], v[150:153], v[222:225], v[70:73]
	v_mfma_f32_16x16x32_bf16 v[66:69], v[154:157], v[186:189], v[66:69]
	v_mfma_f32_16x16x32_bf16 v[66:69], v[158:161], v[222:225], v[66:69]
	s_waitcnt vmcnt(8)
	s_barrier
	s_setprio 0
	s_add_u32 s42, s40, 0x8000
	s_addc_u32 s43, s41, 0
	s_add_i32 s72, s72, s59
	s_mov_b32 m0, s72
	ds_read_b128 v[162:165], v241 offset:49152
	ds_read_b128 v[166:169], v241 offset:50176
	ds_read_b128 v[170:173], v241 offset:51200
	ds_read_b128 v[174:177], v241 offset:52224
	ds_read_b128 v[178:181], v241 offset:53248
	ds_read_b128 v[182:185], v241 offset:54272
	ds_read_b128 v[186:189], v241 offset:55296
	ds_read_b128 v[222:225], v241 offset:56320
	global_load_lds_dwordx4 v190, s[42:43]
	s_add_i32 m0, s72, 0x2000
	s_add_u32 s40, s40, 0xc000
	v_lshl_add_u64 v[226:227], s[42:43], 0, v[192:193]
	s_addc_u32 s41, s41, 0
	s_add_i32 s42, s73, s59
	global_load_lds_dwordx4 v[226:227], off
	s_mov_b32 m0, s42
	s_nop 0
	global_load_lds_dwordx4 v190, s[40:41]
	s_add_i32 m0, s42, 0x2000
	s_nop 0
	global_load_lds_dwordx4 v192, s[40:41]
	s_mov_b32 m0, s80
	s_nop 0
	global_load_lds_dwordx4 v190, s[38:39]
	s_mov_b32 m0, s81
	s_nop 0
	global_load_lds_dwordx4 v192, s[38:39]
	s_and_b64 vcc, exec, s[16:17]
	s_cbranch_vccnz .Lmy_skipw_12
	s_waitcnt vmcnt(8)
; #define PG8_STAGE(bufoff, gbase, voff) do { _Pragma("unroll") for (int _i = 0; _i < 2; ++_i) \
;         __builtin_amdgcn_global_load_lds((const unsigned*)((const char*)(gbase) + (voff)[_i]), (PG8_LAS unsigned*)(lds + (bufoff) + ldsw + _i * 8192), 16, 0, 0); } while (0)
; #define PG8_LDA(dst, b, h) do { _Pragma("unroll") for (int m = 0; m < 4; ++m) _Pragma("unroll") for (int k = 0; k < 2; ++k) dst[m][k] = *(const PG8_LAS bf16x8*)(lds + PG8_SA(b, h) + aoff + m * 2048 + k * 1024); } while (0)
; #define PG8_LDB(dst, b, h) do { _Pragma("unroll") for (int n = 0; n < 2; ++n) _Pragma("unroll") for (int k = 0; k < 2; ++k) dst[n][k] = *(const PG8_LAS bf16x8*)(lds + PG8_SB(b, h) + boff + n * 2048 + k * 1024); } while (0)
; #define PG8_MMA(ai, bj, At, Bt) do { __builtin_amdgcn_s_setprio(1); _Pragma("unroll") for (int m = 0; m < 4; ++m) _Pragma("unroll") for (int n = 0; n < 2; ++n) _Pragma("unroll") for (int k = 0; k < 2; ++k) \
;         acc[ai][bj][m][n] = __builtin_amdgcn_mfma_f32_16x16x32_bf16(Bt[n][k], At[m][k], acc[ai][bj][m][n], 0, 0, 0); __builtin_amdgcn_s_setprio(0); } while (0)
; #define PG8_WAIT_V(n) asm volatile("s_waitcnt vmcnt(" #n ")" ::: "memory")
; #define PG8_WAIT_L(n) asm volatile("s_waitcnt lgkmcnt(" #n ")" ::: "memory")
; #define PG8_BAR __builtin_amdgcn_s_barrier()
; #define PG8_SCHED __builtin_amdgcn_sched_barrier(0)
; template <class Epi, class Sched, bool ALIGN_EPI = false, bool SP2 = false, bool A_TILED = false>
; __device__ __forceinline__ void gemm_phase(PG8_LAS unsigned char* lds, const Gemm g, const Sched& S, const Epi& E) {
;     ...
;         for (int t = 0; t < nt; t += 2) {
;             const bool last = (t == nt - 2);
;             const char* a1 = cA + (size_t)(t + 1) * kstepA;
;             const char* a2 = last ? nA : cA + (size_t)(t + 2) * kstepA; const char* b2 = last ? nB : cB + (size_t)(t + 2) * kstepB;
;             const char* a3 = a2 + kstepA; const char* b3 = b2 + kstepB;
;             if (last && has_next) S.a_ready(nxt);
;             if constexpr (SP2) {
;             PG8_LDB(B0, 0, 0); PG8_LDB(B1, 0, 1); PG8_SCHED; PG8_LDA(At, 0, 0); PG8_STAGE(PG8_SA(1, 1), a1 + hstepA, voffA);
;             PG8_WAIT_V(8); PG8_WAIT_L(0); PG8_BAR; PG8_MMA(0, 0, At, B0); PG8_MMA(0, 1, At, B1); PG8_BAR; PG8_SCHED;
;     ...
;             PG8_WAIT_V(8); PG8_WAIT_L(0); PG8_BAR; PG8_MMA(1, 0, At, B0); PG8_MMA(1, 1, At, B1); PG8_BAR; PG8_SCHED;
.Lmy_skipw_12:
	s_waitcnt lgkmcnt(0)
	s_setprio 1
	s_barrier
	v_mfma_f32_16x16x32_bf16 v[62:65], v[130:133], v[162:165], v[62:65]
	v_mfma_f32_16x16x32_bf16 v[62:65], v[134:137], v[166:169], v[62:65]
	v_mfma_f32_16x16x32_bf16 v[58:61], v[138:141], v[162:165], v[58:61]
	v_mfma_f32_16x16x32_bf16 v[58:61], v[142:145], v[166:169], v[58:61]
	v_mfma_f32_16x16x32_bf16 v[54:57], v[146:149], v[162:165], v[54:57]
	v_mfma_f32_16x16x32_bf16 v[54:57], v[150:153], v[166:169], v[54:57]
	v_mfma_f32_16x16x32_bf16 v[50:53], v[154:157], v[162:165], v[50:53]
	v_mfma_f32_16x16x32_bf16 v[50:53], v[158:161], v[166:169], v[50:53]
	v_mfma_f32_16x16x32_bf16 v[46:49], v[130:133], v[170:173], v[46:49]
	v_mfma_f32_16x16x32_bf16 v[46:49], v[134:137], v[174:177], v[46:49]
	v_mfma_f32_16x16x32_bf16 v[42:45], v[138:141], v[170:173], v[42:45]
	v_mfma_f32_16x16x32_bf16 v[42:45], v[142:145], v[174:177], v[42:45]
	v_mfma_f32_16x16x32_bf16 v[38:41], v[146:149], v[170:173], v[38:41]
	v_mfma_f32_16x16x32_bf16 v[38:41], v[150:153], v[174:177], v[38:41]
	v_mfma_f32_16x16x32_bf16 v[34:37], v[154:157], v[170:173], v[34:37]
	v_mfma_f32_16x16x32_bf16 v[34:37], v[158:161], v[174:177], v[34:37]
	v_mfma_f32_16x16x32_bf16 v[30:33], v[130:133], v[178:181], v[30:33]
	v_mfma_f32_16x16x32_bf16 v[30:33], v[134:137], v[182:185], v[30:33]
	v_mfma_f32_16x16x32_bf16 v[26:29], v[138:141], v[178:181], v[26:29]
	v_mfma_f32_16x16x32_bf16 v[26:29], v[142:145], v[182:185], v[26:29]
	v_mfma_f32_16x16x32_bf16 v[22:25], v[146:149], v[178:181], v[22:25]
	v_mfma_f32_16x16x32_bf16 v[22:25], v[150:153], v[182:185], v[22:25]
	v_mfma_f32_16x16x32_bf16 v[18:21], v[154:157], v[178:181], v[18:21]
	v_mfma_f32_16x16x32_bf16 v[18:21], v[158:161], v[182:185], v[18:21]
	v_mfma_f32_16x16x32_bf16 v[14:17], v[130:133], v[186:189], v[14:17]
	v_mfma_f32_16x16x32_bf16 v[14:17], v[134:137], v[222:225], v[14:17]
	v_mfma_f32_16x16x32_bf16 v[10:13], v[138:141], v[186:189], v[10:13]
	v_mfma_f32_16x16x32_bf16 v[10:13], v[142:145], v[222:225], v[10:13]
	v_mfma_f32_16x16x32_bf16 v[6:9], v[146:149], v[186:189], v[6:9]
	v_mfma_f32_16x16x32_bf16 v[6:9], v[150:153], v[222:225], v[6:9]
	v_mfma_f32_16x16x32_bf16 v[2:5], v[154:157], v[186:189], v[2:5]
	v_mfma_f32_16x16x32_bf16 v[2:5], v[158:161], v[222:225], v[2:5]
	s_waitcnt vmcnt(8)
	s_barrier
	s_setprio 0
	s_add_i32 s70, s70, 2
	s_add_u32 s36, s36, 0x10000
	s_addc_u32 s37, s37, 0
	s_add_u32 s33, s33, 0x10000
	s_addc_u32 s35, s35, 0
.LBB0_274:
	ds_read_b128 v[130:133], v197
	ds_read_b128 v[134:137], v197 offset:1024
	ds_read_b128 v[138:141], v197 offset:2048
	ds_read_b128 v[142:145], v197 offset:3072
	ds_read_b128 v[146:149], v240
	ds_read_b128 v[150:153], v240 offset:1024
	ds_read_b128 v[154:157], v240 offset:2048
	ds_read_b128 v[158:161], v240 offset:3072
	s_add_u32 s38, s36, 0x4000
	s_addc_u32 s39, s37, 0
	s_cmpk_eq_i32 s70, 0xa8
	s_cselect_b32 s42, s4, s38
	s_cselect_b32 s43, s5, s39
	s_cselect_b32 s40, s30, s33
	s_cselect_b32 s41, s31, s35
	s_add_u32 s38, s42, 0x8000
	s_addc_u32 s39, s43, 0
	s_add_i32 m0, s62, 0xc000
	ds_read_b128 v[162:165], v241
	ds_read_b128 v[166:169], v241 offset:1024
	ds_read_b128 v[170:173], v241 offset:2048
	ds_read_b128 v[174:177], v241 offset:3072
	ds_read_b128 v[178:181], v241 offset:4096
	ds_read_b128 v[182:185], v241 offset:5120
	ds_read_b128 v[186:189], v241 offset:6144
	ds_read_b128 v[222:225], v241 offset:7168
	global_load_lds_dwordx4 v214, s[36:37]
	s_add_i32 m0, s62, 0xe000
	s_nop 0
	global_load_lds_dwordx4 v216, s[36:37]
	s_and_b64 vcc, exec, s[16:17]
	s_cbranch_vccnz .Lmy_skipw_13
	s_waitcnt vmcnt(8)
; #define PG8_STAGE(bufoff, gbase, voff) do { _Pragma("unroll") for (int _i = 0; _i < 2; ++_i) \
;         __builtin_amdgcn_global_load_lds((const unsigned*)((const char*)(gbase) + (voff)[_i]), (PG8_LAS unsigned*)(lds + (bufoff) + ldsw + _i * 8192), 16, 0, 0); } while (0)
; #define PG8_LDA(dst, b, h) do { _Pragma("unroll") for (int m = 0; m < 4; ++m) _Pragma("unroll") for (int k = 0; k < 2; ++k) dst[m][k] = *(const PG8_LAS bf16x8*)(lds + PG8_SA(b, h) + aoff + m * 2048 + k * 1024); } while (0)
; #define PG8_LDB(dst, b, h) do { _Pragma("unroll") for (int n = 0; n < 2; ++n) _Pragma("unroll") for (int k = 0; k < 2; ++k) dst[n][k] = *(const PG8_LAS bf16x8*)(lds + PG8_SB(b, h) + boff + n * 2048 + k * 1024); } while (0)
; #define PG8_MMA(ai, bj, At, Bt) do { __builtin_amdgcn_s_setprio(1); _Pragma("unroll") for (int m = 0; m < 4; ++m) _Pragma("unroll") for (int n = 0; n < 2; ++n) _Pragma("unroll") for (int k = 0; k < 2; ++k) \
;         acc[ai][bj][m][n] = __builtin_amdgcn_mfma_f32_16x16x32_bf16(Bt[n][k], At[m][k], acc[ai][bj][m][n], 0, 0, 0); __builtin_amdgcn_s_setprio(0); } while (0)
; #define PG8_WAIT_V(n) asm volatile("s_waitcnt vmcnt(" #n ")" ::: "memory")
; #define PG8_WAIT_L(n) asm volatile("s_waitcnt lgkmcnt(" #n ")" ::: "memory")
; #define PG8_BAR __builtin_amdgcn_s_barrier()
; #define PG8_SCHED __builtin_amdgcn_sched_barrier(0)
; template <class Epi, class Sched, bool ALIGN_EPI = false, bool SP2 = false, bool A_TILED = false>
; __device__ __forceinline__ void gemm_phase(PG8_LAS unsigned char* lds, const Gemm g, const Sched& S, const Epi& E) {
;     ...
;             PG8_WAIT_V(8); PG8_WAIT_L(0); PG8_BAR; PG8_MMA(0, 0, At, B0); PG8_MMA(0, 1, At, B1); PG8_BAR; PG8_SCHED;
;             PG8_LDA(At, 0, 1); PG8_STAGE(PG8_SB(0, 0), b2, voffB); PG8_STAGE(PG8_SB(0, 1), b2 + hstepB, voffB); PG8_STAGE(PG8_SA(0, 0), a2, voffA);
;             PG8_WAIT_V(8); PG8_WAIT_L(0); PG8_BAR; PG8_MMA(1, 0, At, B0); PG8_MMA(1, 1, At, B1); PG8_BAR; PG8_SCHED;
;             PG8_LDB(B0, 1, 0); PG8_LDB(B1, 1, 1); PG8_SCHED; PG8_LDA(At, 1, 0); PG8_STAGE(PG8_SA(0, 1), a2 + hstepA, voffA);
;             PG8_WAIT_V(8); PG8_WAIT_L(0); PG8_BAR; PG8_MMA(0, 0, At, B0); PG8_MMA(0, 1, At, B1); PG8_BAR; PG8_SCHED;
;             PG8_LDA(At, 1, 1); PG8_STAGE(PG8_SB(1, 0), b3, voffB); PG8_STAGE(PG8_SB(1, 1), b3 + hstepB, voffB); PG8_STAGE(PG8_SA(1, 0), a3, voffA);
.Lmy_skipw_13:
	s_waitcnt lgkmcnt(0)
	s_setprio 1
	s_barrier
	v_mfma_f32_16x16x32_bf16 v[90:93], v[130:133], v[162:165], v[90:93]
	v_mfma_f32_16x16x32_bf16 v[90:93], v[134:137], v[166:169], v[90:93]
	v_mfma_f32_16x16x32_bf16 v[98:101], v[138:141], v[162:165], v[98:101]
	v_mfma_f32_16x16x32_bf16 v[98:101], v[142:145], v[166:169], v[98:101]
	v_mfma_f32_16x16x32_bf16 v[106:109], v[146:149], v[162:165], v[106:109]
	v_mfma_f32_16x16x32_bf16 v[106:109], v[150:153], v[166:169], v[106:109]
	v_mfma_f32_16x16x32_bf16 v[114:117], v[154:157], v[162:165], v[114:117]
	v_mfma_f32_16x16x32_bf16 v[114:117], v[158:161], v[166:169], v[114:117]
	v_mfma_f32_16x16x32_bf16 v[122:125], v[130:133], v[170:173], v[122:125]
	v_mfma_f32_16x16x32_bf16 v[122:125], v[134:137], v[174:177], v[122:125]
	v_mfma_f32_16x16x32_bf16 v[126:129], v[138:141], v[170:173], v[126:129]
	v_mfma_f32_16x16x32_bf16 v[126:129], v[142:145], v[174:177], v[126:129]
	v_mfma_f32_16x16x32_bf16 v[118:121], v[146:149], v[170:173], v[118:121]
	v_mfma_f32_16x16x32_bf16 v[118:121], v[150:153], v[174:177], v[118:121]
	v_mfma_f32_16x16x32_bf16 v[110:113], v[154:157], v[170:173], v[110:113]
	v_mfma_f32_16x16x32_bf16 v[110:113], v[158:161], v[174:177], v[110:113]
	v_mfma_f32_16x16x32_bf16 v[102:105], v[130:133], v[178:181], v[102:105]
	v_mfma_f32_16x16x32_bf16 v[102:105], v[134:137], v[182:185], v[102:105]
	v_mfma_f32_16x16x32_bf16 v[94:97], v[138:141], v[178:181], v[94:97]
	v_mfma_f32_16x16x32_bf16 v[94:97], v[142:145], v[182:185], v[94:97]
	v_mfma_f32_16x16x32_bf16 v[86:89], v[146:149], v[178:181], v[86:89]
	v_mfma_f32_16x16x32_bf16 v[86:89], v[150:153], v[182:185], v[86:89]
	v_mfma_f32_16x16x32_bf16 v[82:85], v[154:157], v[178:181], v[82:85]
	v_mfma_f32_16x16x32_bf16 v[82:85], v[158:161], v[182:185], v[82:85]
	v_mfma_f32_16x16x32_bf16 v[78:81], v[130:133], v[186:189], v[78:81]
	v_mfma_f32_16x16x32_bf16 v[78:81], v[134:137], v[222:225], v[78:81]
	v_mfma_f32_16x16x32_bf16 v[74:77], v[138:141], v[186:189], v[74:77]
	v_mfma_f32_16x16x32_bf16 v[74:77], v[142:145], v[222:225], v[74:77]
	v_mfma_f32_16x16x32_bf16 v[70:73], v[146:149], v[186:189], v[70:73]
	v_mfma_f32_16x16x32_bf16 v[70:73], v[150:153], v[222:225], v[70:73]
	v_mfma_f32_16x16x32_bf16 v[66:69], v[154:157], v[186:189], v[66:69]
	v_mfma_f32_16x16x32_bf16 v[66:69], v[158:161], v[222:225], v[66:69]
	s_waitcnt vmcnt(8)
	s_barrier
	s_setprio 0
	s_add_i32 s72, s83, s59
	s_mov_b32 m0, s72
	ds_read_b128 v[162:165], v241 offset:16384
	ds_read_b128 v[166:169], v241 offset:17408
	ds_read_b128 v[170:173], v241 offset:18432
	ds_read_b128 v[174:177], v241 offset:19456
	ds_read_b128 v[178:181], v241 offset:20480
	ds_read_b128 v[182:185], v241 offset:21504
	ds_read_b128 v[186:189], v241 offset:22528
	ds_read_b128 v[222:225], v241 offset:23552
	global_load_lds_dwordx4 v190, s[40:41]
	s_add_i32 m0, s72, 0x2000
	s_add_u32 s72, s40, 0x4000
	s_addc_u32 s73, s41, 0
	s_add_i32 s74, s84, s59
	global_load_lds_dwordx4 v192, s[40:41]
	s_mov_b32 m0, s74
	s_nop 0
	global_load_lds_dwordx4 v190, s[72:73]
	s_add_i32 m0, s74, 0x2000
	s_nop 0
	global_load_lds_dwordx4 v192, s[72:73]
	s_mov_b32 m0, s62
	s_nop 0
	global_load_lds_dwordx4 v190, s[42:43]
	s_mov_b32 m0, s63
	s_nop 0
	global_load_lds_dwordx4 v192, s[42:43]
	s_and_b64 vcc, exec, s[16:17]
	s_cbranch_vccnz .Lmy_skipw_14
	s_waitcnt vmcnt(8)
.Lmy_skipw_14:
	s_waitcnt lgkmcnt(0)
	s_setprio 1
	s_barrier
	v_mfma_f32_16x16x32_bf16 v[62:65], v[130:133], v[162:165], v[62:65]
	v_mfma_f32_16x16x32_bf16 v[62:65], v[134:137], v[166:169], v[62:65]
	v_mfma_f32_16x16x32_bf16 v[58:61], v[138:141], v[162:165], v[58:61]
	v_mfma_f32_16x16x32_bf16 v[58:61], v[142:145], v[166:169], v[58:61]
	v_mfma_f32_16x16x32_bf16 v[54:57], v[146:149], v[162:165], v[54:57]
	v_mfma_f32_16x16x32_bf16 v[54:57], v[150:153], v[166:169], v[54:57]
	v_mfma_f32_16x16x32_bf16 v[50:53], v[154:157], v[162:165], v[50:53]
	v_mfma_f32_16x16x32_bf16 v[50:53], v[158:161], v[166:169], v[50:53]
	v_mfma_f32_16x16x32_bf16 v[46:49], v[130:133], v[170:173], v[46:49]
	v_mfma_f32_16x16x32_bf16 v[46:49], v[134:137], v[174:177], v[46:49]
	v_mfma_f32_16x16x32_bf16 v[42:45], v[138:141], v[170:173], v[42:45]
	v_mfma_f32_16x16x32_bf16 v[42:45], v[142:145], v[174:177], v[42:45]
	v_mfma_f32_16x16x32_bf16 v[38:41], v[146:149], v[170:173], v[38:41]
	v_mfma_f32_16x16x32_bf16 v[38:41], v[150:153], v[174:177], v[38:41]
	v_mfma_f32_16x16x32_bf16 v[34:37], v[154:157], v[170:173], v[34:37]
	v_mfma_f32_16x16x32_bf16 v[34:37], v[158:161], v[174:177], v[34:37]
	v_mfma_f32_16x16x32_bf16 v[30:33], v[130:133], v[178:181], v[30:33]
	v_mfma_f32_16x16x32_bf16 v[30:33], v[134:137], v[182:185], v[30:33]
	v_mfma_f32_16x16x32_bf16 v[26:29], v[138:141], v[178:181], v[26:29]
	v_mfma_f32_16x16x32_bf16 v[26:29], v[142:145], v[182:185], v[26:29]
	v_mfma_f32_16x16x32_bf16 v[22:25], v[146:149], v[178:181], v[22:25]
	v_mfma_f32_16x16x32_bf16 v[22:25], v[150:153], v[182:185], v[22:25]
	v_mfma_f32_16x16x32_bf16 v[18:21], v[154:157], v[178:181], v[18:21]
	v_mfma_f32_16x16x32_bf16 v[18:21], v[158:161], v[182:185], v[18:21]
	v_mfma_f32_16x16x32_bf16 v[14:17], v[130:133], v[186:189], v[14:17]
	v_mfma_f32_16x16x32_bf16 v[14:17], v[134:137], v[222:225], v[14:17]
	v_mfma_f32_16x16x32_bf16 v[10:13], v[138:141], v[186:189], v[10:13]
	v_mfma_f32_16x16x32_bf16 v[10:13], v[142:145], v[222:225], v[10:13]
	v_mfma_f32_16x16x32_bf16 v[6:9], v[146:149], v[186:189], v[6:9]
	v_mfma_f32_16x16x32_bf16 v[6:9], v[150:153], v[222:225], v[6:9]
	v_mfma_f32_16x16x32_bf16 v[2:5], v[154:157], v[186:189], v[2:5]
	v_mfma_f32_16x16x32_bf16 v[2:5], v[158:161], v[222:225], v[2:5]
	s_waitcnt vmcnt(8)
	s_barrier
	s_setprio 0
	s_add_i32 s72, 0, 0x18000
	s_add_i32 s73, 0, 0x1c000
	ds_read_b128 v[130:133], v197 offset:32768
	ds_read_b128 v[134:137], v197 offset:33792
	ds_read_b128 v[138:141], v197 offset:34816
	ds_read_b128 v[142:145], v197 offset:35840
	ds_read_b128 v[146:149], v197 offset:49152
	ds_read_b128 v[150:153], v197 offset:50176
	ds_read_b128 v[154:157], v197 offset:51200
	ds_read_b128 v[158:161], v197 offset:52224
	s_add_u32 s42, s42, 0x4000
	s_addc_u32 s43, s43, 0
	s_mov_b32 m0, s69
	ds_read_b128 v[162:165], v241 offset:32768
	ds_read_b128 v[166:169], v241 offset:33792
	ds_read_b128 v[170:173], v241 offset:34816
	ds_read_b128 v[174:177], v241 offset:35840
	ds_read_b128 v[178:181], v241 offset:36864
	ds_read_b128 v[182:185], v241 offset:37888
	ds_read_b128 v[186:189], v241 offset:38912
	ds_read_b128 v[222:225], v241 offset:39936
	global_load_lds_dwordx4 v190, s[42:43]
	s_mov_b32 m0, s71
	s_nop 0
	global_load_lds_dwordx4 v192, s[42:43]
	s_and_b64 vcc, exec, s[16:17]
	s_cbranch_vccnz .Lmy_skipw_15
	s_waitcnt vmcnt(8)

; #define PG8_STAGE(bufoff, gbase, voff) do { _Pragma("unroll") for (int _i = 0; _i < 2; ++_i) \
;         __builtin_amdgcn_global_load_lds((const unsigned*)((const char*)(gbase) + (voff)[_i]), (PG8_LAS unsigned*)(lds + (bufoff) + ldsw + _i * 8192), 16, 0, 0); } while (0)
; #define PG8_LDA(dst, b, h) do { _Pragma("unroll") for (int m = 0; m < 4; ++m) _Pragma("unroll") for (int k = 0; k < 2; ++k) dst[m][k] = *(const PG8_LAS bf16x8*)(lds + PG8_SA(b, h) + aoff + m * 2048 + k * 1024); } while (0)
; #define PG8_MMA(ai, bj, At, Bt) do { __builtin_amdgcn_s_setprio(1); _Pragma("unroll") for (int m = 0; m < 4; ++m) _Pragma("unroll") for (int n = 0; n < 2; ++n) _Pragma("unroll") for (int k = 0; k < 2; ++k) \
;         acc[ai][bj][m][n] = __builtin_amdgcn_mfma_f32_16x16x32_bf16(Bt[n][k], At[m][k], acc[ai][bj][m][n], 0, 0, 0); __builtin_amdgcn_s_setprio(0); } while (0)
; #define PG8_WAIT_V(n) asm volatile("s_waitcnt vmcnt(" #n ")" ::: "memory")
; #define PG8_WAIT_L(n) asm volatile("s_waitcnt lgkmcnt(" #n ")" ::: "memory")
; #define PG8_BAR __builtin_amdgcn_s_barrier()
; #define PG8_SCHED __builtin_amdgcn_sched_barrier(0)
; template <class Epi, class Sched, bool ALIGN_EPI = false, bool SP2 = false, bool A_TILED = false>
; __device__ __forceinline__ void gemm_phase(PG8_LAS unsigned char* lds, const Gemm g, const Sched& S, const Epi& E) {
;     ...
;             PG8_LDA(At, 1, 1); PG8_STAGE(PG8_SB(1, 0), b3, voffB); PG8_STAGE(PG8_SB(1, 1), b3 + hstepB, voffB); PG8_STAGE(PG8_SA(1, 0), a3, voffA);
;             PG8_WAIT_V(8); PG8_WAIT_L(0); PG8_BAR; PG8_MMA(1, 0, At, B0); PG8_MMA(1, 1, At, B1); PG8_BAR; PG8_SCHED;
.Lmy_skipw_16:
	s_waitcnt lgkmcnt(0)
	s_setprio 1
	s_barrier
	v_mfma_f32_16x16x32_bf16 v[62:65], v[130:133], v[162:165], v[62:65]
	v_mfma_f32_16x16x32_bf16 v[62:65], v[134:137], v[166:169], v[62:65]
	v_mfma_f32_16x16x32_bf16 v[58:61], v[138:141], v[162:165], v[58:61]
	v_mfma_f32_16x16x32_bf16 v[58:61], v[142:145], v[166:169], v[58:61]
	v_mfma_f32_16x16x32_bf16 v[54:57], v[146:149], v[162:165], v[54:57]
	v_mfma_f32_16x16x32_bf16 v[54:57], v[150:153], v[166:169], v[54:57]
	v_mfma_f32_16x16x32_bf16 v[50:53], v[154:157], v[162:165], v[50:53]
	v_mfma_f32_16x16x32_bf16 v[50:53], v[158:161], v[166:169], v[50:53]
	v_mfma_f32_16x16x32_bf16 v[46:49], v[130:133], v[170:173], v[46:49]
	v_mfma_f32_16x16x32_bf16 v[46:49], v[134:137], v[174:177], v[46:49]
	v_mfma_f32_16x16x32_bf16 v[42:45], v[138:141], v[170:173], v[42:45]
	v_mfma_f32_16x16x32_bf16 v[42:45], v[142:145], v[174:177], v[42:45]
	v_mfma_f32_16x16x32_bf16 v[38:41], v[146:149], v[170:173], v[38:41]
	v_mfma_f32_16x16x32_bf16 v[38:41], v[150:153], v[174:177], v[38:41]
	v_mfma_f32_16x16x32_bf16 v[34:37], v[154:157], v[170:173], v[34:37]
	v_mfma_f32_16x16x32_bf16 v[34:37], v[158:161], v[174:177], v[34:37]
	v_mfma_f32_16x16x32_bf16 v[30:33], v[130:133], v[178:181], v[30:33]
	v_mfma_f32_16x16x32_bf16 v[30:33], v[134:137], v[182:185], v[30:33]
	v_mfma_f32_16x16x32_bf16 v[26:29], v[138:141], v[178:181], v[26:29]
	v_mfma_f32_16x16x32_bf16 v[26:29], v[142:145], v[182:185], v[26:29]
	v_mfma_f32_16x16x32_bf16 v[22:25], v[146:149], v[178:181], v[22:25]
	v_mfma_f32_16x16x32_bf16 v[22:25], v[150:153], v[182:185], v[22:25]
	v_mfma_f32_16x16x32_bf16 v[18:21], v[154:157], v[178:181], v[18:21]
	v_mfma_f32_16x16x32_bf16 v[18:21], v[158:161], v[182:185], v[18:21]
	v_mfma_f32_16x16x32_bf16 v[14:17], v[130:133], v[186:189], v[14:17]
	v_mfma_f32_16x16x32_bf16 v[14:17], v[134:137], v[222:225], v[14:17]
	v_mfma_f32_16x16x32_bf16 v[10:13], v[138:141], v[186:189], v[10:13]
	v_mfma_f32_16x16x32_bf16 v[10:13], v[142:145], v[222:225], v[10:13]
	v_mfma_f32_16x16x32_bf16 v[6:9], v[146:149], v[186:189], v[6:9]
	v_mfma_f32_16x16x32_bf16 v[6:9], v[150:153], v[222:225], v[6:9]
	v_mfma_f32_16x16x32_bf16 v[2:5], v[154:157], v[186:189], v[2:5]
	v_mfma_f32_16x16x32_bf16 v[2:5], v[158:161], v[222:225], v[2:5]
	s_waitcnt vmcnt(8)
	s_barrier
	s_setprio 0
	s_add_i32 s70, s70, 2
	s_add_u32 s36, s36, 0x10000
	s_addc_u32 s37, s37, 0
	s_add_u32 s33, s33, 0x10000
	s_addc_u32 s35, s35, 0
	s_cmpk_gt_u32 s70, 0xa9
	s_cbranch_scc0 .LBB0_274
	s_and_b64 vcc, exec, s[16:17]
	s_cbranch_vccz .LBB0_277
	s_barrier

; #define PG8_STAGE(bufoff, gbase, voff) do { _Pragma("unroll") for (int _i = 0; _i < 2; ++_i) \
;         __builtin_amdgcn_global_load_lds((const unsigned*)((const char*)(gbase) + (voff)[_i]), (PG8_LAS unsigned*)(lds + (bufoff) + ldsw + _i * 8192), 16, 0, 0); } while (0)
; #define PG8_LDA(dst, b, h) do { _Pragma("unroll") for (int m = 0; m < 4; ++m) _Pragma("unroll") for (int k = 0; k < 2; ++k) dst[m][k] = *(const PG8_LAS bf16x8*)(lds + PG8_SA(b, h) + aoff + m * 2048 + k * 1024); } while (0)
; #define PG8_LDB(dst, b, h) do { _Pragma("unroll") for (int n = 0; n < 2; ++n) _Pragma("unroll") for (int k = 0; k < 2; ++k) dst[n][k] = *(const PG8_LAS bf16x8*)(lds + PG8_SB(b, h) + boff + n * 2048 + k * 1024); } while (0)
; #define PG8_WAIT_V(n) asm volatile("s_waitcnt vmcnt(" #n ")" ::: "memory")
; #define PG8_WAIT_L(n) asm volatile("s_waitcnt lgkmcnt(" #n ")" ::: "memory")
; #define PG8_BAR __builtin_amdgcn_s_barrier()
; #define PG8_SCHED __builtin_amdgcn_sched_barrier(0)
; template <class Epi, class Sched, bool ALIGN_EPI = false, bool SP2 = false, bool A_TILED = false>
; __device__ __forceinline__ void gemm_phase(PG8_LAS unsigned char* lds, const Gemm g, const Sched& S, const Epi& E) {
;     ...
;         const bool has_next = S.next(ui + 1, nxt);
;         const char* nA = has_next ? (const char*)g.A + (size_t)nxt.pm * tstepA : cA; const char* nB = has_next ? (const char*)g.Bt + (size_t)nxt.pn * tstepB : cB;
;         for (int t = 0; t < nt; t += 2) {
;             const bool last = (t == nt - 2);
;             const char* a1 = cA + (size_t)(t + 1) * kstepA;
;             const char* a2 = last ? nA : cA + (size_t)(t + 2) * kstepA; const char* b2 = last ? nB : cB + (size_t)(t + 2) * kstepB;
;             const char* a3 = a2 + kstepA; const char* b3 = b2 + kstepB;
;             if (last && has_next) S.a_ready(nxt);
;             if constexpr (SP2) {
;             PG8_LDB(B0, 0, 0); PG8_LDB(B1, 0, 1); PG8_SCHED; PG8_LDA(At, 0, 0); PG8_STAGE(PG8_SA(1, 1), a1 + hstepA, voffA);
;             PG8_WAIT_V(8); PG8_WAIT_L(0); PG8_BAR; PG8_MMA(0, 0, At, B0); PG8_MMA(0, 1, At, B1); PG8_BAR; PG8_SCHED;
;             PG8_LDA(At, 0, 1); PG8_STAGE(PG8_SB(0, 0), b2, voffB); PG8_STAGE(PG8_SB(0, 1), b2 + hstepB, voffB); PG8_STAGE(PG8_SA(0, 0), a2, voffA);
;             PG8_WAIT_V(8); PG8_WAIT_L(0); PG8_BAR; PG8_MMA(1, 0, At, B0); PG8_MMA(1, 1, At, B1); PG8_BAR; PG8_SCHED;
.LBB0_355:
	s_ashr_i32 s39, s38, 31
	s_lshl_b64 s[12:13], s[38:39], 21
	s_add_u32 s40, s78, s12
	s_addc_u32 s41, s79, s13
	s_and_b64 s[12:13], s[0:1], exec
	s_cselect_b32 s3, s41, s9
	s_cselect_b32 s5, s40, s8
	s_ashr_i32 s37, s36, 31
	s_lshl_b64 s[12:13], s[36:37], 21
	s_add_u32 s42, s71, s12
	s_addc_u32 s43, s76, s13
	s_and_b64 s[12:13], s[0:1], exec
	s_cselect_b32 s7, s43, s11
	s_cselect_b32 s33, s42, s10
	s_add_u32 s8, s8, 0xc000
	s_addc_u32 s9, s9, 0
	s_add_u32 s37, s10, 0x10000
	v_mov_b32_e32 v2, 0
	s_addc_u32 s39, s11, 0
	s_mov_b32 s58, -2
	s_waitcnt lgkmcnt(0)
	ds_read_b128 v[156:159], v170
	ds_read_b128 v[160:163], v170 offset:1024
	ds_read_b128 v[164:167], v170 offset:2048
	ds_read_b128 v[176:179], v170 offset:3072
	ds_read_b128 v[180:183], v171
	ds_read_b128 v[184:187], v171 offset:1024
	ds_read_b128 v[188:191], v171 offset:2048
	ds_read_b128 v[192:195], v171 offset:3072
	s_add_u32 s10, s8, 0x4000
	s_addc_u32 s11, s9, 0
	s_cmp_eq_u32 s58, 60
	s_cselect_b32 s44, s5, s10
	s_cselect_b32 s45, s3, s11
	s_cselect_b32 s12, s33, s37
	s_cselect_b32 s13, s7, s39
	s_add_u32 s10, s44, 0x8000
	s_addc_u32 s11, s45, 0
	s_add_i32 m0, s77, 0xc000
	ds_read_b128 v[196:199], v172
	ds_read_b128 v[200:203], v172 offset:1024
	ds_read_b128 v[204:207], v172 offset:2048
	ds_read_b128 v[208:211], v172 offset:3072
	ds_read_b128 v[212:215], v172 offset:4096
	ds_read_b128 v[216:219], v172 offset:5120
	ds_read_b128 v[220:223], v172 offset:6144
	ds_read_b128 v[224:227], v172 offset:7168
	global_load_lds_dwordx4 v148, s[8:9]
	s_add_i32 m0, s77, 0xe000
	s_nop 0
	global_load_lds_dwordx4 v150, s[8:9]
	s_and_b64 vcc, exec, s[30:31]
	s_cbranch_vccnz .Lmy_skipw_17
	s_waitcnt vmcnt(8)
.Lmy_skipw_17:
	s_waitcnt lgkmcnt(0)
	s_setprio 1
	s_barrier
	v_mfma_f32_16x16x32_bf16 v[126:129], v[156:159], v[196:199], 0
	v_mfma_f32_16x16x32_bf16 v[126:129], v[160:163], v[200:203], v[126:129]
	v_mfma_f32_16x16x32_bf16 v[122:125], v[164:167], v[196:199], 0
	v_mfma_f32_16x16x32_bf16 v[122:125], v[176:179], v[200:203], v[122:125]
	v_mfma_f32_16x16x32_bf16 v[118:121], v[180:183], v[196:199], 0
	v_mfma_f32_16x16x32_bf16 v[118:121], v[184:187], v[200:203], v[118:121]
	v_mfma_f32_16x16x32_bf16 v[114:117], v[188:191], v[196:199], 0
	v_mfma_f32_16x16x32_bf16 v[114:117], v[192:195], v[200:203], v[114:117]
	v_mfma_f32_16x16x32_bf16 v[110:113], v[156:159], v[204:207], 0
	v_mfma_f32_16x16x32_bf16 v[110:113], v[160:163], v[208:211], v[110:113]
	v_mfma_f32_16x16x32_bf16 v[106:109], v[164:167], v[204:207], 0
	v_mfma_f32_16x16x32_bf16 v[106:109], v[176:179], v[208:211], v[106:109]
	v_mfma_f32_16x16x32_bf16 v[102:105], v[180:183], v[204:207], 0
	v_mfma_f32_16x16x32_bf16 v[102:105], v[184:187], v[208:211], v[102:105]
	v_mfma_f32_16x16x32_bf16 v[98:101], v[188:191], v[204:207], 0
	v_mfma_f32_16x16x32_bf16 v[98:101], v[192:195], v[208:211], v[98:101]
	v_mfma_f32_16x16x32_bf16 v[94:97], v[156:159], v[212:215], 0
	v_mfma_f32_16x16x32_bf16 v[94:97], v[160:163], v[216:219], v[94:97]
	v_mfma_f32_16x16x32_bf16 v[90:93], v[164:167], v[212:215], 0
	v_mfma_f32_16x16x32_bf16 v[90:93], v[176:179], v[216:219], v[90:93]
	v_mfma_f32_16x16x32_bf16 v[86:89], v[180:183], v[212:215], 0
	v_mfma_f32_16x16x32_bf16 v[86:89], v[184:187], v[216:219], v[86:89]
	v_mfma_f32_16x16x32_bf16 v[82:85], v[188:191], v[212:215], 0
	v_mfma_f32_16x16x32_bf16 v[82:85], v[192:195], v[216:219], v[82:85]
	v_mfma_f32_16x16x32_bf16 v[78:81], v[156:159], v[220:223], 0
	v_mfma_f32_16x16x32_bf16 v[78:81], v[160:163], v[224:227], v[78:81]
	v_mfma_f32_16x16x32_bf16 v[74:77], v[164:167], v[220:223], 0
	v_mfma_f32_16x16x32_bf16 v[74:77], v[176:179], v[224:227], v[74:77]
	v_mfma_f32_16x16x32_bf16 v[70:73], v[180:183], v[220:223], 0
	v_mfma_f32_16x16x32_bf16 v[70:73], v[184:187], v[224:227], v[70:73]
	v_mfma_f32_16x16x32_bf16 v[66:69], v[188:191], v[220:223], 0
	v_mfma_f32_16x16x32_bf16 v[66:69], v[192:195], v[224:227], v[66:69]
	s_waitcnt vmcnt(8)
	s_barrier
	s_setprio 0
	s_add_i32 s59, s92, s69
	s_mov_b32 m0, s59
	ds_read_b128 v[196:199], v172 offset:16384
	ds_read_b128 v[200:203], v172 offset:17408
	ds_read_b128 v[204:207], v172 offset:18432
	ds_read_b128 v[208:211], v172 offset:19456
	ds_read_b128 v[212:215], v172 offset:20480
	ds_read_b128 v[216:219], v172 offset:21504
	ds_read_b128 v[220:223], v172 offset:22528
	ds_read_b128 v[224:227], v172 offset:23552
	global_load_lds_dwordx4 v134, s[12:13]
	s_add_i32 m0, s59, 0x2000
	s_add_u32 s62, s12, 0x4000
	s_addc_u32 s63, s13, 0
	s_add_i32 s59, s93, s69
	global_load_lds_dwordx4 v138, s[12:13]
	s_mov_b32 m0, s59
	s_nop 0
	global_load_lds_dwordx4 v134, s[62:63]
	s_add_i32 m0, s59, 0x2000
	s_nop 0
	global_load_lds_dwordx4 v138, s[62:63]
	s_mov_b32 m0, s77
	s_nop 0
	global_load_lds_dwordx4 v132, s[44:45]
	s_mov_b32 m0, s84
	s_nop 0
	global_load_lds_dwordx4 v136, s[44:45]
	s_and_b64 vcc, exec, s[30:31]
	s_cbranch_vccnz .Lmy_skipw_18
	s_waitcnt vmcnt(8)
; #define PG8_STAGE(bufoff, gbase, voff) do { _Pragma("unroll") for (int _i = 0; _i < 2; ++_i) \
;         __builtin_amdgcn_global_load_lds((const unsigned*)((const char*)(gbase) + (voff)[_i]), (PG8_LAS unsigned*)(lds + (bufoff) + ldsw + _i * 8192), 16, 0, 0); } while (0)
; #define PG8_LDA(dst, b, h) do { _Pragma("unroll") for (int m = 0; m < 4; ++m) _Pragma("unroll") for (int k = 0; k < 2; ++k) dst[m][k] = *(const PG8_LAS bf16x8*)(lds + PG8_SA(b, h) + aoff + m * 2048 + k * 1024); } while (0)
; #define PG8_LDB(dst, b, h) do { _Pragma("unroll") for (int n = 0; n < 2; ++n) _Pragma("unroll") for (int k = 0; k < 2; ++k) dst[n][k] = *(const PG8_LAS bf16x8*)(lds + PG8_SB(b, h) + boff + n * 2048 + k * 1024); } while (0)
; #define PG8_MMA(ai, bj, At, Bt) do { __builtin_amdgcn_s_setprio(1); _Pragma("unroll") for (int m = 0; m < 4; ++m) _Pragma("unroll") for (int n = 0; n < 2; ++n) _Pragma("unroll") for (int k = 0; k < 2; ++k) \
;         acc[ai][bj][m][n] = __builtin_amdgcn_mfma_f32_16x16x32_bf16(Bt[n][k], At[m][k], acc[ai][bj][m][n], 0, 0, 0); __builtin_amdgcn_s_setprio(0); } while (0)
; #define PG8_WAIT_V(n) asm volatile("s_waitcnt vmcnt(" #n ")" ::: "memory")
; #define PG8_WAIT_L(n) asm volatile("s_waitcnt lgkmcnt(" #n ")" ::: "memory")
; #define PG8_BAR __builtin_amdgcn_s_barrier()
; #define PG8_SCHED __builtin_amdgcn_sched_barrier(0)
; template <class Epi, class Sched, bool ALIGN_EPI = false, bool SP2 = false, bool A_TILED = false>
; __device__ __forceinline__ void gemm_phase(PG8_LAS unsigned char* lds, const Gemm g, const Sched& S, const Epi& E) {
;     ...
;             PG8_WAIT_V(8); PG8_WAIT_L(0); PG8_BAR; PG8_MMA(1, 0, At, B0); PG8_MMA(1, 1, At, B1); PG8_BAR; PG8_SCHED;
;             PG8_LDB(B0, 1, 0); PG8_LDB(B1, 1, 1); PG8_SCHED; PG8_LDA(At, 1, 0); PG8_STAGE(PG8_SA(0, 1), a2 + hstepA, voffA);
;             PG8_WAIT_V(8); PG8_WAIT_L(0); PG8_BAR; PG8_MMA(0, 0, At, B0); PG8_MMA(0, 1, At, B1); PG8_BAR; PG8_SCHED;
;             PG8_LDA(At, 1, 1); PG8_STAGE(PG8_SB(1, 0), b3, voffB); PG8_STAGE(PG8_SB(1, 1), b3 + hstepB, voffB); PG8_STAGE(PG8_SA(1, 0), a3, voffA);
.Lmy_skipw_18:
	s_waitcnt lgkmcnt(0)
	s_setprio 1
	s_barrier
	v_mfma_f32_16x16x32_bf16 v[62:65], v[156:159], v[196:199], 0
	v_mfma_f32_16x16x32_bf16 v[62:65], v[160:163], v[200:203], v[62:65]
	v_mfma_f32_16x16x32_bf16 v[58:61], v[164:167], v[196:199], 0
	v_mfma_f32_16x16x32_bf16 v[58:61], v[176:179], v[200:203], v[58:61]
	v_mfma_f32_16x16x32_bf16 v[54:57], v[180:183], v[196:199], 0
	v_mfma_f32_16x16x32_bf16 v[54:57], v[184:187], v[200:203], v[54:57]
	v_mfma_f32_16x16x32_bf16 v[50:53], v[188:191], v[196:199], 0
	v_mfma_f32_16x16x32_bf16 v[50:53], v[192:195], v[200:203], v[50:53]
	v_mfma_f32_16x16x32_bf16 v[46:49], v[156:159], v[204:207], 0
	v_mfma_f32_16x16x32_bf16 v[46:49], v[160:163], v[208:211], v[46:49]
	v_mfma_f32_16x16x32_bf16 v[42:45], v[164:167], v[204:207], 0
	v_mfma_f32_16x16x32_bf16 v[42:45], v[176:179], v[208:211], v[42:45]
	v_mfma_f32_16x16x32_bf16 v[38:41], v[180:183], v[204:207], 0
	v_mfma_f32_16x16x32_bf16 v[38:41], v[184:187], v[208:211], v[38:41]
	v_mfma_f32_16x16x32_bf16 v[34:37], v[188:191], v[204:207], 0
	v_mfma_f32_16x16x32_bf16 v[34:37], v[192:195], v[208:211], v[34:37]
	v_mfma_f32_16x16x32_bf16 v[30:33], v[156:159], v[212:215], 0
	v_mfma_f32_16x16x32_bf16 v[30:33], v[160:163], v[216:219], v[30:33]
	v_mfma_f32_16x16x32_bf16 v[26:29], v[164:167], v[212:215], 0
	v_mfma_f32_16x16x32_bf16 v[26:29], v[176:179], v[216:219], v[26:29]
	v_mfma_f32_16x16x32_bf16 v[22:25], v[180:183], v[212:215], 0
	v_mfma_f32_16x16x32_bf16 v[22:25], v[184:187], v[216:219], v[22:25]
	v_mfma_f32_16x16x32_bf16 v[18:21], v[188:191], v[212:215], 0
	v_mfma_f32_16x16x32_bf16 v[18:21], v[192:195], v[216:219], v[18:21]
	v_mfma_f32_16x16x32_bf16 v[14:17], v[156:159], v[220:223], 0
	v_mfma_f32_16x16x32_bf16 v[14:17], v[160:163], v[224:227], v[14:17]
	v_mfma_f32_16x16x32_bf16 v[10:13], v[164:167], v[220:223], 0
	v_mfma_f32_16x16x32_bf16 v[10:13], v[176:179], v[224:227], v[10:13]
	v_mfma_f32_16x16x32_bf16 v[6:9], v[180:183], v[220:223], 0
	v_mfma_f32_16x16x32_bf16 v[6:9], v[184:187], v[224:227], v[6:9]
	v_mfma_f32_16x16x32_bf16 v[2:5], v[188:191], v[220:223], 0
	v_mfma_f32_16x16x32_bf16 v[2:5], v[192:195], v[224:227], v[2:5]
	s_waitcnt vmcnt(8)
	s_barrier
	s_setprio 0
	s_add_i32 s59, 0, 0x18000
	s_add_i32 s62, 0, 0x1c000
	ds_read_b128 v[156:159], v170 offset:32768
	ds_read_b128 v[160:163], v170 offset:33792
	ds_read_b128 v[164:167], v170 offset:34816
	ds_read_b128 v[176:179], v170 offset:35840
	ds_read_b128 v[180:183], v170 offset:49152
	ds_read_b128 v[184:187], v170 offset:50176
	ds_read_b128 v[188:191], v170 offset:51200
	ds_read_b128 v[192:195], v170 offset:52224
	s_add_u32 s44, s44, 0x4000
	s_addc_u32 s45, s45, 0
	s_mov_b32 m0, s85
	ds_read_b128 v[196:199], v172 offset:32768
	ds_read_b128 v[200:203], v172 offset:33792
	ds_read_b128 v[204:207], v172 offset:34816
	ds_read_b128 v[208:211], v172 offset:35840
	ds_read_b128 v[212:215], v172 offset:36864
	ds_read_b128 v[216:219], v172 offset:37888
	ds_read_b128 v[220:223], v172 offset:38912
	ds_read_b128 v[224:227], v172 offset:39936
	global_load_lds_dwordx4 v132, s[44:45]
	s_mov_b32 m0, s86
	s_nop 0
	global_load_lds_dwordx4 v136, s[44:45]
	s_and_b64 vcc, exec, s[30:31]
	s_cbranch_vccnz .Lmy_skipw_19
	s_waitcnt vmcnt(8)
.Lmy_skipw_19:
	s_waitcnt lgkmcnt(0)
	s_setprio 1
	s_barrier
	v_mfma_f32_16x16x32_bf16 v[126:129], v[156:159], v[196:199], v[126:129]
	v_mfma_f32_16x16x32_bf16 v[126:129], v[160:163], v[200:203], v[126:129]
	v_mfma_f32_16x16x32_bf16 v[122:125], v[164:167], v[196:199], v[122:125]
	v_mfma_f32_16x16x32_bf16 v[122:125], v[176:179], v[200:203], v[122:125]
	v_mfma_f32_16x16x32_bf16 v[118:121], v[180:183], v[196:199], v[118:121]
	v_mfma_f32_16x16x32_bf16 v[118:121], v[184:187], v[200:203], v[118:121]
	v_mfma_f32_16x16x32_bf16 v[114:117], v[188:191], v[196:199], v[114:117]
	v_mfma_f32_16x16x32_bf16 v[114:117], v[192:195], v[200:203], v[114:117]
	v_mfma_f32_16x16x32_bf16 v[110:113], v[156:159], v[204:207], v[110:113]
	v_mfma_f32_16x16x32_bf16 v[110:113], v[160:163], v[208:211], v[110:113]
	v_mfma_f32_16x16x32_bf16 v[106:109], v[164:167], v[204:207], v[106:109]
	v_mfma_f32_16x16x32_bf16 v[106:109], v[176:179], v[208:211], v[106:109]
	v_mfma_f32_16x16x32_bf16 v[102:105], v[180:183], v[204:207], v[102:105]
	v_mfma_f32_16x16x32_bf16 v[102:105], v[184:187], v[208:211], v[102:105]
	v_mfma_f32_16x16x32_bf16 v[98:101], v[188:191], v[204:207], v[98:101]
	v_mfma_f32_16x16x32_bf16 v[98:101], v[192:195], v[208:211], v[98:101]
	v_mfma_f32_16x16x32_bf16 v[94:97], v[156:159], v[212:215], v[94:97]
	v_mfma_f32_16x16x32_bf16 v[94:97], v[160:163], v[216:219], v[94:97]
	v_mfma_f32_16x16x32_bf16 v[90:93], v[164:167], v[212:215], v[90:93]
	v_mfma_f32_16x16x32_bf16 v[90:93], v[176:179], v[216:219], v[90:93]
	v_mfma_f32_16x16x32_bf16 v[86:89], v[180:183], v[212:215], v[86:89]
	v_mfma_f32_16x16x32_bf16 v[86:89], v[184:187], v[216:219], v[86:89]
	v_mfma_f32_16x16x32_bf16 v[82:85], v[188:191], v[212:215], v[82:85]
	v_mfma_f32_16x16x32_bf16 v[82:85], v[192:195], v[216:219], v[82:85]
	v_mfma_f32_16x16x32_bf16 v[78:81], v[156:159], v[220:223], v[78:81]
	v_mfma_f32_16x16x32_bf16 v[78:81], v[160:163], v[224:227], v[78:81]
	v_mfma_f32_16x16x32_bf16 v[74:77], v[164:167], v[220:223], v[74:77]
	v_mfma_f32_16x16x32_bf16 v[74:77], v[176:179], v[224:227], v[74:77]
	v_mfma_f32_16x16x32_bf16 v[70:73], v[180:183], v[220:223], v[70:73]
	v_mfma_f32_16x16x32_bf16 v[70:73], v[184:187], v[224:227], v[70:73]
	v_mfma_f32_16x16x32_bf16 v[66:69], v[188:191], v[220:223], v[66:69]
	v_mfma_f32_16x16x32_bf16 v[66:69], v[192:195], v[224:227], v[66:69]
	s_waitcnt vmcnt(8)
	s_barrier
	s_setprio 0
	s_add_u32 s44, s12, 0x8000
	s_addc_u32 s45, s13, 0
	s_add_i32 s59, s59, s69
	s_mov_b32 m0, s59
	ds_read_b128 v[196:199], v172 offset:49152
	ds_read_b128 v[200:203], v172 offset:50176
	ds_read_b128 v[204:207], v172 offset:51200
	ds_read_b128 v[208:211], v172 offset:52224
	ds_read_b128 v[212:215], v172 offset:53248
	ds_read_b128 v[216:219], v172 offset:54272
	ds_read_b128 v[220:223], v172 offset:55296
	ds_read_b128 v[224:227], v172 offset:56320
	global_load_lds_dwordx4 v134, s[44:45]
	s_add_i32 m0, s59, 0x2000
	s_add_u32 s12, s12, 0xc000
	v_lshl_add_u64 v[130:131], s[44:45], 0, v[138:139]
	s_addc_u32 s13, s13, 0
	s_add_i32 s44, s62, s69
	global_load_lds_dwordx4 v[130:131], off
	s_mov_b32 m0, s44
	s_nop 0
	global_load_lds_dwordx4 v134, s[12:13]
	s_add_i32 m0, s44, 0x2000
	s_nop 0
	global_load_lds_dwordx4 v138, s[12:13]
	s_mov_b32 m0, s90
	s_nop 0
	global_load_lds_dwordx4 v132, s[10:11]
	s_mov_b32 m0, s91
	s_nop 0
	global_load_lds_dwordx4 v136, s[10:11]
	s_and_b64 vcc, exec, s[30:31]
	s_cbranch_vccnz .Lmy_skipw_20
	s_waitcnt vmcnt(8)
; #define PG8_STAGE(bufoff, gbase, voff) do { _Pragma("unroll") for (int _i = 0; _i < 2; ++_i) \
;         __builtin_amdgcn_global_load_lds((const unsigned*)((const char*)(gbase) + (voff)[_i]), (PG8_LAS unsigned*)(lds + (bufoff) + ldsw + _i * 8192), 16, 0, 0); } while (0)
; #define PG8_LDA(dst, b, h) do { _Pragma("unroll") for (int m = 0; m < 4; ++m) _Pragma("unroll") for (int k = 0; k < 2; ++k) dst[m][k] = *(const PG8_LAS bf16x8*)(lds + PG8_SA(b, h) + aoff + m * 2048 + k * 1024); } while (0)
; #define PG8_LDB(dst, b, h) do { _Pragma("unroll") for (int n = 0; n < 2; ++n) _Pragma("unroll") for (int k = 0; k < 2; ++k) dst[n][k] = *(const PG8_LAS bf16x8*)(lds + PG8_SB(b, h) + boff + n * 2048 + k * 1024); } while (0)
; #define PG8_MMA(ai, bj, At, Bt) do { __builtin_amdgcn_s_setprio(1); _Pragma("unroll") for (int m = 0; m < 4; ++m) _Pragma("unroll") for (int n = 0; n < 2; ++n) _Pragma("unroll") for (int k = 0; k < 2; ++k) \
;         acc[ai][bj][m][n] = __builtin_amdgcn_mfma_f32_16x16x32_bf16(Bt[n][k], At[m][k], acc[ai][bj][m][n], 0, 0, 0); __builtin_amdgcn_s_setprio(0); } while (0)
; #define PG8_WAIT_V(n) asm volatile("s_waitcnt vmcnt(" #n ")" ::: "memory")
; #define PG8_WAIT_L(n) asm volatile("s_waitcnt lgkmcnt(" #n ")" ::: "memory")
; #define PG8_BAR __builtin_amdgcn_s_barrier()
; #define PG8_SCHED __builtin_amdgcn_sched_barrier(0)
; template <class Epi, class Sched, bool ALIGN_EPI = false, bool SP2 = false, bool A_TILED = false>
; __device__ __forceinline__ void gemm_phase(PG8_LAS unsigned char* lds, const Gemm g, const Sched& S, const Epi& E) {
;     ...
;         for (int t = 0; t < nt; t += 2) {
;             const bool last = (t == nt - 2);
;             const char* a1 = cA + (size_t)(t + 1) * kstepA;
;             const char* a2 = last ? nA : cA + (size_t)(t + 2) * kstepA; const char* b2 = last ? nB : cB + (size_t)(t + 2) * kstepB;
;             const char* a3 = a2 + kstepA; const char* b3 = b2 + kstepB;
;             if (last && has_next) S.a_ready(nxt);
;             if constexpr (SP2) {
;             PG8_LDB(B0, 0, 0); PG8_LDB(B1, 0, 1); PG8_SCHED; PG8_LDA(At, 0, 0); PG8_STAGE(PG8_SA(1, 1), a1 + hstepA, voffA);
;             PG8_WAIT_V(8); PG8_WAIT_L(0); PG8_BAR; PG8_MMA(0, 0, At, B0); PG8_MMA(0, 1, At, B1); PG8_BAR; PG8_SCHED;
;     ...
;             PG8_WAIT_V(8); PG8_WAIT_L(0); PG8_BAR; PG8_MMA(1, 0, At, B0); PG8_MMA(1, 1, At, B1); PG8_BAR; PG8_SCHED;
.Lmy_skipw_20:
	s_waitcnt lgkmcnt(0)
	s_setprio 1
	s_barrier
	v_mfma_f32_16x16x32_bf16 v[62:65], v[156:159], v[196:199], v[62:65]
	v_mfma_f32_16x16x32_bf16 v[62:65], v[160:163], v[200:203], v[62:65]
	v_mfma_f32_16x16x32_bf16 v[58:61], v[164:167], v[196:199], v[58:61]
	v_mfma_f32_16x16x32_bf16 v[58:61], v[176:179], v[200:203], v[58:61]
	v_mfma_f32_16x16x32_bf16 v[54:57], v[180:183], v[196:199], v[54:57]
	v_mfma_f32_16x16x32_bf16 v[54:57], v[184:187], v[200:203], v[54:57]
	v_mfma_f32_16x16x32_bf16 v[50:53], v[188:191], v[196:199], v[50:53]
	v_mfma_f32_16x16x32_bf16 v[50:53], v[192:195], v[200:203], v[50:53]
	v_mfma_f32_16x16x32_bf16 v[46:49], v[156:159], v[204:207], v[46:49]
	v_mfma_f32_16x16x32_bf16 v[46:49], v[160:163], v[208:211], v[46:49]
	v_mfma_f32_16x16x32_bf16 v[42:45], v[164:167], v[204:207], v[42:45]
	v_mfma_f32_16x16x32_bf16 v[42:45], v[176:179], v[208:211], v[42:45]
	v_mfma_f32_16x16x32_bf16 v[38:41], v[180:183], v[204:207], v[38:41]
	v_mfma_f32_16x16x32_bf16 v[38:41], v[184:187], v[208:211], v[38:41]
	v_mfma_f32_16x16x32_bf16 v[34:37], v[188:191], v[204:207], v[34:37]
	v_mfma_f32_16x16x32_bf16 v[34:37], v[192:195], v[208:211], v[34:37]
	v_mfma_f32_16x16x32_bf16 v[30:33], v[156:159], v[212:215], v[30:33]
	v_mfma_f32_16x16x32_bf16 v[30:33], v[160:163], v[216:219], v[30:33]
	v_mfma_f32_16x16x32_bf16 v[26:29], v[164:167], v[212:215], v[26:29]
	v_mfma_f32_16x16x32_bf16 v[26:29], v[176:179], v[216:219], v[26:29]
	v_mfma_f32_16x16x32_bf16 v[22:25], v[180:183], v[212:215], v[22:25]
	v_mfma_f32_16x16x32_bf16 v[22:25], v[184:187], v[216:219], v[22:25]
	v_mfma_f32_16x16x32_bf16 v[18:21], v[188:191], v[212:215], v[18:21]
	v_mfma_f32_16x16x32_bf16 v[18:21], v[192:195], v[216:219], v[18:21]
	v_mfma_f32_16x16x32_bf16 v[14:17], v[156:159], v[220:223], v[14:17]
	v_mfma_f32_16x16x32_bf16 v[14:17], v[160:163], v[224:227], v[14:17]
	v_mfma_f32_16x16x32_bf16 v[10:13], v[164:167], v[220:223], v[10:13]
	v_mfma_f32_16x16x32_bf16 v[10:13], v[176:179], v[224:227], v[10:13]
	v_mfma_f32_16x16x32_bf16 v[6:9], v[180:183], v[220:223], v[6:9]
	v_mfma_f32_16x16x32_bf16 v[6:9], v[184:187], v[224:227], v[6:9]
	v_mfma_f32_16x16x32_bf16 v[2:5], v[188:191], v[220:223], v[2:5]
	v_mfma_f32_16x16x32_bf16 v[2:5], v[192:195], v[224:227], v[2:5]
	s_waitcnt vmcnt(8)
	s_barrier
	s_setprio 0
	s_add_i32 s58, s58, 2
	s_add_u32 s8, s8, 0x10000
	s_addc_u32 s9, s9, 0
	s_add_u32 s37, s37, 0x10000
	s_addc_u32 s39, s39, 0
.LBB0_356:
	ds_read_b128 v[156:159], v170
	ds_read_b128 v[160:163], v170 offset:1024
	ds_read_b128 v[164:167], v170 offset:2048
	ds_read_b128 v[176:179], v170 offset:3072
	ds_read_b128 v[180:183], v171
	ds_read_b128 v[184:187], v171 offset:1024
	ds_read_b128 v[188:191], v171 offset:2048
	ds_read_b128 v[192:195], v171 offset:3072
	s_add_u32 s10, s8, 0x4000
	s_addc_u32 s11, s9, 0
	s_cmp_eq_u32 s58, 60
	s_cselect_b32 s44, s5, s10
	s_cselect_b32 s45, s3, s11
	s_cselect_b32 s12, s33, s37
	s_cselect_b32 s13, s7, s39
	s_add_u32 s10, s44, 0x8000
	s_addc_u32 s11, s45, 0
	s_add_i32 m0, s77, 0xc000
	ds_read_b128 v[196:199], v172
	ds_read_b128 v[200:203], v172 offset:1024
	ds_read_b128 v[204:207], v172 offset:2048
	ds_read_b128 v[208:211], v172 offset:3072
	ds_read_b128 v[212:215], v172 offset:4096
	ds_read_b128 v[216:219], v172 offset:5120
	ds_read_b128 v[220:223], v172 offset:6144
	ds_read_b128 v[224:227], v172 offset:7168
	global_load_lds_dwordx4 v148, s[8:9]
	s_add_i32 m0, s77, 0xe000
	s_nop 0
	global_load_lds_dwordx4 v150, s[8:9]
	s_and_b64 vcc, exec, s[30:31]
	s_cbranch_vccnz .Lmy_skipw_21
	s_waitcnt vmcnt(8)
; #define PG8_STAGE(bufoff, gbase, voff) do { _Pragma("unroll") for (int _i = 0; _i < 2; ++_i) \
;         __builtin_amdgcn_global_load_lds((const unsigned*)((const char*)(gbase) + (voff)[_i]), (PG8_LAS unsigned*)(lds + (bufoff) + ldsw + _i * 8192), 16, 0, 0); } while (0)
; #define PG8_LDA(dst, b, h) do { _Pragma("unroll") for (int m = 0; m < 4; ++m) _Pragma("unroll") for (int k = 0; k < 2; ++k) dst[m][k] = *(const PG8_LAS bf16x8*)(lds + PG8_SA(b, h) + aoff + m * 2048 + k * 1024); } while (0)
; #define PG8_LDB(dst, b, h) do { _Pragma("unroll") for (int n = 0; n < 2; ++n) _Pragma("unroll") for (int k = 0; k < 2; ++k) dst[n][k] = *(const PG8_LAS bf16x8*)(lds + PG8_SB(b, h) + boff + n * 2048 + k * 1024); } while (0)
; #define PG8_MMA(ai, bj, At, Bt) do { __builtin_amdgcn_s_setprio(1); _Pragma("unroll") for (int m = 0; m < 4; ++m) _Pragma("unroll") for (int n = 0; n < 2; ++n) _Pragma("unroll") for (int k = 0; k < 2; ++k) \
;         acc[ai][bj][m][n] = __builtin_amdgcn_mfma_f32_16x16x32_bf16(Bt[n][k], At[m][k], acc[ai][bj][m][n], 0, 0, 0); __builtin_amdgcn_s_setprio(0); } while (0)
; #define PG8_WAIT_V(n) asm volatile("s_waitcnt vmcnt(" #n ")" ::: "memory")
; #define PG8_WAIT_L(n) asm volatile("s_waitcnt lgkmcnt(" #n ")" ::: "memory")
; #define PG8_BAR __builtin_amdgcn_s_barrier()
; #define PG8_SCHED __builtin_amdgcn_sched_barrier(0)
; template <class Epi, class Sched, bool ALIGN_EPI = false, bool SP2 = false, bool A_TILED = false>
; __device__ __forceinline__ void gemm_phase(PG8_LAS unsigned char* lds, const Gemm g, const Sched& S, const Epi& E) {
;     ...
;             PG8_WAIT_V(8); PG8_WAIT_L(0); PG8_BAR; PG8_MMA(0, 0, At, B0); PG8_MMA(0, 1, At, B1); PG8_BAR; PG8_SCHED;
;             PG8_LDA(At, 0, 1); PG8_STAGE(PG8_SB(0, 0), b2, voffB); PG8_STAGE(PG8_SB(0, 1), b2 + hstepB, voffB); PG8_STAGE(PG8_SA(0, 0), a2, voffA);
;             PG8_WAIT_V(8); PG8_WAIT_L(0); PG8_BAR; PG8_MMA(1, 0, At, B0); PG8_MMA(1, 1, At, B1); PG8_BAR; PG8_SCHED;
;             PG8_LDB(B0, 1, 0); PG8_LDB(B1, 1, 1); PG8_SCHED; PG8_LDA(At, 1, 0); PG8_STAGE(PG8_SA(0, 1), a2 + hstepA, voffA);
;             PG8_WAIT_V(8); PG8_WAIT_L(0); PG8_BAR; PG8_MMA(0, 0, At, B0); PG8_MMA(0, 1, At, B1); PG8_BAR; PG8_SCHED;
;             PG8_LDA(At, 1, 1); PG8_STAGE(PG8_SB(1, 0), b3, voffB); PG8_STAGE(PG8_SB(1, 1), b3 + hstepB, voffB); PG8_STAGE(PG8_SA(1, 0), a3, voffA);
.Lmy_skipw_21:
	s_waitcnt lgkmcnt(0)
	s_setprio 1
	s_barrier
	v_mfma_f32_16x16x32_bf16 v[126:129], v[156:159], v[196:199], v[126:129]
	v_mfma_f32_16x16x32_bf16 v[126:129], v[160:163], v[200:203], v[126:129]
	v_mfma_f32_16x16x32_bf16 v[122:125], v[164:167], v[196:199], v[122:125]
	v_mfma_f32_16x16x32_bf16 v[122:125], v[176:179], v[200:203], v[122:125]
	v_mfma_f32_16x16x32_bf16 v[118:121], v[180:183], v[196:199], v[118:121]
	v_mfma_f32_16x16x32_bf16 v[118:121], v[184:187], v[200:203], v[118:121]
	v_mfma_f32_16x16x32_bf16 v[114:117], v[188:191], v[196:199], v[114:117]
	v_mfma_f32_16x16x32_bf16 v[114:117], v[192:195], v[200:203], v[114:117]
	v_mfma_f32_16x16x32_bf16 v[110:113], v[156:159], v[204:207], v[110:113]
	v_mfma_f32_16x16x32_bf16 v[110:113], v[160:163], v[208:211], v[110:113]
	v_mfma_f32_16x16x32_bf16 v[106:109], v[164:167], v[204:207], v[106:109]
	v_mfma_f32_16x16x32_bf16 v[106:109], v[176:179], v[208:211], v[106:109]
	v_mfma_f32_16x16x32_bf16 v[102:105], v[180:183], v[204:207], v[102:105]
	v_mfma_f32_16x16x32_bf16 v[102:105], v[184:187], v[208:211], v[102:105]
	v_mfma_f32_16x16x32_bf16 v[98:101], v[188:191], v[204:207], v[98:101]
	v_mfma_f32_16x16x32_bf16 v[98:101], v[192:195], v[208:211], v[98:101]
	v_mfma_f32_16x16x32_bf16 v[94:97], v[156:159], v[212:215], v[94:97]
	v_mfma_f32_16x16x32_bf16 v[94:97], v[160:163], v[216:219], v[94:97]
	v_mfma_f32_16x16x32_bf16 v[90:93], v[164:167], v[212:215], v[90:93]
	v_mfma_f32_16x16x32_bf16 v[90:93], v[176:179], v[216:219], v[90:93]
	v_mfma_f32_16x16x32_bf16 v[86:89], v[180:183], v[212:215], v[86:89]
	v_mfma_f32_16x16x32_bf16 v[86:89], v[184:187], v[216:219], v[86:89]
	v_mfma_f32_16x16x32_bf16 v[82:85], v[188:191], v[212:215], v[82:85]
	v_mfma_f32_16x16x32_bf16 v[82:85], v[192:195], v[216:219], v[82:85]
	v_mfma_f32_16x16x32_bf16 v[78:81], v[156:159], v[220:223], v[78:81]
	v_mfma_f32_16x16x32_bf16 v[78:81], v[160:163], v[224:227], v[78:81]
	v_mfma_f32_16x16x32_bf16 v[74:77], v[164:167], v[220:223], v[74:77]
	v_mfma_f32_16x16x32_bf16 v[74:77], v[176:179], v[224:227], v[74:77]
	v_mfma_f32_16x16x32_bf16 v[70:73], v[180:183], v[220:223], v[70:73]
	v_mfma_f32_16x16x32_bf16 v[70:73], v[184:187], v[224:227], v[70:73]
	v_mfma_f32_16x16x32_bf16 v[66:69], v[188:191], v[220:223], v[66:69]
	v_mfma_f32_16x16x32_bf16 v[66:69], v[192:195], v[224:227], v[66:69]
	s_waitcnt vmcnt(8)
	s_barrier
	s_setprio 0
	s_add_i32 s59, s92, s69
	s_mov_b32 m0, s59
	ds_read_b128 v[196:199], v172 offset:16384
	ds_read_b128 v[200:203], v172 offset:17408
	ds_read_b128 v[204:207], v172 offset:18432
	ds_read_b128 v[208:211], v172 offset:19456
	ds_read_b128 v[212:215], v172 offset:20480
	ds_read_b128 v[216:219], v172 offset:21504
	ds_read_b128 v[220:223], v172 offset:22528
	ds_read_b128 v[224:227], v172 offset:23552
	global_load_lds_dwordx4 v134, s[12:13]
	s_add_i32 m0, s59, 0x2000
	s_add_u32 s62, s12, 0x4000
	s_addc_u32 s63, s13, 0
	s_add_i32 s59, s93, s69
	global_load_lds_dwordx4 v138, s[12:13]
	s_mov_b32 m0, s59
	s_nop 0
	global_load_lds_dwordx4 v134, s[62:63]
	s_add_i32 m0, s59, 0x2000
	s_nop 0
	global_load_lds_dwordx4 v138, s[62:63]
	s_mov_b32 m0, s77
	s_nop 0
	global_load_lds_dwordx4 v132, s[44:45]
	s_mov_b32 m0, s84
	s_nop 0
	global_load_lds_dwordx4 v136, s[44:45]
	s_and_b64 vcc, exec, s[30:31]
	s_cbranch_vccnz .Lmy_skipw_22
	s_waitcnt vmcnt(8)
.Lmy_skipw_22:
	s_waitcnt lgkmcnt(0)
	s_setprio 1
	s_barrier
	v_mfma_f32_16x16x32_bf16 v[62:65], v[156:159], v[196:199], v[62:65]
	v_mfma_f32_16x16x32_bf16 v[62:65], v[160:163], v[200:203], v[62:65]
	v_mfma_f32_16x16x32_bf16 v[58:61], v[164:167], v[196:199], v[58:61]
	v_mfma_f32_16x16x32_bf16 v[58:61], v[176:179], v[200:203], v[58:61]
	v_mfma_f32_16x16x32_bf16 v[54:57], v[180:183], v[196:199], v[54:57]
	v_mfma_f32_16x16x32_bf16 v[54:57], v[184:187], v[200:203], v[54:57]
	v_mfma_f32_16x16x32_bf16 v[50:53], v[188:191], v[196:199], v[50:53]
	v_mfma_f32_16x16x32_bf16 v[50:53], v[192:195], v[200:203], v[50:53]
	v_mfma_f32_16x16x32_bf16 v[46:49], v[156:159], v[204:207], v[46:49]
	v_mfma_f32_16x16x32_bf16 v[46:49], v[160:163], v[208:211], v[46:49]
	v_mfma_f32_16x16x32_bf16 v[42:45], v[164:167], v[204:207], v[42:45]
	v_mfma_f32_16x16x32_bf16 v[42:45], v[176:179], v[208:211], v[42:45]
	v_mfma_f32_16x16x32_bf16 v[38:41], v[180:183], v[204:207], v[38:41]
	v_mfma_f32_16x16x32_bf16 v[38:41], v[184:187], v[208:211], v[38:41]
	v_mfma_f32_16x16x32_bf16 v[34:37], v[188:191], v[204:207], v[34:37]
	v_mfma_f32_16x16x32_bf16 v[34:37], v[192:195], v[208:211], v[34:37]
	v_mfma_f32_16x16x32_bf16 v[30:33], v[156:159], v[212:215], v[30:33]
	v_mfma_f32_16x16x32_bf16 v[30:33], v[160:163], v[216:219], v[30:33]
	v_mfma_f32_16x16x32_bf16 v[26:29], v[164:167], v[212:215], v[26:29]
	v_mfma_f32_16x16x32_bf16 v[26:29], v[176:179], v[216:219], v[26:29]
	v_mfma_f32_16x16x32_bf16 v[22:25], v[180:183], v[212:215], v[22:25]
	v_mfma_f32_16x16x32_bf16 v[22:25], v[184:187], v[216:219], v[22:25]
	v_mfma_f32_16x16x32_bf16 v[18:21], v[188:191], v[212:215], v[18:21]
	v_mfma_f32_16x16x32_bf16 v[18:21], v[192:195], v[216:219], v[18:21]
	v_mfma_f32_16x16x32_bf16 v[14:17], v[156:159], v[220:223], v[14:17]
	v_mfma_f32_16x16x32_bf16 v[14:17], v[160:163], v[224:227], v[14:17]
	v_mfma_f32_16x16x32_bf16 v[10:13], v[164:167], v[220:223], v[10:13]
	v_mfma_f32_16x16x32_bf16 v[10:13], v[176:179], v[224:227], v[10:13]
	v_mfma_f32_16x16x32_bf16 v[6:9], v[180:183], v[220:223], v[6:9]
	v_mfma_f32_16x16x32_bf16 v[6:9], v[184:187], v[224:227], v[6:9]
	v_mfma_f32_16x16x32_bf16 v[2:5], v[188:191], v[220:223], v[2:5]
	v_mfma_f32_16x16x32_bf16 v[2:5], v[192:195], v[224:227], v[2:5]
	s_waitcnt vmcnt(8)
	s_barrier
	s_setprio 0
	s_add_i32 s59, 0, 0x18000
	s_add_i32 s62, 0, 0x1c000
	ds_read_b128 v[156:159], v170 offset:32768
	ds_read_b128 v[160:163], v170 offset:33792
	ds_read_b128 v[164:167], v170 offset:34816
	ds_read_b128 v[176:179], v170 offset:35840
	ds_read_b128 v[180:183], v170 offset:49152
	ds_read_b128 v[184:187], v170 offset:50176
	ds_read_b128 v[188:191], v170 offset:51200
	ds_read_b128 v[192:195], v170 offset:52224
	s_add_u32 s44, s44, 0x4000
	s_addc_u32 s45, s45, 0
	s_mov_b32 m0, s85
	ds_read_b128 v[196:199], v172 offset:32768
	ds_read_b128 v[200:203], v172 offset:33792
	ds_read_b128 v[204:207], v172 offset:34816
	ds_read_b128 v[208:211], v172 offset:35840
	ds_read_b128 v[212:215], v172 offset:36864
	ds_read_b128 v[216:219], v172 offset:37888
	ds_read_b128 v[220:223], v172 offset:38912
	ds_read_b128 v[224:227], v172 offset:39936
	global_load_lds_dwordx4 v132, s[44:45]
	s_mov_b32 m0, s86
	s_nop 0
	global_load_lds_dwordx4 v136, s[44:45]
	s_and_b64 vcc, exec, s[30:31]
	s_cbranch_vccnz .Lmy_skipw_23
	s_waitcnt vmcnt(8)

; #define PG8_STAGE(bufoff, gbase, voff) do { _Pragma("unroll") for (int _i = 0; _i < 2; ++_i) \
;         __builtin_amdgcn_global_load_lds((const unsigned*)((const char*)(gbase) + (voff)[_i]), (PG8_LAS unsigned*)(lds + (bufoff) + ldsw + _i * 8192), 16, 0, 0); } while (0)
; #define PG8_LDA(dst, b, h) do { _Pragma("unroll") for (int m = 0; m < 4; ++m) _Pragma("unroll") for (int k = 0; k < 2; ++k) dst[m][k] = *(const PG8_LAS bf16x8*)(lds + PG8_SA(b, h) + aoff + m * 2048 + k * 1024); } while (0)
; #define PG8_MMA(ai, bj, At, Bt) do { __builtin_amdgcn_s_setprio(1); _Pragma("unroll") for (int m = 0; m < 4; ++m) _Pragma("unroll") for (int n = 0; n < 2; ++n) _Pragma("unroll") for (int k = 0; k < 2; ++k) \
;         acc[ai][bj][m][n] = __builtin_amdgcn_mfma_f32_16x16x32_bf16(Bt[n][k], At[m][k], acc[ai][bj][m][n], 0, 0, 0); __builtin_amdgcn_s_setprio(0); } while (0)
; #define PG8_WAIT_V(n) asm volatile("s_waitcnt vmcnt(" #n ")" ::: "memory")
; #define PG8_WAIT_L(n) asm volatile("s_waitcnt lgkmcnt(" #n ")" ::: "memory")
; #define PG8_BAR __builtin_amdgcn_s_barrier()
; #define PG8_SCHED __builtin_amdgcn_sched_barrier(0)
; template <class Epi, class Sched, bool ALIGN_EPI = false, bool SP2 = false, bool A_TILED = false>
; __device__ __forceinline__ void gemm_phase(PG8_LAS unsigned char* lds, const Gemm g, const Sched& S, const Epi& E) {
;     ...
;             PG8_LDA(At, 1, 1); PG8_STAGE(PG8_SB(1, 0), b3, voffB); PG8_STAGE(PG8_SB(1, 1), b3 + hstepB, voffB); PG8_STAGE(PG8_SA(1, 0), a3, voffA);
;             PG8_WAIT_V(8); PG8_WAIT_L(0); PG8_BAR; PG8_MMA(1, 0, At, B0); PG8_MMA(1, 1, At, B1); PG8_BAR; PG8_SCHED;
.Lmy_skipw_24:
	s_waitcnt lgkmcnt(0)
	s_setprio 1
	s_barrier
	v_mfma_f32_16x16x32_bf16 v[62:65], v[156:159], v[196:199], v[62:65]
	v_mfma_f32_16x16x32_bf16 v[62:65], v[160:163], v[200:203], v[62:65]
	v_mfma_f32_16x16x32_bf16 v[58:61], v[164:167], v[196:199], v[58:61]
	v_mfma_f32_16x16x32_bf16 v[58:61], v[176:179], v[200:203], v[58:61]
	v_mfma_f32_16x16x32_bf16 v[54:57], v[180:183], v[196:199], v[54:57]
	v_mfma_f32_16x16x32_bf16 v[54:57], v[184:187], v[200:203], v[54:57]
	v_mfma_f32_16x16x32_bf16 v[50:53], v[188:191], v[196:199], v[50:53]
	v_mfma_f32_16x16x32_bf16 v[50:53], v[192:195], v[200:203], v[50:53]
	v_mfma_f32_16x16x32_bf16 v[46:49], v[156:159], v[204:207], v[46:49]
	v_mfma_f32_16x16x32_bf16 v[46:49], v[160:163], v[208:211], v[46:49]
	v_mfma_f32_16x16x32_bf16 v[42:45], v[164:167], v[204:207], v[42:45]
	v_mfma_f32_16x16x32_bf16 v[42:45], v[176:179], v[208:211], v[42:45]
	v_mfma_f32_16x16x32_bf16 v[38:41], v[180:183], v[204:207], v[38:41]
	v_mfma_f32_16x16x32_bf16 v[38:41], v[184:187], v[208:211], v[38:41]
	v_mfma_f32_16x16x32_bf16 v[34:37], v[188:191], v[204:207], v[34:37]
	v_mfma_f32_16x16x32_bf16 v[34:37], v[192:195], v[208:211], v[34:37]
	v_mfma_f32_16x16x32_bf16 v[30:33], v[156:159], v[212:215], v[30:33]
	v_mfma_f32_16x16x32_bf16 v[30:33], v[160:163], v[216:219], v[30:33]
	v_mfma_f32_16x16x32_bf16 v[26:29], v[164:167], v[212:215], v[26:29]
	v_mfma_f32_16x16x32_bf16 v[26:29], v[176:179], v[216:219], v[26:29]
	v_mfma_f32_16x16x32_bf16 v[22:25], v[180:183], v[212:215], v[22:25]
	v_mfma_f32_16x16x32_bf16 v[22:25], v[184:187], v[216:219], v[22:25]
	v_mfma_f32_16x16x32_bf16 v[18:21], v[188:191], v[212:215], v[18:21]
	v_mfma_f32_16x16x32_bf16 v[18:21], v[192:195], v[216:219], v[18:21]
	v_mfma_f32_16x16x32_bf16 v[14:17], v[156:159], v[220:223], v[14:17]
	v_mfma_f32_16x16x32_bf16 v[14:17], v[160:163], v[224:227], v[14:17]
	v_mfma_f32_16x16x32_bf16 v[10:13], v[164:167], v[220:223], v[10:13]
	v_mfma_f32_16x16x32_bf16 v[10:13], v[176:179], v[224:227], v[10:13]
	v_mfma_f32_16x16x32_bf16 v[6:9], v[180:183], v[220:223], v[6:9]
	v_mfma_f32_16x16x32_bf16 v[6:9], v[184:187], v[224:227], v[6:9]
	v_mfma_f32_16x16x32_bf16 v[2:5], v[188:191], v[220:223], v[2:5]
	v_mfma_f32_16x16x32_bf16 v[2:5], v[192:195], v[224:227], v[2:5]
	s_waitcnt vmcnt(8)
	s_barrier
	s_setprio 0
	s_add_i32 s58, s58, 2
	s_add_u32 s8, s8, 0x10000
	s_addc_u32 s9, s9, 0
	s_add_u32 s37, s37, 0x10000
	s_addc_u32 s39, s39, 0
	s_cmp_gt_u32 s58, 61
	s_cbranch_scc0 .LBB0_356
	s_and_b64 vcc, exec, s[30:31]
	s_cbranch_vccz .LBB0_359
	s_barrier

; #define PG8_STAGE(bufoff, gbase, voff) do { _Pragma("unroll") for (int _i = 0; _i < 2; ++_i) \
;         __builtin_amdgcn_global_load_lds((const unsigned*)((const char*)(gbase) + (voff)[_i]), (PG8_LAS unsigned*)(lds + (bufoff) + ldsw + _i * 8192), 16, 0, 0); } while (0)
; #define PG8_LDA(dst, b, h) do { _Pragma("unroll") for (int m = 0; m < 4; ++m) _Pragma("unroll") for (int k = 0; k < 2; ++k) dst[m][k] = *(const PG8_LAS bf16x8*)(lds + PG8_SA(b, h) + aoff + m * 2048 + k * 1024); } while (0)
; #define PG8_LDB(dst, b, h) do { _Pragma("unroll") for (int n = 0; n < 2; ++n) _Pragma("unroll") for (int k = 0; k < 2; ++k) dst[n][k] = *(const PG8_LAS bf16x8*)(lds + PG8_SB(b, h) + boff + n * 2048 + k * 1024); } while (0)
; #define PG8_WAIT_V(n) asm volatile("s_waitcnt vmcnt(" #n ")" ::: "memory")
; #define PG8_WAIT_L(n) asm volatile("s_waitcnt lgkmcnt(" #n ")" ::: "memory")
; #define PG8_BAR __builtin_amdgcn_s_barrier()
; #define PG8_SCHED __builtin_amdgcn_sched_barrier(0)
; template <class Epi, class Sched, bool ALIGN_EPI = false, bool SP2 = false, bool A_TILED = false>
; __device__ __forceinline__ void gemm_phase(PG8_LAS unsigned char* lds, const Gemm g, const Sched& S, const Epi& E) {
;     ...
;         const bool has_next = S.next(ui + 1, nxt);
;         const char* nA = has_next ? (const char*)g.A + (size_t)nxt.pm * tstepA : cA; const char* nB = has_next ? (const char*)g.Bt + (size_t)nxt.pn * tstepB : cB;
;         for (int t = 0; t < nt; t += 2) {
;             const bool last = (t == nt - 2);
;             const char* a1 = cA + (size_t)(t + 1) * kstepA;
;             const char* a2 = last ? nA : cA + (size_t)(t + 2) * kstepA; const char* b2 = last ? nB : cB + (size_t)(t + 2) * kstepB;
;             const char* a3 = a2 + kstepA; const char* b3 = b2 + kstepB;
;             if (last && has_next) S.a_ready(nxt);
;             if constexpr (SP2) {
;             PG8_LDB(B0, 0, 0); PG8_LDB(B1, 0, 1); PG8_SCHED; PG8_LDA(At, 0, 0); PG8_STAGE(PG8_SA(1, 1), a1 + hstepA, voffA);
;             PG8_WAIT_V(8); PG8_WAIT_L(0); PG8_BAR; PG8_MMA(0, 0, At, B0); PG8_MMA(0, 1, At, B1); PG8_BAR; PG8_SCHED;
;             PG8_LDA(At, 0, 1); PG8_STAGE(PG8_SB(0, 0), b2, voffB); PG8_STAGE(PG8_SB(0, 1), b2 + hstepB, voffB); PG8_STAGE(PG8_SA(0, 0), a2, voffA);
;             PG8_WAIT_V(8); PG8_WAIT_L(0); PG8_BAR; PG8_MMA(1, 0, At, B0); PG8_MMA(1, 1, At, B1); PG8_BAR; PG8_SCHED;
.LBB0_1171:
	s_ashr_i32 s17, s16, 31
	s_lshl_b64 s[18:19], s[16:17], 21
	s_add_u32 s18, s3, s18
	s_addc_u32 s19, s30, s19
	s_and_b64 s[20:21], s[0:1], exec
	s_cselect_b32 s17, s19, s23
	s_cselect_b32 s33, s18, s22
	s_ashr_i32 s15, s14, 31
	s_lshl_b64 s[20:21], s[14:15], 21
	s_add_u32 s20, s31, s20
	s_addc_u32 s21, s34, s21
	s_and_b64 s[26:27], s[0:1], exec
	s_cselect_b32 s15, s21, s25
	s_cselect_b32 s58, s20, s24
	s_add_u32 s22, s22, 0xc000
	s_addc_u32 s23, s23, 0
	s_add_u32 s59, s24, 0x10000
	v_mov_b32_e32 v2, 0
	s_addc_u32 s60, s25, 0
	s_mov_b32 s61, -2
	ds_read_b128 v[152:155], v141
	ds_read_b128 v[160:163], v141 offset:1024
	ds_read_b128 v[164:167], v141 offset:2048
	ds_read_b128 v[168:171], v141 offset:3072
	ds_read_b128 v[172:175], v156
	ds_read_b128 v[176:179], v156 offset:1024
	ds_read_b128 v[180:183], v156 offset:2048
	ds_read_b128 v[184:187], v156 offset:3072
	s_add_u32 s24, s22, 0x4000
	s_addc_u32 s25, s23, 0
	s_cmp_eq_u32 s61, 60
	s_cselect_b32 s28, s33, s24
	s_cselect_b32 s29, s17, s25
	s_cselect_b32 s26, s58, s59
	s_cselect_b32 s27, s15, s60
	s_add_u32 s24, s28, 0x8000
	s_addc_u32 s25, s29, 0
	s_add_i32 m0, s38, 0xc000
	ds_read_b128 v[188:191], v157
	ds_read_b128 v[192:195], v157 offset:1024
	ds_read_b128 v[196:199], v157 offset:2048
	ds_read_b128 v[200:203], v157 offset:3072
	ds_read_b128 v[204:207], v157 offset:4096
	ds_read_b128 v[208:211], v157 offset:5120
	ds_read_b128 v[212:215], v157 offset:6144
	ds_read_b128 v[216:219], v157 offset:7168
	global_load_lds_dwordx4 v144, s[22:23]
	s_add_i32 m0, s38, 0xe000
	s_nop 0
	global_load_lds_dwordx4 v146, s[22:23]
	s_and_b64 vcc, exec, s[12:13]
	s_cbranch_vccnz .Lmy_skipw_25
	s_waitcnt vmcnt(8)
.Lmy_skipw_25:
	s_waitcnt lgkmcnt(0)
	s_barrier
	s_setprio 1
	s_waitcnt lgkmcnt(0)
	v_mfma_f32_16x16x32_bf16 v[126:129], v[152:155], v[188:191], 0
	v_mfma_f32_16x16x32_bf16 v[122:125], v[164:167], v[188:191], 0
	v_mfma_f32_16x16x32_bf16 v[110:113], v[152:155], v[196:199], 0
	v_mfma_f32_16x16x32_bf16 v[106:109], v[164:167], v[196:199], 0
	v_mfma_f32_16x16x32_bf16 v[94:97], v[152:155], v[204:207], 0
	v_mfma_f32_16x16x32_bf16 v[90:93], v[164:167], v[204:207], 0
	v_mfma_f32_16x16x32_bf16 v[78:81], v[152:155], v[212:215], 0
	v_mfma_f32_16x16x32_bf16 v[74:77], v[164:167], v[212:215], 0
	v_mfma_f32_16x16x32_bf16 v[126:129], v[160:163], v[192:195], v[126:129]
	v_mfma_f32_16x16x32_bf16 v[122:125], v[168:171], v[192:195], v[122:125]
	v_mfma_f32_16x16x32_bf16 v[110:113], v[160:163], v[200:203], v[110:113]
	v_mfma_f32_16x16x32_bf16 v[106:109], v[168:171], v[200:203], v[106:109]
	v_mfma_f32_16x16x32_bf16 v[94:97], v[160:163], v[208:211], v[94:97]
	v_mfma_f32_16x16x32_bf16 v[90:93], v[168:171], v[208:211], v[90:93]
	v_mfma_f32_16x16x32_bf16 v[78:81], v[160:163], v[216:219], v[78:81]
	v_mfma_f32_16x16x32_bf16 v[74:77], v[168:171], v[216:219], v[74:77]
	s_setprio 0
	s_setprio 1
	v_mfma_f32_16x16x32_bf16 v[118:121], v[172:175], v[188:191], 0
	v_mfma_f32_16x16x32_bf16 v[114:117], v[180:183], v[188:191], 0
	v_mfma_f32_16x16x32_bf16 v[102:105], v[172:175], v[196:199], 0
	v_mfma_f32_16x16x32_bf16 v[98:101], v[180:183], v[196:199], 0
	v_mfma_f32_16x16x32_bf16 v[86:89], v[172:175], v[204:207], 0
	v_mfma_f32_16x16x32_bf16 v[82:85], v[180:183], v[204:207], 0
	v_mfma_f32_16x16x32_bf16 v[70:73], v[172:175], v[212:215], 0
	v_mfma_f32_16x16x32_bf16 v[66:69], v[180:183], v[212:215], 0
	v_mfma_f32_16x16x32_bf16 v[118:121], v[176:179], v[192:195], v[118:121]
	v_mfma_f32_16x16x32_bf16 v[114:117], v[184:187], v[192:195], v[114:117]
	v_mfma_f32_16x16x32_bf16 v[102:105], v[176:179], v[200:203], v[102:105]
	v_mfma_f32_16x16x32_bf16 v[98:101], v[184:187], v[200:203], v[98:101]
	v_mfma_f32_16x16x32_bf16 v[86:89], v[176:179], v[208:211], v[86:89]
	v_mfma_f32_16x16x32_bf16 v[82:85], v[184:187], v[208:211], v[82:85]
	v_mfma_f32_16x16x32_bf16 v[70:73], v[176:179], v[216:219], v[70:73]
	v_mfma_f32_16x16x32_bf16 v[66:69], v[184:187], v[216:219], v[66:69]
	s_setprio 0
	s_waitcnt vmcnt(8)
	s_barrier
	s_add_i32 s62, s55, s35
	s_mov_b32 m0, s62
	ds_read_b128 v[188:191], v157 offset:16384
	ds_read_b128 v[192:195], v157 offset:17408
	ds_read_b128 v[196:199], v157 offset:18432
	ds_read_b128 v[200:203], v157 offset:19456
	ds_read_b128 v[204:207], v157 offset:20480
	ds_read_b128 v[208:211], v157 offset:21504
	ds_read_b128 v[212:215], v157 offset:22528
	ds_read_b128 v[216:219], v157 offset:23552
	global_load_lds_dwordx4 v132, s[26:27]
	s_add_i32 m0, s62, 0x2000
	s_add_u32 s62, s26, 0x4000
	s_addc_u32 s63, s27, 0
	s_add_i32 s64, s56, s35
	global_load_lds_dwordx4 v136, s[26:27]
	s_mov_b32 m0, s64
	s_nop 0
	global_load_lds_dwordx4 v132, s[62:63]
	s_add_i32 m0, s64, 0x2000
	s_nop 0
	global_load_lds_dwordx4 v136, s[62:63]
	s_mov_b32 m0, s38
	s_nop 0
	global_load_lds_dwordx4 v130, s[28:29]
	s_mov_b32 m0, s39
	s_nop 0
	global_load_lds_dwordx4 v134, s[28:29]
	s_and_b64 vcc, exec, s[12:13]
	s_cbranch_vccnz .Lmy_skipw_26
	s_waitcnt vmcnt(8)
; #define PG8_STAGE(bufoff, gbase, voff) do { _Pragma("unroll") for (int _i = 0; _i < 2; ++_i) \
;         __builtin_amdgcn_global_load_lds((const unsigned*)((const char*)(gbase) + (voff)[_i]), (PG8_LAS unsigned*)(lds + (bufoff) + ldsw + _i * 8192), 16, 0, 0); } while (0)
; #define PG8_LDA(dst, b, h) do { _Pragma("unroll") for (int m = 0; m < 4; ++m) _Pragma("unroll") for (int k = 0; k < 2; ++k) dst[m][k] = *(const PG8_LAS bf16x8*)(lds + PG8_SA(b, h) + aoff + m * 2048 + k * 1024); } while (0)
; #define PG8_LDB(dst, b, h) do { _Pragma("unroll") for (int n = 0; n < 2; ++n) _Pragma("unroll") for (int k = 0; k < 2; ++k) dst[n][k] = *(const PG8_LAS bf16x8*)(lds + PG8_SB(b, h) + boff + n * 2048 + k * 1024); } while (0)
; #define PG8_MMA(ai, bj, At, Bt) do { __builtin_amdgcn_s_setprio(1); _Pragma("unroll") for (int m = 0; m < 4; ++m) _Pragma("unroll") for (int n = 0; n < 2; ++n) _Pragma("unroll") for (int k = 0; k < 2; ++k) \
;         acc[ai][bj][m][n] = __builtin_amdgcn_mfma_f32_16x16x32_bf16(Bt[n][k], At[m][k], acc[ai][bj][m][n], 0, 0, 0); __builtin_amdgcn_s_setprio(0); } while (0)
; #define PG8_WAIT_V(n) asm volatile("s_waitcnt vmcnt(" #n ")" ::: "memory")
; #define PG8_WAIT_L(n) asm volatile("s_waitcnt lgkmcnt(" #n ")" ::: "memory")
; #define PG8_BAR __builtin_amdgcn_s_barrier()
; #define PG8_SCHED __builtin_amdgcn_sched_barrier(0)
; template <class Epi, class Sched, bool ALIGN_EPI = false, bool SP2 = false, bool A_TILED = false>
; __device__ __forceinline__ void gemm_phase(PG8_LAS unsigned char* lds, const Gemm g, const Sched& S, const Epi& E) {
;     ...
;             PG8_WAIT_V(8); PG8_WAIT_L(0); PG8_BAR; PG8_MMA(1, 0, At, B0); PG8_MMA(1, 1, At, B1); PG8_BAR; PG8_SCHED;
;             PG8_LDB(B0, 1, 0); PG8_LDB(B1, 1, 1); PG8_SCHED; PG8_LDA(At, 1, 0); PG8_STAGE(PG8_SA(0, 1), a2 + hstepA, voffA);
;             PG8_WAIT_V(8); PG8_WAIT_L(0); PG8_BAR; PG8_MMA(0, 0, At, B0); PG8_MMA(0, 1, At, B1); PG8_BAR; PG8_SCHED;
;             PG8_LDA(At, 1, 1); PG8_STAGE(PG8_SB(1, 0), b3, voffB); PG8_STAGE(PG8_SB(1, 1), b3 + hstepB, voffB); PG8_STAGE(PG8_SA(1, 0), a3, voffA);
.Lmy_skipw_26:
	s_waitcnt lgkmcnt(0)
	s_setprio 1
	s_barrier
	v_mfma_f32_16x16x32_bf16 v[62:65], v[152:155], v[188:191], 0
	v_mfma_f32_16x16x32_bf16 v[62:65], v[160:163], v[192:195], v[62:65]
	v_mfma_f32_16x16x32_bf16 v[58:61], v[164:167], v[188:191], 0
	v_mfma_f32_16x16x32_bf16 v[58:61], v[168:171], v[192:195], v[58:61]
	v_mfma_f32_16x16x32_bf16 v[54:57], v[172:175], v[188:191], 0
	v_mfma_f32_16x16x32_bf16 v[54:57], v[176:179], v[192:195], v[54:57]
	v_mfma_f32_16x16x32_bf16 v[50:53], v[180:183], v[188:191], 0
	v_mfma_f32_16x16x32_bf16 v[50:53], v[184:187], v[192:195], v[50:53]
	v_mfma_f32_16x16x32_bf16 v[46:49], v[152:155], v[196:199], 0
	v_mfma_f32_16x16x32_bf16 v[46:49], v[160:163], v[200:203], v[46:49]
	v_mfma_f32_16x16x32_bf16 v[42:45], v[164:167], v[196:199], 0
	v_mfma_f32_16x16x32_bf16 v[42:45], v[168:171], v[200:203], v[42:45]
	v_mfma_f32_16x16x32_bf16 v[38:41], v[172:175], v[196:199], 0
	v_mfma_f32_16x16x32_bf16 v[38:41], v[176:179], v[200:203], v[38:41]
	v_mfma_f32_16x16x32_bf16 v[34:37], v[180:183], v[196:199], 0
	v_mfma_f32_16x16x32_bf16 v[34:37], v[184:187], v[200:203], v[34:37]
	v_mfma_f32_16x16x32_bf16 v[30:33], v[152:155], v[204:207], 0
	v_mfma_f32_16x16x32_bf16 v[30:33], v[160:163], v[208:211], v[30:33]
	v_mfma_f32_16x16x32_bf16 v[26:29], v[164:167], v[204:207], 0
	v_mfma_f32_16x16x32_bf16 v[26:29], v[168:171], v[208:211], v[26:29]
	v_mfma_f32_16x16x32_bf16 v[22:25], v[172:175], v[204:207], 0
	v_mfma_f32_16x16x32_bf16 v[22:25], v[176:179], v[208:211], v[22:25]
	v_mfma_f32_16x16x32_bf16 v[18:21], v[180:183], v[204:207], 0
	v_mfma_f32_16x16x32_bf16 v[18:21], v[184:187], v[208:211], v[18:21]
	v_mfma_f32_16x16x32_bf16 v[14:17], v[152:155], v[212:215], 0
	v_mfma_f32_16x16x32_bf16 v[14:17], v[160:163], v[216:219], v[14:17]
	v_mfma_f32_16x16x32_bf16 v[10:13], v[164:167], v[212:215], 0
	v_mfma_f32_16x16x32_bf16 v[10:13], v[168:171], v[216:219], v[10:13]
	v_mfma_f32_16x16x32_bf16 v[6:9], v[172:175], v[212:215], 0
	v_mfma_f32_16x16x32_bf16 v[6:9], v[176:179], v[216:219], v[6:9]
	v_mfma_f32_16x16x32_bf16 v[2:5], v[180:183], v[212:215], 0
	v_mfma_f32_16x16x32_bf16 v[2:5], v[184:187], v[216:219], v[2:5]
	s_waitcnt vmcnt(8)
	s_barrier
	s_setprio 0
	s_add_i32 s62, 0, 0x18000
	s_add_i32 s63, 0, 0x1c000
	ds_read_b128 v[152:155], v141 offset:32768
	ds_read_b128 v[160:163], v141 offset:33792
	ds_read_b128 v[164:167], v141 offset:34816
	ds_read_b128 v[168:171], v141 offset:35840
	ds_read_b128 v[172:175], v141 offset:49152
	ds_read_b128 v[176:179], v141 offset:50176
	ds_read_b128 v[180:183], v141 offset:51200
	ds_read_b128 v[184:187], v141 offset:52224
	s_add_u32 s28, s28, 0x4000
	s_addc_u32 s29, s29, 0
	s_mov_b32 m0, s40
	ds_read_b128 v[188:191], v157 offset:32768
	ds_read_b128 v[192:195], v157 offset:33792
	ds_read_b128 v[196:199], v157 offset:34816
	ds_read_b128 v[200:203], v157 offset:35840
	ds_read_b128 v[204:207], v157 offset:36864
	ds_read_b128 v[208:211], v157 offset:37888
	ds_read_b128 v[212:215], v157 offset:38912
	ds_read_b128 v[216:219], v157 offset:39936
	global_load_lds_dwordx4 v130, s[28:29]
	s_mov_b32 m0, s41
	s_nop 0
	global_load_lds_dwordx4 v134, s[28:29]
	s_and_b64 vcc, exec, s[12:13]
	s_cbranch_vccnz .Lmy_skipw_27
	s_waitcnt vmcnt(8)
.Lmy_skipw_27:
	s_waitcnt lgkmcnt(0)
	s_setprio 1
	s_barrier
	v_mfma_f32_16x16x32_bf16 v[126:129], v[152:155], v[188:191], v[126:129]
	v_mfma_f32_16x16x32_bf16 v[126:129], v[160:163], v[192:195], v[126:129]
	v_mfma_f32_16x16x32_bf16 v[122:125], v[164:167], v[188:191], v[122:125]
	v_mfma_f32_16x16x32_bf16 v[122:125], v[168:171], v[192:195], v[122:125]
	v_mfma_f32_16x16x32_bf16 v[118:121], v[172:175], v[188:191], v[118:121]
	v_mfma_f32_16x16x32_bf16 v[118:121], v[176:179], v[192:195], v[118:121]
	v_mfma_f32_16x16x32_bf16 v[114:117], v[180:183], v[188:191], v[114:117]
	v_mfma_f32_16x16x32_bf16 v[114:117], v[184:187], v[192:195], v[114:117]
	v_mfma_f32_16x16x32_bf16 v[110:113], v[152:155], v[196:199], v[110:113]
	v_mfma_f32_16x16x32_bf16 v[110:113], v[160:163], v[200:203], v[110:113]
	v_mfma_f32_16x16x32_bf16 v[106:109], v[164:167], v[196:199], v[106:109]
	v_mfma_f32_16x16x32_bf16 v[106:109], v[168:171], v[200:203], v[106:109]
	v_mfma_f32_16x16x32_bf16 v[102:105], v[172:175], v[196:199], v[102:105]
	v_mfma_f32_16x16x32_bf16 v[102:105], v[176:179], v[200:203], v[102:105]
	v_mfma_f32_16x16x32_bf16 v[98:101], v[180:183], v[196:199], v[98:101]
	v_mfma_f32_16x16x32_bf16 v[98:101], v[184:187], v[200:203], v[98:101]
	v_mfma_f32_16x16x32_bf16 v[94:97], v[152:155], v[204:207], v[94:97]
	v_mfma_f32_16x16x32_bf16 v[94:97], v[160:163], v[208:211], v[94:97]
	v_mfma_f32_16x16x32_bf16 v[90:93], v[164:167], v[204:207], v[90:93]
	v_mfma_f32_16x16x32_bf16 v[90:93], v[168:171], v[208:211], v[90:93]
	v_mfma_f32_16x16x32_bf16 v[86:89], v[172:175], v[204:207], v[86:89]
	v_mfma_f32_16x16x32_bf16 v[86:89], v[176:179], v[208:211], v[86:89]
	v_mfma_f32_16x16x32_bf16 v[82:85], v[180:183], v[204:207], v[82:85]
	v_mfma_f32_16x16x32_bf16 v[82:85], v[184:187], v[208:211], v[82:85]
	v_mfma_f32_16x16x32_bf16 v[78:81], v[152:155], v[212:215], v[78:81]
	v_mfma_f32_16x16x32_bf16 v[78:81], v[160:163], v[216:219], v[78:81]
	v_mfma_f32_16x16x32_bf16 v[74:77], v[164:167], v[212:215], v[74:77]
	v_mfma_f32_16x16x32_bf16 v[74:77], v[168:171], v[216:219], v[74:77]
	v_mfma_f32_16x16x32_bf16 v[70:73], v[172:175], v[212:215], v[70:73]
	v_mfma_f32_16x16x32_bf16 v[70:73], v[176:179], v[216:219], v[70:73]
	v_mfma_f32_16x16x32_bf16 v[66:69], v[180:183], v[212:215], v[66:69]
	v_mfma_f32_16x16x32_bf16 v[66:69], v[184:187], v[216:219], v[66:69]
	s_waitcnt vmcnt(8)
	s_barrier
	s_setprio 0
	s_add_u32 s28, s26, 0x8000
	s_addc_u32 s29, s27, 0
	s_add_i32 s62, s62, s35
	s_mov_b32 m0, s62
	ds_read_b128 v[188:191], v157 offset:49152
	ds_read_b128 v[192:195], v157 offset:50176
	ds_read_b128 v[196:199], v157 offset:51200
	ds_read_b128 v[200:203], v157 offset:52224
	ds_read_b128 v[204:207], v157 offset:53248
	ds_read_b128 v[208:211], v157 offset:54272
	ds_read_b128 v[212:215], v157 offset:55296
	ds_read_b128 v[216:219], v157 offset:56320
	global_load_lds_dwordx4 v132, s[28:29]
	s_add_i32 m0, s62, 0x2000
	s_add_u32 s26, s26, 0xc000
	v_lshl_add_u64 v[220:221], s[28:29], 0, v[136:137]
	s_addc_u32 s27, s27, 0
	s_add_i32 s28, s63, s35
	global_load_lds_dwordx4 v[220:221], off
	s_mov_b32 m0, s28
	s_nop 0
	global_load_lds_dwordx4 v132, s[26:27]
	s_add_i32 m0, s28, 0x2000
	s_nop 0
	global_load_lds_dwordx4 v136, s[26:27]
	s_mov_b32 m0, s45
	s_nop 0
	global_load_lds_dwordx4 v130, s[24:25]
	s_mov_b32 m0, s54
	s_nop 0
	global_load_lds_dwordx4 v134, s[24:25]
	s_and_b64 vcc, exec, s[12:13]
	s_cbranch_vccnz .Lmy_skipw_28
	s_waitcnt vmcnt(8)
; #define PG8_STAGE(bufoff, gbase, voff) do { _Pragma("unroll") for (int _i = 0; _i < 2; ++_i) \
;         __builtin_amdgcn_global_load_lds((const unsigned*)((const char*)(gbase) + (voff)[_i]), (PG8_LAS unsigned*)(lds + (bufoff) + ldsw + _i * 8192), 16, 0, 0); } while (0)
; #define PG8_LDA(dst, b, h) do { _Pragma("unroll") for (int m = 0; m < 4; ++m) _Pragma("unroll") for (int k = 0; k < 2; ++k) dst[m][k] = *(const PG8_LAS bf16x8*)(lds + PG8_SA(b, h) + aoff + m * 2048 + k * 1024); } while (0)
; #define PG8_LDB(dst, b, h) do { _Pragma("unroll") for (int n = 0; n < 2; ++n) _Pragma("unroll") for (int k = 0; k < 2; ++k) dst[n][k] = *(const PG8_LAS bf16x8*)(lds + PG8_SB(b, h) + boff + n * 2048 + k * 1024); } while (0)
; #define PG8_MMA(ai, bj, At, Bt) do { __builtin_amdgcn_s_setprio(1); _Pragma("unroll") for (int m = 0; m < 4; ++m) _Pragma("unroll") for (int n = 0; n < 2; ++n) _Pragma("unroll") for (int k = 0; k < 2; ++k) \
;         acc[ai][bj][m][n] = __builtin_amdgcn_mfma_f32_16x16x32_bf16(Bt[n][k], At[m][k], acc[ai][bj][m][n], 0, 0, 0); __builtin_amdgcn_s_setprio(0); } while (0)
; #define PG8_WAIT_V(n) asm volatile("s_waitcnt vmcnt(" #n ")" ::: "memory")
; #define PG8_WAIT_L(n) asm volatile("s_waitcnt lgkmcnt(" #n ")" ::: "memory")
; #define PG8_BAR __builtin_amdgcn_s_barrier()
; #define PG8_SCHED __builtin_amdgcn_sched_barrier(0)
; template <class Epi, class Sched, bool ALIGN_EPI = false, bool SP2 = false, bool A_TILED = false>
; __device__ __forceinline__ void gemm_phase(PG8_LAS unsigned char* lds, const Gemm g, const Sched& S, const Epi& E) {
;     ...
;         for (int t = 0; t < nt; t += 2) {
;             const bool last = (t == nt - 2);
;             const char* a1 = cA + (size_t)(t + 1) * kstepA;
;             const char* a2 = last ? nA : cA + (size_t)(t + 2) * kstepA; const char* b2 = last ? nB : cB + (size_t)(t + 2) * kstepB;
;             const char* a3 = a2 + kstepA; const char* b3 = b2 + kstepB;
;             if (last && has_next) S.a_ready(nxt);
;             if constexpr (SP2) {
;             PG8_LDB(B0, 0, 0); PG8_LDB(B1, 0, 1); PG8_SCHED; PG8_LDA(At, 0, 0); PG8_STAGE(PG8_SA(1, 1), a1 + hstepA, voffA);
;             PG8_WAIT_V(8); PG8_WAIT_L(0); PG8_BAR; PG8_MMA(0, 0, At, B0); PG8_MMA(0, 1, At, B1); PG8_BAR; PG8_SCHED;
;     ...
;             PG8_WAIT_V(8); PG8_WAIT_L(0); PG8_BAR; PG8_MMA(1, 0, At, B0); PG8_MMA(1, 1, At, B1); PG8_BAR; PG8_SCHED;
.Lmy_skipw_28:
	s_waitcnt lgkmcnt(0)
	s_setprio 1
	s_barrier
	v_mfma_f32_16x16x32_bf16 v[62:65], v[152:155], v[188:191], v[62:65]
	v_mfma_f32_16x16x32_bf16 v[62:65], v[160:163], v[192:195], v[62:65]
	v_mfma_f32_16x16x32_bf16 v[58:61], v[164:167], v[188:191], v[58:61]
	v_mfma_f32_16x16x32_bf16 v[58:61], v[168:171], v[192:195], v[58:61]
	v_mfma_f32_16x16x32_bf16 v[54:57], v[172:175], v[188:191], v[54:57]
	v_mfma_f32_16x16x32_bf16 v[54:57], v[176:179], v[192:195], v[54:57]
	v_mfma_f32_16x16x32_bf16 v[50:53], v[180:183], v[188:191], v[50:53]
	v_mfma_f32_16x16x32_bf16 v[50:53], v[184:187], v[192:195], v[50:53]
	v_mfma_f32_16x16x32_bf16 v[46:49], v[152:155], v[196:199], v[46:49]
	v_mfma_f32_16x16x32_bf16 v[46:49], v[160:163], v[200:203], v[46:49]
	v_mfma_f32_16x16x32_bf16 v[42:45], v[164:167], v[196:199], v[42:45]
	v_mfma_f32_16x16x32_bf16 v[42:45], v[168:171], v[200:203], v[42:45]
	v_mfma_f32_16x16x32_bf16 v[38:41], v[172:175], v[196:199], v[38:41]
	v_mfma_f32_16x16x32_bf16 v[38:41], v[176:179], v[200:203], v[38:41]
	v_mfma_f32_16x16x32_bf16 v[34:37], v[180:183], v[196:199], v[34:37]
	v_mfma_f32_16x16x32_bf16 v[34:37], v[184:187], v[200:203], v[34:37]
	v_mfma_f32_16x16x32_bf16 v[30:33], v[152:155], v[204:207], v[30:33]
	v_mfma_f32_16x16x32_bf16 v[30:33], v[160:163], v[208:211], v[30:33]
	v_mfma_f32_16x16x32_bf16 v[26:29], v[164:167], v[204:207], v[26:29]
	v_mfma_f32_16x16x32_bf16 v[26:29], v[168:171], v[208:211], v[26:29]
	v_mfma_f32_16x16x32_bf16 v[22:25], v[172:175], v[204:207], v[22:25]
	v_mfma_f32_16x16x32_bf16 v[22:25], v[176:179], v[208:211], v[22:25]
	v_mfma_f32_16x16x32_bf16 v[18:21], v[180:183], v[204:207], v[18:21]
	v_mfma_f32_16x16x32_bf16 v[18:21], v[184:187], v[208:211], v[18:21]
	v_mfma_f32_16x16x32_bf16 v[14:17], v[152:155], v[212:215], v[14:17]
	v_mfma_f32_16x16x32_bf16 v[14:17], v[160:163], v[216:219], v[14:17]
	v_mfma_f32_16x16x32_bf16 v[10:13], v[164:167], v[212:215], v[10:13]
	v_mfma_f32_16x16x32_bf16 v[10:13], v[168:171], v[216:219], v[10:13]
	v_mfma_f32_16x16x32_bf16 v[6:9], v[172:175], v[212:215], v[6:9]
	v_mfma_f32_16x16x32_bf16 v[6:9], v[176:179], v[216:219], v[6:9]
	v_mfma_f32_16x16x32_bf16 v[2:5], v[180:183], v[212:215], v[2:5]
	v_mfma_f32_16x16x32_bf16 v[2:5], v[184:187], v[216:219], v[2:5]
	s_waitcnt vmcnt(8)
	s_barrier
	s_setprio 0
	s_add_i32 s61, s61, 2
	s_add_u32 s22, s22, 0x10000
	s_addc_u32 s23, s23, 0
	s_add_u32 s59, s59, 0x10000
	s_addc_u32 s60, s60, 0
.LBB0_1172:
	ds_read_b128 v[152:155], v141
	ds_read_b128 v[160:163], v141 offset:1024
	ds_read_b128 v[164:167], v141 offset:2048
	ds_read_b128 v[168:171], v141 offset:3072
	ds_read_b128 v[172:175], v156
	ds_read_b128 v[176:179], v156 offset:1024
	ds_read_b128 v[180:183], v156 offset:2048
	ds_read_b128 v[184:187], v156 offset:3072
	s_add_u32 s24, s22, 0x4000
	s_addc_u32 s25, s23, 0
	s_cmp_eq_u32 s61, 60
	s_cselect_b32 s28, s33, s24
	s_cselect_b32 s29, s17, s25
	s_cselect_b32 s26, s58, s59
	s_cselect_b32 s27, s15, s60
	s_add_u32 s24, s28, 0x8000
	s_addc_u32 s25, s29, 0
	s_add_i32 m0, s38, 0xc000
	ds_read_b128 v[188:191], v157
	ds_read_b128 v[192:195], v157 offset:1024
	ds_read_b128 v[196:199], v157 offset:2048
	ds_read_b128 v[200:203], v157 offset:3072
	ds_read_b128 v[204:207], v157 offset:4096
	ds_read_b128 v[208:211], v157 offset:5120
	ds_read_b128 v[212:215], v157 offset:6144
	ds_read_b128 v[216:219], v157 offset:7168
	global_load_lds_dwordx4 v144, s[22:23]
	s_add_i32 m0, s38, 0xe000
	s_nop 0
	global_load_lds_dwordx4 v146, s[22:23]
	s_and_b64 vcc, exec, s[12:13]
	s_cbranch_vccnz .Lmy_skipw_29
	s_waitcnt vmcnt(8)
; #define PG8_STAGE(bufoff, gbase, voff) do { _Pragma("unroll") for (int _i = 0; _i < 2; ++_i) \
;         __builtin_amdgcn_global_load_lds((const unsigned*)((const char*)(gbase) + (voff)[_i]), (PG8_LAS unsigned*)(lds + (bufoff) + ldsw + _i * 8192), 16, 0, 0); } while (0)
; #define PG8_LDA(dst, b, h) do { _Pragma("unroll") for (int m = 0; m < 4; ++m) _Pragma("unroll") for (int k = 0; k < 2; ++k) dst[m][k] = *(const PG8_LAS bf16x8*)(lds + PG8_SA(b, h) + aoff + m * 2048 + k * 1024); } while (0)
; #define PG8_LDB(dst, b, h) do { _Pragma("unroll") for (int n = 0; n < 2; ++n) _Pragma("unroll") for (int k = 0; k < 2; ++k) dst[n][k] = *(const PG8_LAS bf16x8*)(lds + PG8_SB(b, h) + boff + n * 2048 + k * 1024); } while (0)
; #define PG8_MMA(ai, bj, At, Bt) do { __builtin_amdgcn_s_setprio(1); _Pragma("unroll") for (int m = 0; m < 4; ++m) _Pragma("unroll") for (int n = 0; n < 2; ++n) _Pragma("unroll") for (int k = 0; k < 2; ++k) \
;         acc[ai][bj][m][n] = __builtin_amdgcn_mfma_f32_16x16x32_bf16(Bt[n][k], At[m][k], acc[ai][bj][m][n], 0, 0, 0); __builtin_amdgcn_s_setprio(0); } while (0)
; #define PG8_WAIT_V(n) asm volatile("s_waitcnt vmcnt(" #n ")" ::: "memory")
; #define PG8_WAIT_L(n) asm volatile("s_waitcnt lgkmcnt(" #n ")" ::: "memory")
; #define PG8_BAR __builtin_amdgcn_s_barrier()
; #define PG8_SCHED __builtin_amdgcn_sched_barrier(0)
; template <class Epi, class Sched, bool ALIGN_EPI = false, bool SP2 = false, bool A_TILED = false>
; __device__ __forceinline__ void gemm_phase(PG8_LAS unsigned char* lds, const Gemm g, const Sched& S, const Epi& E) {
;     ...
;             PG8_WAIT_V(8); PG8_WAIT_L(0); PG8_BAR; PG8_MMA(0, 0, At, B0); PG8_MMA(0, 1, At, B1); PG8_BAR; PG8_SCHED;
;             PG8_LDA(At, 0, 1); PG8_STAGE(PG8_SB(0, 0), b2, voffB); PG8_STAGE(PG8_SB(0, 1), b2 + hstepB, voffB); PG8_STAGE(PG8_SA(0, 0), a2, voffA);
;             PG8_WAIT_V(8); PG8_WAIT_L(0); PG8_BAR; PG8_MMA(1, 0, At, B0); PG8_MMA(1, 1, At, B1); PG8_BAR; PG8_SCHED;
;             PG8_LDB(B0, 1, 0); PG8_LDB(B1, 1, 1); PG8_SCHED; PG8_LDA(At, 1, 0); PG8_STAGE(PG8_SA(0, 1), a2 + hstepA, voffA);
;             PG8_WAIT_V(8); PG8_WAIT_L(0); PG8_BAR; PG8_MMA(0, 0, At, B0); PG8_MMA(0, 1, At, B1); PG8_BAR; PG8_SCHED;
;             PG8_LDA(At, 1, 1); PG8_STAGE(PG8_SB(1, 0), b3, voffB); PG8_STAGE(PG8_SB(1, 1), b3 + hstepB, voffB); PG8_STAGE(PG8_SA(1, 0), a3, voffA);
.Lmy_skipw_29:
	s_waitcnt lgkmcnt(0)
	s_barrier
	s_setprio 1
	s_waitcnt lgkmcnt(0)
	v_mfma_f32_16x16x32_bf16 v[126:129], v[152:155], v[188:191], v[126:129]
	v_mfma_f32_16x16x32_bf16 v[122:125], v[164:167], v[188:191], v[122:125]
	v_mfma_f32_16x16x32_bf16 v[110:113], v[152:155], v[196:199], v[110:113]
	v_mfma_f32_16x16x32_bf16 v[106:109], v[164:167], v[196:199], v[106:109]
	v_mfma_f32_16x16x32_bf16 v[94:97], v[152:155], v[204:207], v[94:97]
	v_mfma_f32_16x16x32_bf16 v[90:93], v[164:167], v[204:207], v[90:93]
	v_mfma_f32_16x16x32_bf16 v[78:81], v[152:155], v[212:215], v[78:81]
	v_mfma_f32_16x16x32_bf16 v[74:77], v[164:167], v[212:215], v[74:77]
	v_mfma_f32_16x16x32_bf16 v[126:129], v[160:163], v[192:195], v[126:129]
	v_mfma_f32_16x16x32_bf16 v[122:125], v[168:171], v[192:195], v[122:125]
	v_mfma_f32_16x16x32_bf16 v[110:113], v[160:163], v[200:203], v[110:113]
	v_mfma_f32_16x16x32_bf16 v[106:109], v[168:171], v[200:203], v[106:109]
	v_mfma_f32_16x16x32_bf16 v[94:97], v[160:163], v[208:211], v[94:97]
	v_mfma_f32_16x16x32_bf16 v[90:93], v[168:171], v[208:211], v[90:93]
	v_mfma_f32_16x16x32_bf16 v[78:81], v[160:163], v[216:219], v[78:81]
	v_mfma_f32_16x16x32_bf16 v[74:77], v[168:171], v[216:219], v[74:77]
	s_setprio 0
	s_setprio 1
	v_mfma_f32_16x16x32_bf16 v[118:121], v[172:175], v[188:191], v[118:121]
	v_mfma_f32_16x16x32_bf16 v[114:117], v[180:183], v[188:191], v[114:117]
	v_mfma_f32_16x16x32_bf16 v[102:105], v[172:175], v[196:199], v[102:105]
	v_mfma_f32_16x16x32_bf16 v[98:101], v[180:183], v[196:199], v[98:101]
	v_mfma_f32_16x16x32_bf16 v[86:89], v[172:175], v[204:207], v[86:89]
	v_mfma_f32_16x16x32_bf16 v[82:85], v[180:183], v[204:207], v[82:85]
	v_mfma_f32_16x16x32_bf16 v[70:73], v[172:175], v[212:215], v[70:73]
	v_mfma_f32_16x16x32_bf16 v[66:69], v[180:183], v[212:215], v[66:69]
	v_mfma_f32_16x16x32_bf16 v[118:121], v[176:179], v[192:195], v[118:121]
	v_mfma_f32_16x16x32_bf16 v[114:117], v[184:187], v[192:195], v[114:117]
	v_mfma_f32_16x16x32_bf16 v[102:105], v[176:179], v[200:203], v[102:105]
	v_mfma_f32_16x16x32_bf16 v[98:101], v[184:187], v[200:203], v[98:101]
	v_mfma_f32_16x16x32_bf16 v[86:89], v[176:179], v[208:211], v[86:89]
	v_mfma_f32_16x16x32_bf16 v[82:85], v[184:187], v[208:211], v[82:85]
	v_mfma_f32_16x16x32_bf16 v[70:73], v[176:179], v[216:219], v[70:73]
	v_mfma_f32_16x16x32_bf16 v[66:69], v[184:187], v[216:219], v[66:69]
	s_setprio 0
	s_waitcnt vmcnt(8)
	s_barrier
	s_add_i32 s62, s55, s35
	s_mov_b32 m0, s62
	ds_read_b128 v[188:191], v157 offset:16384
	ds_read_b128 v[192:195], v157 offset:17408
	ds_read_b128 v[196:199], v157 offset:18432
	ds_read_b128 v[200:203], v157 offset:19456
	ds_read_b128 v[204:207], v157 offset:20480
	ds_read_b128 v[208:211], v157 offset:21504
	ds_read_b128 v[212:215], v157 offset:22528
	ds_read_b128 v[216:219], v157 offset:23552
	global_load_lds_dwordx4 v132, s[26:27]
	s_add_i32 m0, s62, 0x2000
	s_add_u32 s62, s26, 0x4000
	s_addc_u32 s63, s27, 0
	s_add_i32 s64, s56, s35
	global_load_lds_dwordx4 v136, s[26:27]
	s_mov_b32 m0, s64
	s_nop 0
	global_load_lds_dwordx4 v132, s[62:63]
	s_add_i32 m0, s64, 0x2000
	s_nop 0
	global_load_lds_dwordx4 v136, s[62:63]
	s_mov_b32 m0, s38
	s_nop 0
	global_load_lds_dwordx4 v130, s[28:29]
	s_mov_b32 m0, s39
	s_nop 0
	global_load_lds_dwordx4 v134, s[28:29]
	s_and_b64 vcc, exec, s[12:13]
	s_cbranch_vccnz .Lmy_skipw_30
	s_waitcnt vmcnt(8)
.Lmy_skipw_30:
	s_waitcnt lgkmcnt(0)
	s_setprio 1
	s_barrier
	v_mfma_f32_16x16x32_bf16 v[62:65], v[152:155], v[188:191], v[62:65]
	v_mfma_f32_16x16x32_bf16 v[62:65], v[160:163], v[192:195], v[62:65]
	v_mfma_f32_16x16x32_bf16 v[58:61], v[164:167], v[188:191], v[58:61]
	v_mfma_f32_16x16x32_bf16 v[58:61], v[168:171], v[192:195], v[58:61]
	v_mfma_f32_16x16x32_bf16 v[54:57], v[172:175], v[188:191], v[54:57]
	v_mfma_f32_16x16x32_bf16 v[54:57], v[176:179], v[192:195], v[54:57]
	v_mfma_f32_16x16x32_bf16 v[50:53], v[180:183], v[188:191], v[50:53]
	v_mfma_f32_16x16x32_bf16 v[50:53], v[184:187], v[192:195], v[50:53]
	v_mfma_f32_16x16x32_bf16 v[46:49], v[152:155], v[196:199], v[46:49]
	v_mfma_f32_16x16x32_bf16 v[46:49], v[160:163], v[200:203], v[46:49]
	v_mfma_f32_16x16x32_bf16 v[42:45], v[164:167], v[196:199], v[42:45]
	v_mfma_f32_16x16x32_bf16 v[42:45], v[168:171], v[200:203], v[42:45]
	v_mfma_f32_16x16x32_bf16 v[38:41], v[172:175], v[196:199], v[38:41]
	v_mfma_f32_16x16x32_bf16 v[38:41], v[176:179], v[200:203], v[38:41]
	v_mfma_f32_16x16x32_bf16 v[34:37], v[180:183], v[196:199], v[34:37]
	v_mfma_f32_16x16x32_bf16 v[34:37], v[184:187], v[200:203], v[34:37]
	v_mfma_f32_16x16x32_bf16 v[30:33], v[152:155], v[204:207], v[30:33]
	v_mfma_f32_16x16x32_bf16 v[30:33], v[160:163], v[208:211], v[30:33]
	v_mfma_f32_16x16x32_bf16 v[26:29], v[164:167], v[204:207], v[26:29]
	v_mfma_f32_16x16x32_bf16 v[26:29], v[168:171], v[208:211], v[26:29]
	v_mfma_f32_16x16x32_bf16 v[22:25], v[172:175], v[204:207], v[22:25]
	v_mfma_f32_16x16x32_bf16 v[22:25], v[176:179], v[208:211], v[22:25]
	v_mfma_f32_16x16x32_bf16 v[18:21], v[180:183], v[204:207], v[18:21]
	v_mfma_f32_16x16x32_bf16 v[18:21], v[184:187], v[208:211], v[18:21]
	v_mfma_f32_16x16x32_bf16 v[14:17], v[152:155], v[212:215], v[14:17]
	v_mfma_f32_16x16x32_bf16 v[14:17], v[160:163], v[216:219], v[14:17]
	v_mfma_f32_16x16x32_bf16 v[10:13], v[164:167], v[212:215], v[10:13]
	v_mfma_f32_16x16x32_bf16 v[10:13], v[168:171], v[216:219], v[10:13]
	v_mfma_f32_16x16x32_bf16 v[6:9], v[172:175], v[212:215], v[6:9]
	v_mfma_f32_16x16x32_bf16 v[6:9], v[176:179], v[216:219], v[6:9]
	v_mfma_f32_16x16x32_bf16 v[2:5], v[180:183], v[212:215], v[2:5]
	v_mfma_f32_16x16x32_bf16 v[2:5], v[184:187], v[216:219], v[2:5]
	s_waitcnt vmcnt(8)
	s_barrier
	s_setprio 0
	s_add_i32 s62, 0, 0x18000
	s_add_i32 s63, 0, 0x1c000
	ds_read_b128 v[152:155], v141 offset:32768
	ds_read_b128 v[160:163], v141 offset:33792
	ds_read_b128 v[164:167], v141 offset:34816
	ds_read_b128 v[168:171], v141 offset:35840
	ds_read_b128 v[172:175], v141 offset:49152
	ds_read_b128 v[176:179], v141 offset:50176
	ds_read_b128 v[180:183], v141 offset:51200
	ds_read_b128 v[184:187], v141 offset:52224
	s_add_u32 s28, s28, 0x4000
	s_addc_u32 s29, s29, 0
	s_mov_b32 m0, s40
	ds_read_b128 v[188:191], v157 offset:32768
	ds_read_b128 v[192:195], v157 offset:33792
	ds_read_b128 v[196:199], v157 offset:34816
	ds_read_b128 v[200:203], v157 offset:35840
	ds_read_b128 v[204:207], v157 offset:36864
	ds_read_b128 v[208:211], v157 offset:37888
	ds_read_b128 v[212:215], v157 offset:38912
	ds_read_b128 v[216:219], v157 offset:39936
	global_load_lds_dwordx4 v130, s[28:29]
	s_mov_b32 m0, s41
	s_nop 0
	global_load_lds_dwordx4 v134, s[28:29]
	s_and_b64 vcc, exec, s[12:13]
	s_cbranch_vccnz .Lmy_skipw_31
	s_waitcnt vmcnt(8)

; #define PG8_STAGE(bufoff, gbase, voff) do { _Pragma("unroll") for (int _i = 0; _i < 2; ++_i) \
;         __builtin_amdgcn_global_load_lds((const unsigned*)((const char*)(gbase) + (voff)[_i]), (PG8_LAS unsigned*)(lds + (bufoff) + ldsw + _i * 8192), 16, 0, 0); } while (0)
; #define PG8_LDA(dst, b, h) do { _Pragma("unroll") for (int m = 0; m < 4; ++m) _Pragma("unroll") for (int k = 0; k < 2; ++k) dst[m][k] = *(const PG8_LAS bf16x8*)(lds + PG8_SA(b, h) + aoff + m * 2048 + k * 1024); } while (0)
; #define PG8_MMA(ai, bj, At, Bt) do { __builtin_amdgcn_s_setprio(1); _Pragma("unroll") for (int m = 0; m < 4; ++m) _Pragma("unroll") for (int n = 0; n < 2; ++n) _Pragma("unroll") for (int k = 0; k < 2; ++k) \
;         acc[ai][bj][m][n] = __builtin_amdgcn_mfma_f32_16x16x32_bf16(Bt[n][k], At[m][k], acc[ai][bj][m][n], 0, 0, 0); __builtin_amdgcn_s_setprio(0); } while (0)
; #define PG8_WAIT_V(n) asm volatile("s_waitcnt vmcnt(" #n ")" ::: "memory")
; #define PG8_WAIT_L(n) asm volatile("s_waitcnt lgkmcnt(" #n ")" ::: "memory")
; #define PG8_BAR __builtin_amdgcn_s_barrier()
; #define PG8_SCHED __builtin_amdgcn_sched_barrier(0)
; template <class Epi, class Sched, bool ALIGN_EPI = false, bool SP2 = false, bool A_TILED = false>
; __device__ __forceinline__ void gemm_phase(PG8_LAS unsigned char* lds, const Gemm g, const Sched& S, const Epi& E) {
;     ...
;             PG8_LDA(At, 1, 1); PG8_STAGE(PG8_SB(1, 0), b3, voffB); PG8_STAGE(PG8_SB(1, 1), b3 + hstepB, voffB); PG8_STAGE(PG8_SA(1, 0), a3, voffA);
;             PG8_WAIT_V(8); PG8_WAIT_L(0); PG8_BAR; PG8_MMA(1, 0, At, B0); PG8_MMA(1, 1, At, B1); PG8_BAR; PG8_SCHED;
.Lmy_skipw_32:
	s_waitcnt lgkmcnt(0)
	s_setprio 1
	s_barrier
	v_mfma_f32_16x16x32_bf16 v[62:65], v[152:155], v[188:191], v[62:65]
	v_mfma_f32_16x16x32_bf16 v[62:65], v[160:163], v[192:195], v[62:65]
	v_mfma_f32_16x16x32_bf16 v[58:61], v[164:167], v[188:191], v[58:61]
	v_mfma_f32_16x16x32_bf16 v[58:61], v[168:171], v[192:195], v[58:61]
	v_mfma_f32_16x16x32_bf16 v[54:57], v[172:175], v[188:191], v[54:57]
	v_mfma_f32_16x16x32_bf16 v[54:57], v[176:179], v[192:195], v[54:57]
	v_mfma_f32_16x16x32_bf16 v[50:53], v[180:183], v[188:191], v[50:53]
	v_mfma_f32_16x16x32_bf16 v[50:53], v[184:187], v[192:195], v[50:53]
	v_mfma_f32_16x16x32_bf16 v[46:49], v[152:155], v[196:199], v[46:49]
	v_mfma_f32_16x16x32_bf16 v[46:49], v[160:163], v[200:203], v[46:49]
	v_mfma_f32_16x16x32_bf16 v[42:45], v[164:167], v[196:199], v[42:45]
	v_mfma_f32_16x16x32_bf16 v[42:45], v[168:171], v[200:203], v[42:45]
	v_mfma_f32_16x16x32_bf16 v[38:41], v[172:175], v[196:199], v[38:41]
	v_mfma_f32_16x16x32_bf16 v[38:41], v[176:179], v[200:203], v[38:41]
	v_mfma_f32_16x16x32_bf16 v[34:37], v[180:183], v[196:199], v[34:37]
	v_mfma_f32_16x16x32_bf16 v[34:37], v[184:187], v[200:203], v[34:37]
	v_mfma_f32_16x16x32_bf16 v[30:33], v[152:155], v[204:207], v[30:33]
	v_mfma_f32_16x16x32_bf16 v[30:33], v[160:163], v[208:211], v[30:33]
	v_mfma_f32_16x16x32_bf16 v[26:29], v[164:167], v[204:207], v[26:29]
	v_mfma_f32_16x16x32_bf16 v[26:29], v[168:171], v[208:211], v[26:29]
	v_mfma_f32_16x16x32_bf16 v[22:25], v[172:175], v[204:207], v[22:25]
	v_mfma_f32_16x16x32_bf16 v[22:25], v[176:179], v[208:211], v[22:25]
	v_mfma_f32_16x16x32_bf16 v[18:21], v[180:183], v[204:207], v[18:21]
	v_mfma_f32_16x16x32_bf16 v[18:21], v[184:187], v[208:211], v[18:21]
	v_mfma_f32_16x16x32_bf16 v[14:17], v[152:155], v[212:215], v[14:17]
	v_mfma_f32_16x16x32_bf16 v[14:17], v[160:163], v[216:219], v[14:17]
	v_mfma_f32_16x16x32_bf16 v[10:13], v[164:167], v[212:215], v[10:13]
	v_mfma_f32_16x16x32_bf16 v[10:13], v[168:171], v[216:219], v[10:13]
	v_mfma_f32_16x16x32_bf16 v[6:9], v[172:175], v[212:215], v[6:9]
	v_mfma_f32_16x16x32_bf16 v[6:9], v[176:179], v[216:219], v[6:9]
	v_mfma_f32_16x16x32_bf16 v[2:5], v[180:183], v[212:215], v[2:5]
	v_mfma_f32_16x16x32_bf16 v[2:5], v[184:187], v[216:219], v[2:5]
	s_waitcnt vmcnt(8)
	s_barrier
	s_setprio 0
	s_add_i32 s61, s61, 2
	s_add_u32 s22, s22, 0x10000
	s_addc_u32 s23, s23, 0
	s_add_u32 s59, s59, 0x10000
	s_addc_u32 s60, s60, 0
	s_cmp_gt_u32 s61, 61
	s_cbranch_scc0 .LBB0_1172
	s_and_b64 vcc, exec, s[12:13]
	s_cbranch_vccz .LBB0_1175
	s_barrier

; #define PG8_STAGE(bufoff, gbase, voff) do { _Pragma("unroll") for (int _i = 0; _i < 2; ++_i) \
;         __builtin_amdgcn_global_load_lds((const unsigned*)((const char*)(gbase) + (voff)[_i]), (PG8_LAS unsigned*)(lds + (bufoff) + ldsw + _i * 8192), 16, 0, 0); } while (0)
; #define PG8_LDA(dst, b, h) do { _Pragma("unroll") for (int m = 0; m < 4; ++m) _Pragma("unroll") for (int k = 0; k < 2; ++k) dst[m][k] = *(const PG8_LAS bf16x8*)(lds + PG8_SA(b, h) + aoff + m * 2048 + k * 1024); } while (0)
; #define PG8_LDB(dst, b, h) do { _Pragma("unroll") for (int n = 0; n < 2; ++n) _Pragma("unroll") for (int k = 0; k < 2; ++k) dst[n][k] = *(const PG8_LAS bf16x8*)(lds + PG8_SB(b, h) + boff + n * 2048 + k * 1024); } while (0)
; #define PG8_WAIT_V(n) asm volatile("s_waitcnt vmcnt(" #n ")" ::: "memory")
; #define PG8_WAIT_L(n) asm volatile("s_waitcnt lgkmcnt(" #n ")" ::: "memory")
; #define PG8_BAR __builtin_amdgcn_s_barrier()
; #define PG8_SCHED __builtin_amdgcn_sched_barrier(0)
; template <class Epi, class Sched, bool ALIGN_EPI = false, bool SP2 = false, bool A_TILED = false>
; __device__ __forceinline__ void gemm_phase(PG8_LAS unsigned char* lds, const Gemm g, const Sched& S, const Epi& E) {
;     ...
;         const bool has_next = S.next(ui + 1, nxt);
;         const char* nA = has_next ? (const char*)g.A + (size_t)nxt.pm * tstepA : cA; const char* nB = has_next ? (const char*)g.Bt + (size_t)nxt.pn * tstepB : cB;
;         for (int t = 0; t < nt; t += 2) {
;             const bool last = (t == nt - 2);
;             const char* a1 = cA + (size_t)(t + 1) * kstepA;
;             const char* a2 = last ? nA : cA + (size_t)(t + 2) * kstepA; const char* b2 = last ? nB : cB + (size_t)(t + 2) * kstepB;
;             const char* a3 = a2 + kstepA; const char* b3 = b2 + kstepB;
;             if (last && has_next) S.a_ready(nxt);
;             if constexpr (SP2) {
;             PG8_LDB(B0, 0, 0); PG8_LDB(B1, 0, 1); PG8_SCHED; PG8_LDA(At, 0, 0); PG8_STAGE(PG8_SA(1, 1), a1 + hstepA, voffA);
;             PG8_WAIT_V(8); PG8_WAIT_L(0); PG8_BAR; PG8_MMA(0, 0, At, B0); PG8_MMA(0, 1, At, B1); PG8_BAR; PG8_SCHED;
;             PG8_LDA(At, 0, 1); PG8_STAGE(PG8_SB(0, 0), b2, voffB); PG8_STAGE(PG8_SB(0, 1), b2 + hstepB, voffB); PG8_STAGE(PG8_SA(0, 0), a2, voffA);
;             PG8_WAIT_V(8); PG8_WAIT_L(0); PG8_BAR; PG8_MMA(1, 0, At, B0); PG8_MMA(1, 1, At, B1); PG8_BAR; PG8_SCHED;
.LBB0_1246:
	s_add_u32 s22, s22, 0xc000
	s_addc_u32 s23, s23, 0
	s_add_u32 s56, s24, 0x10000
	v_mov_b32_e32 v2, 0
	s_addc_u32 s57, s25, 0
	s_mov_b32 s58, -2
	ds_read_b128 v[142:145], v156
	ds_read_b128 v[146:149], v156 offset:1024
	ds_read_b128 v[150:153], v156 offset:2048
	ds_read_b128 v[160:163], v156 offset:3072
	ds_read_b128 v[164:167], v157
	ds_read_b128 v[168:171], v157 offset:1024
	ds_read_b128 v[172:175], v157 offset:2048
	ds_read_b128 v[176:179], v157 offset:3072
	s_add_u32 s24, s22, 0x4000
	s_addc_u32 s25, s23, 0
	s_cmpk_eq_i32 s58, 0xa8
	s_cselect_b32 s28, s4, s24
	s_cselect_b32 s29, s5, s25
	s_cselect_b32 s26, s20, s56
	s_cselect_b32 s27, s21, s57
	s_add_u32 s24, s28, 0x8000
	s_addc_u32 s25, s29, 0
	s_add_i32 m0, s35, 0xc000
	ds_read_b128 v[180:183], v158
	ds_read_b128 v[184:187], v158 offset:1024
	ds_read_b128 v[188:191], v158 offset:2048
	ds_read_b128 v[192:195], v158 offset:3072
	ds_read_b128 v[196:199], v158 offset:4096
	ds_read_b128 v[200:203], v158 offset:5120
	ds_read_b128 v[204:207], v158 offset:6144
	ds_read_b128 v[208:211], v158 offset:7168
	global_load_lds_dwordx4 v134, s[22:23]
	s_add_i32 m0, s35, 0xe000
	s_nop 0
	global_load_lds_dwordx4 v136, s[22:23]
	s_and_b64 vcc, exec, s[10:11]
	s_cbranch_vccnz .Lmy_skipw_33
	s_waitcnt vmcnt(8)
.Lmy_skipw_33:
	s_waitcnt lgkmcnt(0)
	s_barrier
	s_setprio 1
	s_waitcnt lgkmcnt(0)
	v_mfma_f32_16x16x32_bf16 v[126:129], v[142:145], v[180:183], 0
	v_mfma_f32_16x16x32_bf16 v[122:125], v[150:153], v[180:183], 0
	v_mfma_f32_16x16x32_bf16 v[118:121], v[142:145], v[188:191], 0
	v_mfma_f32_16x16x32_bf16 v[114:117], v[150:153], v[188:191], 0
	v_mfma_f32_16x16x32_bf16 v[94:97], v[142:145], v[196:199], 0
	v_mfma_f32_16x16x32_bf16 v[90:93], v[150:153], v[196:199], 0
	v_mfma_f32_16x16x32_bf16 v[86:89], v[142:145], v[204:207], 0
	v_mfma_f32_16x16x32_bf16 v[82:85], v[150:153], v[204:207], 0
	v_mfma_f32_16x16x32_bf16 v[126:129], v[146:149], v[184:187], v[126:129]
	v_mfma_f32_16x16x32_bf16 v[122:125], v[160:163], v[184:187], v[122:125]
	v_mfma_f32_16x16x32_bf16 v[118:121], v[146:149], v[192:195], v[118:121]
	v_mfma_f32_16x16x32_bf16 v[114:117], v[160:163], v[192:195], v[114:117]
	v_mfma_f32_16x16x32_bf16 v[94:97], v[146:149], v[200:203], v[94:97]
	v_mfma_f32_16x16x32_bf16 v[90:93], v[160:163], v[200:203], v[90:93]
	v_mfma_f32_16x16x32_bf16 v[86:89], v[146:149], v[208:211], v[86:89]
	v_mfma_f32_16x16x32_bf16 v[82:85], v[160:163], v[208:211], v[82:85]
	s_setprio 0
	s_setprio 1
	v_mfma_f32_16x16x32_bf16 v[110:113], v[164:167], v[180:183], 0
	v_mfma_f32_16x16x32_bf16 v[106:109], v[172:175], v[180:183], 0
	v_mfma_f32_16x16x32_bf16 v[102:105], v[164:167], v[188:191], 0
	v_mfma_f32_16x16x32_bf16 v[98:101], v[172:175], v[188:191], 0
	v_mfma_f32_16x16x32_bf16 v[78:81], v[164:167], v[196:199], 0
	v_mfma_f32_16x16x32_bf16 v[74:77], v[172:175], v[196:199], 0
	v_mfma_f32_16x16x32_bf16 v[70:73], v[164:167], v[204:207], 0
	v_mfma_f32_16x16x32_bf16 v[66:69], v[172:175], v[204:207], 0
	v_mfma_f32_16x16x32_bf16 v[110:113], v[168:171], v[184:187], v[110:113]
	v_mfma_f32_16x16x32_bf16 v[106:109], v[176:179], v[184:187], v[106:109]
	v_mfma_f32_16x16x32_bf16 v[102:105], v[168:171], v[192:195], v[102:105]
	v_mfma_f32_16x16x32_bf16 v[98:101], v[176:179], v[192:195], v[98:101]
	v_mfma_f32_16x16x32_bf16 v[78:81], v[168:171], v[200:203], v[78:81]
	v_mfma_f32_16x16x32_bf16 v[74:77], v[176:179], v[200:203], v[74:77]
	v_mfma_f32_16x16x32_bf16 v[70:73], v[168:171], v[208:211], v[70:73]
	v_mfma_f32_16x16x32_bf16 v[66:69], v[176:179], v[208:211], v[66:69]
	s_setprio 0
	s_waitcnt vmcnt(8)
	s_barrier
	s_add_i32 s59, s42, s31
	s_mov_b32 m0, s59
	ds_read_b128 v[180:183], v158 offset:16384
	ds_read_b128 v[184:187], v158 offset:17408
	ds_read_b128 v[188:191], v158 offset:18432
	ds_read_b128 v[192:195], v158 offset:19456
	ds_read_b128 v[196:199], v158 offset:20480
	ds_read_b128 v[200:203], v158 offset:21504
	ds_read_b128 v[204:207], v158 offset:22528
	ds_read_b128 v[208:211], v158 offset:23552
	global_load_lds_dwordx4 v130, s[26:27]
	s_add_i32 m0, s59, 0x2000
	s_add_u32 s60, s26, 0x4000
	s_addc_u32 s61, s27, 0
	s_add_i32 s59, s43, s31
	global_load_lds_dwordx4 v132, s[26:27]
	s_mov_b32 m0, s59
	s_nop 0
	global_load_lds_dwordx4 v130, s[60:61]
	s_add_i32 m0, s59, 0x2000
	s_nop 0
	global_load_lds_dwordx4 v132, s[60:61]
	s_mov_b32 m0, s35
	s_nop 0
	global_load_lds_dwordx4 v130, s[28:29]
	s_mov_b32 m0, s36
	s_nop 0
	global_load_lds_dwordx4 v132, s[28:29]
	s_and_b64 vcc, exec, s[10:11]
	s_cbranch_vccnz .Lmy_skipw_34
	s_waitcnt vmcnt(8)
; #define PG8_STAGE(bufoff, gbase, voff) do { _Pragma("unroll") for (int _i = 0; _i < 2; ++_i) \
;         __builtin_amdgcn_global_load_lds((const unsigned*)((const char*)(gbase) + (voff)[_i]), (PG8_LAS unsigned*)(lds + (bufoff) + ldsw + _i * 8192), 16, 0, 0); } while (0)
; #define PG8_LDA(dst, b, h) do { _Pragma("unroll") for (int m = 0; m < 4; ++m) _Pragma("unroll") for (int k = 0; k < 2; ++k) dst[m][k] = *(const PG8_LAS bf16x8*)(lds + PG8_SA(b, h) + aoff + m * 2048 + k * 1024); } while (0)
; #define PG8_LDB(dst, b, h) do { _Pragma("unroll") for (int n = 0; n < 2; ++n) _Pragma("unroll") for (int k = 0; k < 2; ++k) dst[n][k] = *(const PG8_LAS bf16x8*)(lds + PG8_SB(b, h) + boff + n * 2048 + k * 1024); } while (0)
; #define PG8_MMA(ai, bj, At, Bt) do { __builtin_amdgcn_s_setprio(1); _Pragma("unroll") for (int m = 0; m < 4; ++m) _Pragma("unroll") for (int n = 0; n < 2; ++n) _Pragma("unroll") for (int k = 0; k < 2; ++k) \
;         acc[ai][bj][m][n] = __builtin_amdgcn_mfma_f32_16x16x32_bf16(Bt[n][k], At[m][k], acc[ai][bj][m][n], 0, 0, 0); __builtin_amdgcn_s_setprio(0); } while (0)
; #define PG8_WAIT_V(n) asm volatile("s_waitcnt vmcnt(" #n ")" ::: "memory")
; #define PG8_WAIT_L(n) asm volatile("s_waitcnt lgkmcnt(" #n ")" ::: "memory")
; #define PG8_BAR __builtin_amdgcn_s_barrier()
; #define PG8_SCHED __builtin_amdgcn_sched_barrier(0)
; template <class Epi, class Sched, bool ALIGN_EPI = false, bool SP2 = false, bool A_TILED = false>
; __device__ __forceinline__ void gemm_phase(PG8_LAS unsigned char* lds, const Gemm g, const Sched& S, const Epi& E) {
;     ...
;             PG8_WAIT_V(8); PG8_WAIT_L(0); PG8_BAR; PG8_MMA(1, 0, At, B0); PG8_MMA(1, 1, At, B1); PG8_BAR; PG8_SCHED;
;             PG8_LDB(B0, 1, 0); PG8_LDB(B1, 1, 1); PG8_SCHED; PG8_LDA(At, 1, 0); PG8_STAGE(PG8_SA(0, 1), a2 + hstepA, voffA);
;             PG8_WAIT_V(8); PG8_WAIT_L(0); PG8_BAR; PG8_MMA(0, 0, At, B0); PG8_MMA(0, 1, At, B1); PG8_BAR; PG8_SCHED;
;             PG8_LDA(At, 1, 1); PG8_STAGE(PG8_SB(1, 0), b3, voffB); PG8_STAGE(PG8_SB(1, 1), b3 + hstepB, voffB); PG8_STAGE(PG8_SA(1, 0), a3, voffA);
.Lmy_skipw_34:
	s_waitcnt lgkmcnt(0)
	s_setprio 1
	s_barrier
	v_mfma_f32_16x16x32_bf16 v[62:65], v[142:145], v[180:183], 0
	v_mfma_f32_16x16x32_bf16 v[62:65], v[146:149], v[184:187], v[62:65]
	v_mfma_f32_16x16x32_bf16 v[58:61], v[150:153], v[180:183], 0
	v_mfma_f32_16x16x32_bf16 v[58:61], v[160:163], v[184:187], v[58:61]
	v_mfma_f32_16x16x32_bf16 v[50:53], v[164:167], v[180:183], 0
	v_mfma_f32_16x16x32_bf16 v[50:53], v[168:171], v[184:187], v[50:53]
	v_mfma_f32_16x16x32_bf16 v[42:45], v[172:175], v[180:183], 0
	v_mfma_f32_16x16x32_bf16 v[42:45], v[176:179], v[184:187], v[42:45]
	v_mfma_f32_16x16x32_bf16 v[54:57], v[142:145], v[188:191], 0
	v_mfma_f32_16x16x32_bf16 v[54:57], v[146:149], v[192:195], v[54:57]
	v_mfma_f32_16x16x32_bf16 v[46:49], v[150:153], v[188:191], 0
	v_mfma_f32_16x16x32_bf16 v[46:49], v[160:163], v[192:195], v[46:49]
	v_mfma_f32_16x16x32_bf16 v[34:37], v[164:167], v[188:191], 0
	v_mfma_f32_16x16x32_bf16 v[34:37], v[168:171], v[192:195], v[34:37]
	v_mfma_f32_16x16x32_bf16 v[26:29], v[172:175], v[188:191], 0
	v_mfma_f32_16x16x32_bf16 v[26:29], v[176:179], v[192:195], v[26:29]
	v_mfma_f32_16x16x32_bf16 v[38:41], v[142:145], v[196:199], 0
	v_mfma_f32_16x16x32_bf16 v[38:41], v[146:149], v[200:203], v[38:41]
	v_mfma_f32_16x16x32_bf16 v[30:33], v[150:153], v[196:199], 0
	v_mfma_f32_16x16x32_bf16 v[30:33], v[160:163], v[200:203], v[30:33]
	v_mfma_f32_16x16x32_bf16 v[18:21], v[164:167], v[196:199], 0
	v_mfma_f32_16x16x32_bf16 v[18:21], v[168:171], v[200:203], v[18:21]
	v_mfma_f32_16x16x32_bf16 v[10:13], v[172:175], v[196:199], 0
	v_mfma_f32_16x16x32_bf16 v[10:13], v[176:179], v[200:203], v[10:13]
	v_mfma_f32_16x16x32_bf16 v[22:25], v[142:145], v[204:207], 0
	v_mfma_f32_16x16x32_bf16 v[22:25], v[146:149], v[208:211], v[22:25]
	v_mfma_f32_16x16x32_bf16 v[14:17], v[150:153], v[204:207], 0
	v_mfma_f32_16x16x32_bf16 v[14:17], v[160:163], v[208:211], v[14:17]
	v_mfma_f32_16x16x32_bf16 v[6:9], v[164:167], v[204:207], 0
	v_mfma_f32_16x16x32_bf16 v[6:9], v[168:171], v[208:211], v[6:9]
	v_mfma_f32_16x16x32_bf16 v[2:5], v[172:175], v[204:207], 0
	v_mfma_f32_16x16x32_bf16 v[2:5], v[176:179], v[208:211], v[2:5]
	s_waitcnt vmcnt(8)
	s_barrier
	s_setprio 0
	s_add_i32 s59, 0, 0x18000
	s_add_i32 s60, 0, 0x1c000
	ds_read_b128 v[142:145], v156 offset:32768
	ds_read_b128 v[146:149], v156 offset:33792
	ds_read_b128 v[150:153], v156 offset:34816
	ds_read_b128 v[160:163], v156 offset:35840
	ds_read_b128 v[164:167], v156 offset:49152
	ds_read_b128 v[168:171], v156 offset:50176
	ds_read_b128 v[172:175], v156 offset:51200
	ds_read_b128 v[176:179], v156 offset:52224
	s_add_u32 s28, s28, 0x4000
	s_addc_u32 s29, s29, 0
	s_mov_b32 m0, s37
	ds_read_b128 v[180:183], v158 offset:32768
	ds_read_b128 v[184:187], v158 offset:33792
	ds_read_b128 v[188:191], v158 offset:34816
	ds_read_b128 v[192:195], v158 offset:35840
	ds_read_b128 v[196:199], v158 offset:36864
	ds_read_b128 v[200:203], v158 offset:37888
	ds_read_b128 v[204:207], v158 offset:38912
	ds_read_b128 v[208:211], v158 offset:39936
	global_load_lds_dwordx4 v130, s[28:29]
	s_mov_b32 m0, s38
	s_nop 0
	global_load_lds_dwordx4 v132, s[28:29]
	s_and_b64 vcc, exec, s[10:11]
	s_cbranch_vccnz .Lmy_skipw_35
	s_waitcnt vmcnt(8)
.Lmy_skipw_35:
	s_waitcnt lgkmcnt(0)
	s_setprio 1
	s_barrier
	v_mfma_f32_16x16x32_bf16 v[126:129], v[142:145], v[180:183], v[126:129]
	v_mfma_f32_16x16x32_bf16 v[126:129], v[146:149], v[184:187], v[126:129]
	v_mfma_f32_16x16x32_bf16 v[122:125], v[150:153], v[180:183], v[122:125]
	v_mfma_f32_16x16x32_bf16 v[122:125], v[160:163], v[184:187], v[122:125]
	v_mfma_f32_16x16x32_bf16 v[110:113], v[164:167], v[180:183], v[110:113]
	v_mfma_f32_16x16x32_bf16 v[110:113], v[168:171], v[184:187], v[110:113]
	v_mfma_f32_16x16x32_bf16 v[106:109], v[172:175], v[180:183], v[106:109]
	v_mfma_f32_16x16x32_bf16 v[106:109], v[176:179], v[184:187], v[106:109]
	v_mfma_f32_16x16x32_bf16 v[118:121], v[142:145], v[188:191], v[118:121]
	v_mfma_f32_16x16x32_bf16 v[118:121], v[146:149], v[192:195], v[118:121]
	v_mfma_f32_16x16x32_bf16 v[114:117], v[150:153], v[188:191], v[114:117]
	v_mfma_f32_16x16x32_bf16 v[114:117], v[160:163], v[192:195], v[114:117]
	v_mfma_f32_16x16x32_bf16 v[102:105], v[164:167], v[188:191], v[102:105]
	v_mfma_f32_16x16x32_bf16 v[102:105], v[168:171], v[192:195], v[102:105]
	v_mfma_f32_16x16x32_bf16 v[98:101], v[172:175], v[188:191], v[98:101]
	v_mfma_f32_16x16x32_bf16 v[98:101], v[176:179], v[192:195], v[98:101]
	v_mfma_f32_16x16x32_bf16 v[94:97], v[142:145], v[196:199], v[94:97]
	v_mfma_f32_16x16x32_bf16 v[94:97], v[146:149], v[200:203], v[94:97]
	v_mfma_f32_16x16x32_bf16 v[90:93], v[150:153], v[196:199], v[90:93]
	v_mfma_f32_16x16x32_bf16 v[90:93], v[160:163], v[200:203], v[90:93]
	v_mfma_f32_16x16x32_bf16 v[78:81], v[164:167], v[196:199], v[78:81]
	v_mfma_f32_16x16x32_bf16 v[78:81], v[168:171], v[200:203], v[78:81]
	v_mfma_f32_16x16x32_bf16 v[74:77], v[172:175], v[196:199], v[74:77]
	v_mfma_f32_16x16x32_bf16 v[74:77], v[176:179], v[200:203], v[74:77]
	v_mfma_f32_16x16x32_bf16 v[86:89], v[142:145], v[204:207], v[86:89]
	v_mfma_f32_16x16x32_bf16 v[86:89], v[146:149], v[208:211], v[86:89]
	v_mfma_f32_16x16x32_bf16 v[82:85], v[150:153], v[204:207], v[82:85]
	v_mfma_f32_16x16x32_bf16 v[82:85], v[160:163], v[208:211], v[82:85]
	v_mfma_f32_16x16x32_bf16 v[70:73], v[164:167], v[204:207], v[70:73]
	v_mfma_f32_16x16x32_bf16 v[70:73], v[168:171], v[208:211], v[70:73]
	v_mfma_f32_16x16x32_bf16 v[66:69], v[172:175], v[204:207], v[66:69]
	v_mfma_f32_16x16x32_bf16 v[66:69], v[176:179], v[208:211], v[66:69]
	s_waitcnt vmcnt(8)
	s_barrier
	s_setprio 0
	s_add_u32 s28, s26, 0x8000
	s_addc_u32 s29, s27, 0
	s_add_i32 s59, s59, s31
	s_mov_b32 m0, s59
	ds_read_b128 v[180:183], v158 offset:49152
	ds_read_b128 v[184:187], v158 offset:50176
	ds_read_b128 v[188:191], v158 offset:51200
	ds_read_b128 v[192:195], v158 offset:52224
	ds_read_b128 v[196:199], v158 offset:53248
	ds_read_b128 v[200:203], v158 offset:54272
	ds_read_b128 v[204:207], v158 offset:55296
	ds_read_b128 v[208:211], v158 offset:56320
	global_load_lds_dwordx4 v130, s[28:29]
	s_add_i32 m0, s59, 0x2000
	s_add_u32 s26, s26, 0xc000
	v_lshl_add_u64 v[212:213], s[28:29], 0, v[132:133]
	s_addc_u32 s27, s27, 0
	s_add_i32 s28, s60, s31
	global_load_lds_dwordx4 v[212:213], off
	s_mov_b32 m0, s28
	s_nop 0
	global_load_lds_dwordx4 v130, s[26:27]
	s_add_i32 m0, s28, 0x2000
	s_nop 0
	global_load_lds_dwordx4 v132, s[26:27]
	s_mov_b32 m0, s40
	s_nop 0
	global_load_lds_dwordx4 v130, s[24:25]
	s_mov_b32 m0, s41
	s_nop 0
	global_load_lds_dwordx4 v132, s[24:25]
	s_and_b64 vcc, exec, s[10:11]
	s_cbranch_vccnz .Lmy_skipw_36
	s_waitcnt vmcnt(8)
; #define PG8_STAGE(bufoff, gbase, voff) do { _Pragma("unroll") for (int _i = 0; _i < 2; ++_i) \
;         __builtin_amdgcn_global_load_lds((const unsigned*)((const char*)(gbase) + (voff)[_i]), (PG8_LAS unsigned*)(lds + (bufoff) + ldsw + _i * 8192), 16, 0, 0); } while (0)
; #define PG8_LDA(dst, b, h) do { _Pragma("unroll") for (int m = 0; m < 4; ++m) _Pragma("unroll") for (int k = 0; k < 2; ++k) dst[m][k] = *(const PG8_LAS bf16x8*)(lds + PG8_SA(b, h) + aoff + m * 2048 + k * 1024); } while (0)
; #define PG8_LDB(dst, b, h) do { _Pragma("unroll") for (int n = 0; n < 2; ++n) _Pragma("unroll") for (int k = 0; k < 2; ++k) dst[n][k] = *(const PG8_LAS bf16x8*)(lds + PG8_SB(b, h) + boff + n * 2048 + k * 1024); } while (0)
; #define PG8_MMA(ai, bj, At, Bt) do { __builtin_amdgcn_s_setprio(1); _Pragma("unroll") for (int m = 0; m < 4; ++m) _Pragma("unroll") for (int n = 0; n < 2; ++n) _Pragma("unroll") for (int k = 0; k < 2; ++k) \
;         acc[ai][bj][m][n] = __builtin_amdgcn_mfma_f32_16x16x32_bf16(Bt[n][k], At[m][k], acc[ai][bj][m][n], 0, 0, 0); __builtin_amdgcn_s_setprio(0); } while (0)
; #define PG8_WAIT_V(n) asm volatile("s_waitcnt vmcnt(" #n ")" ::: "memory")
; #define PG8_WAIT_L(n) asm volatile("s_waitcnt lgkmcnt(" #n ")" ::: "memory")
; #define PG8_BAR __builtin_amdgcn_s_barrier()
; #define PG8_SCHED __builtin_amdgcn_sched_barrier(0)
; template <class Epi, class Sched, bool ALIGN_EPI = false, bool SP2 = false, bool A_TILED = false>
; __device__ __forceinline__ void gemm_phase(PG8_LAS unsigned char* lds, const Gemm g, const Sched& S, const Epi& E) {
;     ...
;         for (int t = 0; t < nt; t += 2) {
;             const bool last = (t == nt - 2);
;             const char* a1 = cA + (size_t)(t + 1) * kstepA;
;             const char* a2 = last ? nA : cA + (size_t)(t + 2) * kstepA; const char* b2 = last ? nB : cB + (size_t)(t + 2) * kstepB;
;             const char* a3 = a2 + kstepA; const char* b3 = b2 + kstepB;
;             if (last && has_next) S.a_ready(nxt);
;             if constexpr (SP2) {
;             PG8_LDB(B0, 0, 0); PG8_LDB(B1, 0, 1); PG8_SCHED; PG8_LDA(At, 0, 0); PG8_STAGE(PG8_SA(1, 1), a1 + hstepA, voffA);
;             PG8_WAIT_V(8); PG8_WAIT_L(0); PG8_BAR; PG8_MMA(0, 0, At, B0); PG8_MMA(0, 1, At, B1); PG8_BAR; PG8_SCHED;
;     ...
;             PG8_WAIT_V(8); PG8_WAIT_L(0); PG8_BAR; PG8_MMA(1, 0, At, B0); PG8_MMA(1, 1, At, B1); PG8_BAR; PG8_SCHED;
.Lmy_skipw_36:
	s_waitcnt lgkmcnt(0)
	s_setprio 1
	s_barrier
	v_mfma_f32_16x16x32_bf16 v[62:65], v[142:145], v[180:183], v[62:65]
	v_mfma_f32_16x16x32_bf16 v[62:65], v[146:149], v[184:187], v[62:65]
	v_mfma_f32_16x16x32_bf16 v[58:61], v[150:153], v[180:183], v[58:61]
	v_mfma_f32_16x16x32_bf16 v[58:61], v[160:163], v[184:187], v[58:61]
	v_mfma_f32_16x16x32_bf16 v[50:53], v[164:167], v[180:183], v[50:53]
	v_mfma_f32_16x16x32_bf16 v[50:53], v[168:171], v[184:187], v[50:53]
	v_mfma_f32_16x16x32_bf16 v[42:45], v[172:175], v[180:183], v[42:45]
	v_mfma_f32_16x16x32_bf16 v[42:45], v[176:179], v[184:187], v[42:45]
	v_mfma_f32_16x16x32_bf16 v[54:57], v[142:145], v[188:191], v[54:57]
	v_mfma_f32_16x16x32_bf16 v[54:57], v[146:149], v[192:195], v[54:57]
	v_mfma_f32_16x16x32_bf16 v[46:49], v[150:153], v[188:191], v[46:49]
	v_mfma_f32_16x16x32_bf16 v[46:49], v[160:163], v[192:195], v[46:49]
	v_mfma_f32_16x16x32_bf16 v[34:37], v[164:167], v[188:191], v[34:37]
	v_mfma_f32_16x16x32_bf16 v[34:37], v[168:171], v[192:195], v[34:37]
	v_mfma_f32_16x16x32_bf16 v[26:29], v[172:175], v[188:191], v[26:29]
	v_mfma_f32_16x16x32_bf16 v[26:29], v[176:179], v[192:195], v[26:29]
	v_mfma_f32_16x16x32_bf16 v[38:41], v[142:145], v[196:199], v[38:41]
	v_mfma_f32_16x16x32_bf16 v[38:41], v[146:149], v[200:203], v[38:41]
	v_mfma_f32_16x16x32_bf16 v[30:33], v[150:153], v[196:199], v[30:33]
	v_mfma_f32_16x16x32_bf16 v[30:33], v[160:163], v[200:203], v[30:33]
	v_mfma_f32_16x16x32_bf16 v[18:21], v[164:167], v[196:199], v[18:21]
	v_mfma_f32_16x16x32_bf16 v[18:21], v[168:171], v[200:203], v[18:21]
	v_mfma_f32_16x16x32_bf16 v[10:13], v[172:175], v[196:199], v[10:13]
	v_mfma_f32_16x16x32_bf16 v[10:13], v[176:179], v[200:203], v[10:13]
	v_mfma_f32_16x16x32_bf16 v[22:25], v[142:145], v[204:207], v[22:25]
	v_mfma_f32_16x16x32_bf16 v[22:25], v[146:149], v[208:211], v[22:25]
	v_mfma_f32_16x16x32_bf16 v[14:17], v[150:153], v[204:207], v[14:17]
	v_mfma_f32_16x16x32_bf16 v[14:17], v[160:163], v[208:211], v[14:17]
	v_mfma_f32_16x16x32_bf16 v[6:9], v[164:167], v[204:207], v[6:9]
	v_mfma_f32_16x16x32_bf16 v[6:9], v[168:171], v[208:211], v[6:9]
	v_mfma_f32_16x16x32_bf16 v[2:5], v[172:175], v[204:207], v[2:5]
	v_mfma_f32_16x16x32_bf16 v[2:5], v[176:179], v[208:211], v[2:5]
	s_waitcnt vmcnt(8)
	s_barrier
	s_setprio 0
	s_add_i32 s58, s58, 2
	s_add_u32 s22, s22, 0x10000
	s_addc_u32 s23, s23, 0
	s_add_u32 s56, s56, 0x10000
	s_addc_u32 s57, s57, 0
.LBB0_1247:
	ds_read_b128 v[142:145], v156
	ds_read_b128 v[146:149], v156 offset:1024
	ds_read_b128 v[150:153], v156 offset:2048
	ds_read_b128 v[160:163], v156 offset:3072
	ds_read_b128 v[164:167], v157
	ds_read_b128 v[168:171], v157 offset:1024
	ds_read_b128 v[172:175], v157 offset:2048
	ds_read_b128 v[176:179], v157 offset:3072
	s_add_u32 s24, s22, 0x4000
	s_addc_u32 s25, s23, 0
	s_cmpk_eq_i32 s58, 0xa8
	s_cselect_b32 s28, s4, s24
	s_cselect_b32 s29, s5, s25
	s_cselect_b32 s26, s20, s56
	s_cselect_b32 s27, s21, s57
	s_add_u32 s24, s28, 0x8000
	s_addc_u32 s25, s29, 0
	s_add_i32 m0, s35, 0xc000
	ds_read_b128 v[180:183], v158
	ds_read_b128 v[184:187], v158 offset:1024
	ds_read_b128 v[188:191], v158 offset:2048
	ds_read_b128 v[192:195], v158 offset:3072
	ds_read_b128 v[196:199], v158 offset:4096
	ds_read_b128 v[200:203], v158 offset:5120
	ds_read_b128 v[204:207], v158 offset:6144
	ds_read_b128 v[208:211], v158 offset:7168
	global_load_lds_dwordx4 v134, s[22:23]
	s_add_i32 m0, s35, 0xe000
	s_nop 0
	global_load_lds_dwordx4 v136, s[22:23]
	s_and_b64 vcc, exec, s[10:11]
	s_cbranch_vccnz .Lmy_skipw_37
	s_waitcnt vmcnt(8)
; #define PG8_STAGE(bufoff, gbase, voff) do { _Pragma("unroll") for (int _i = 0; _i < 2; ++_i) \
;         __builtin_amdgcn_global_load_lds((const unsigned*)((const char*)(gbase) + (voff)[_i]), (PG8_LAS unsigned*)(lds + (bufoff) + ldsw + _i * 8192), 16, 0, 0); } while (0)
; #define PG8_LDA(dst, b, h) do { _Pragma("unroll") for (int m = 0; m < 4; ++m) _Pragma("unroll") for (int k = 0; k < 2; ++k) dst[m][k] = *(const PG8_LAS bf16x8*)(lds + PG8_SA(b, h) + aoff + m * 2048 + k * 1024); } while (0)
; #define PG8_LDB(dst, b, h) do { _Pragma("unroll") for (int n = 0; n < 2; ++n) _Pragma("unroll") for (int k = 0; k < 2; ++k) dst[n][k] = *(const PG8_LAS bf16x8*)(lds + PG8_SB(b, h) + boff + n * 2048 + k * 1024); } while (0)
; #define PG8_MMA(ai, bj, At, Bt) do { __builtin_amdgcn_s_setprio(1); _Pragma("unroll") for (int m = 0; m < 4; ++m) _Pragma("unroll") for (int n = 0; n < 2; ++n) _Pragma("unroll") for (int k = 0; k < 2; ++k) \
;         acc[ai][bj][m][n] = __builtin_amdgcn_mfma_f32_16x16x32_bf16(Bt[n][k], At[m][k], acc[ai][bj][m][n], 0, 0, 0); __builtin_amdgcn_s_setprio(0); } while (0)
; #define PG8_WAIT_V(n) asm volatile("s_waitcnt vmcnt(" #n ")" ::: "memory")
; #define PG8_WAIT_L(n) asm volatile("s_waitcnt lgkmcnt(" #n ")" ::: "memory")
; #define PG8_BAR __builtin_amdgcn_s_barrier()
; #define PG8_SCHED __builtin_amdgcn_sched_barrier(0)
; template <class Epi, class Sched, bool ALIGN_EPI = false, bool SP2 = false, bool A_TILED = false>
; __device__ __forceinline__ void gemm_phase(PG8_LAS unsigned char* lds, const Gemm g, const Sched& S, const Epi& E) {
;     ...
;             PG8_WAIT_V(8); PG8_WAIT_L(0); PG8_BAR; PG8_MMA(0, 0, At, B0); PG8_MMA(0, 1, At, B1); PG8_BAR; PG8_SCHED;
;             PG8_LDA(At, 0, 1); PG8_STAGE(PG8_SB(0, 0), b2, voffB); PG8_STAGE(PG8_SB(0, 1), b2 + hstepB, voffB); PG8_STAGE(PG8_SA(0, 0), a2, voffA);
;             PG8_WAIT_V(8); PG8_WAIT_L(0); PG8_BAR; PG8_MMA(1, 0, At, B0); PG8_MMA(1, 1, At, B1); PG8_BAR; PG8_SCHED;
;             PG8_LDB(B0, 1, 0); PG8_LDB(B1, 1, 1); PG8_SCHED; PG8_LDA(At, 1, 0); PG8_STAGE(PG8_SA(0, 1), a2 + hstepA, voffA);
;             PG8_WAIT_V(8); PG8_WAIT_L(0); PG8_BAR; PG8_MMA(0, 0, At, B0); PG8_MMA(0, 1, At, B1); PG8_BAR; PG8_SCHED;
;             PG8_LDA(At, 1, 1); PG8_STAGE(PG8_SB(1, 0), b3, voffB); PG8_STAGE(PG8_SB(1, 1), b3 + hstepB, voffB); PG8_STAGE(PG8_SA(1, 0), a3, voffA);
.Lmy_skipw_37:
	s_waitcnt lgkmcnt(0)
	s_barrier
	s_setprio 1
	s_waitcnt lgkmcnt(0)
	v_mfma_f32_16x16x32_bf16 v[126:129], v[142:145], v[180:183], v[126:129]
	v_mfma_f32_16x16x32_bf16 v[122:125], v[150:153], v[180:183], v[122:125]
	v_mfma_f32_16x16x32_bf16 v[118:121], v[142:145], v[188:191], v[118:121]
	v_mfma_f32_16x16x32_bf16 v[114:117], v[150:153], v[188:191], v[114:117]
	v_mfma_f32_16x16x32_bf16 v[94:97], v[142:145], v[196:199], v[94:97]
	v_mfma_f32_16x16x32_bf16 v[90:93], v[150:153], v[196:199], v[90:93]
	v_mfma_f32_16x16x32_bf16 v[86:89], v[142:145], v[204:207], v[86:89]
	v_mfma_f32_16x16x32_bf16 v[82:85], v[150:153], v[204:207], v[82:85]
	v_mfma_f32_16x16x32_bf16 v[126:129], v[146:149], v[184:187], v[126:129]
	v_mfma_f32_16x16x32_bf16 v[122:125], v[160:163], v[184:187], v[122:125]
	v_mfma_f32_16x16x32_bf16 v[118:121], v[146:149], v[192:195], v[118:121]
	v_mfma_f32_16x16x32_bf16 v[114:117], v[160:163], v[192:195], v[114:117]
	v_mfma_f32_16x16x32_bf16 v[94:97], v[146:149], v[200:203], v[94:97]
	v_mfma_f32_16x16x32_bf16 v[90:93], v[160:163], v[200:203], v[90:93]
	v_mfma_f32_16x16x32_bf16 v[86:89], v[146:149], v[208:211], v[86:89]
	v_mfma_f32_16x16x32_bf16 v[82:85], v[160:163], v[208:211], v[82:85]
	s_setprio 0
	s_setprio 1
	v_mfma_f32_16x16x32_bf16 v[110:113], v[164:167], v[180:183], v[110:113]
	v_mfma_f32_16x16x32_bf16 v[106:109], v[172:175], v[180:183], v[106:109]
	v_mfma_f32_16x16x32_bf16 v[102:105], v[164:167], v[188:191], v[102:105]
	v_mfma_f32_16x16x32_bf16 v[98:101], v[172:175], v[188:191], v[98:101]
	v_mfma_f32_16x16x32_bf16 v[78:81], v[164:167], v[196:199], v[78:81]
	v_mfma_f32_16x16x32_bf16 v[74:77], v[172:175], v[196:199], v[74:77]
	v_mfma_f32_16x16x32_bf16 v[70:73], v[164:167], v[204:207], v[70:73]
	v_mfma_f32_16x16x32_bf16 v[66:69], v[172:175], v[204:207], v[66:69]
	v_mfma_f32_16x16x32_bf16 v[110:113], v[168:171], v[184:187], v[110:113]
	v_mfma_f32_16x16x32_bf16 v[106:109], v[176:179], v[184:187], v[106:109]
	v_mfma_f32_16x16x32_bf16 v[102:105], v[168:171], v[192:195], v[102:105]
	v_mfma_f32_16x16x32_bf16 v[98:101], v[176:179], v[192:195], v[98:101]
	v_mfma_f32_16x16x32_bf16 v[78:81], v[168:171], v[200:203], v[78:81]
	v_mfma_f32_16x16x32_bf16 v[74:77], v[176:179], v[200:203], v[74:77]
	v_mfma_f32_16x16x32_bf16 v[70:73], v[168:171], v[208:211], v[70:73]
	v_mfma_f32_16x16x32_bf16 v[66:69], v[176:179], v[208:211], v[66:69]
	s_setprio 0
	s_waitcnt vmcnt(8)
	s_barrier
	s_add_i32 s59, s42, s31
	s_mov_b32 m0, s59
	ds_read_b128 v[180:183], v158 offset:16384
	ds_read_b128 v[184:187], v158 offset:17408
	ds_read_b128 v[188:191], v158 offset:18432
	ds_read_b128 v[192:195], v158 offset:19456
	ds_read_b128 v[196:199], v158 offset:20480
	ds_read_b128 v[200:203], v158 offset:21504
	ds_read_b128 v[204:207], v158 offset:22528
	ds_read_b128 v[208:211], v158 offset:23552
	global_load_lds_dwordx4 v130, s[26:27]
	s_add_i32 m0, s59, 0x2000
	s_add_u32 s60, s26, 0x4000
	s_addc_u32 s61, s27, 0
	s_add_i32 s59, s43, s31
	global_load_lds_dwordx4 v132, s[26:27]
	s_mov_b32 m0, s59
	s_nop 0
	global_load_lds_dwordx4 v130, s[60:61]
	s_add_i32 m0, s59, 0x2000
	s_nop 0
	global_load_lds_dwordx4 v132, s[60:61]
	s_mov_b32 m0, s35
	s_nop 0
	global_load_lds_dwordx4 v130, s[28:29]
	s_mov_b32 m0, s36
	s_nop 0
	global_load_lds_dwordx4 v132, s[28:29]
	s_and_b64 vcc, exec, s[10:11]
	s_cbranch_vccnz .Lmy_skipw_38
	s_waitcnt vmcnt(8)
.Lmy_skipw_38:
	s_waitcnt lgkmcnt(0)
	s_setprio 1
	s_barrier
	v_mfma_f32_16x16x32_bf16 v[62:65], v[142:145], v[180:183], v[62:65]
	v_mfma_f32_16x16x32_bf16 v[62:65], v[146:149], v[184:187], v[62:65]
	v_mfma_f32_16x16x32_bf16 v[58:61], v[150:153], v[180:183], v[58:61]
	v_mfma_f32_16x16x32_bf16 v[58:61], v[160:163], v[184:187], v[58:61]
	v_mfma_f32_16x16x32_bf16 v[50:53], v[164:167], v[180:183], v[50:53]
	v_mfma_f32_16x16x32_bf16 v[50:53], v[168:171], v[184:187], v[50:53]
	v_mfma_f32_16x16x32_bf16 v[42:45], v[172:175], v[180:183], v[42:45]
	v_mfma_f32_16x16x32_bf16 v[42:45], v[176:179], v[184:187], v[42:45]
	v_mfma_f32_16x16x32_bf16 v[54:57], v[142:145], v[188:191], v[54:57]
	v_mfma_f32_16x16x32_bf16 v[54:57], v[146:149], v[192:195], v[54:57]
	v_mfma_f32_16x16x32_bf16 v[46:49], v[150:153], v[188:191], v[46:49]
	v_mfma_f32_16x16x32_bf16 v[46:49], v[160:163], v[192:195], v[46:49]
	v_mfma_f32_16x16x32_bf16 v[34:37], v[164:167], v[188:191], v[34:37]
	v_mfma_f32_16x16x32_bf16 v[34:37], v[168:171], v[192:195], v[34:37]
	v_mfma_f32_16x16x32_bf16 v[26:29], v[172:175], v[188:191], v[26:29]
	v_mfma_f32_16x16x32_bf16 v[26:29], v[176:179], v[192:195], v[26:29]
	v_mfma_f32_16x16x32_bf16 v[38:41], v[142:145], v[196:199], v[38:41]
	v_mfma_f32_16x16x32_bf16 v[38:41], v[146:149], v[200:203], v[38:41]
	v_mfma_f32_16x16x32_bf16 v[30:33], v[150:153], v[196:199], v[30:33]
	v_mfma_f32_16x16x32_bf16 v[30:33], v[160:163], v[200:203], v[30:33]
	v_mfma_f32_16x16x32_bf16 v[18:21], v[164:167], v[196:199], v[18:21]
	v_mfma_f32_16x16x32_bf16 v[18:21], v[168:171], v[200:203], v[18:21]
	v_mfma_f32_16x16x32_bf16 v[10:13], v[172:175], v[196:199], v[10:13]
	v_mfma_f32_16x16x32_bf16 v[10:13], v[176:179], v[200:203], v[10:13]
	v_mfma_f32_16x16x32_bf16 v[22:25], v[142:145], v[204:207], v[22:25]
	v_mfma_f32_16x16x32_bf16 v[22:25], v[146:149], v[208:211], v[22:25]
	v_mfma_f32_16x16x32_bf16 v[14:17], v[150:153], v[204:207], v[14:17]
	v_mfma_f32_16x16x32_bf16 v[14:17], v[160:163], v[208:211], v[14:17]
	v_mfma_f32_16x16x32_bf16 v[6:9], v[164:167], v[204:207], v[6:9]
	v_mfma_f32_16x16x32_bf16 v[6:9], v[168:171], v[208:211], v[6:9]
	v_mfma_f32_16x16x32_bf16 v[2:5], v[172:175], v[204:207], v[2:5]
	v_mfma_f32_16x16x32_bf16 v[2:5], v[176:179], v[208:211], v[2:5]
	s_waitcnt vmcnt(8)
	s_barrier
	s_setprio 0
	s_add_i32 s59, 0, 0x18000
	s_add_i32 s60, 0, 0x1c000
	ds_read_b128 v[142:145], v156 offset:32768
	ds_read_b128 v[146:149], v156 offset:33792
	ds_read_b128 v[150:153], v156 offset:34816
	ds_read_b128 v[160:163], v156 offset:35840
	ds_read_b128 v[164:167], v156 offset:49152
	ds_read_b128 v[168:171], v156 offset:50176
	ds_read_b128 v[172:175], v156 offset:51200
	ds_read_b128 v[176:179], v156 offset:52224
	s_add_u32 s28, s28, 0x4000
	s_addc_u32 s29, s29, 0
	s_mov_b32 m0, s37
	ds_read_b128 v[180:183], v158 offset:32768
	ds_read_b128 v[184:187], v158 offset:33792
	ds_read_b128 v[188:191], v158 offset:34816
	ds_read_b128 v[192:195], v158 offset:35840
	ds_read_b128 v[196:199], v158 offset:36864
	ds_read_b128 v[200:203], v158 offset:37888
	ds_read_b128 v[204:207], v158 offset:38912
	ds_read_b128 v[208:211], v158 offset:39936
	global_load_lds_dwordx4 v130, s[28:29]
	s_mov_b32 m0, s38
	s_nop 0
	global_load_lds_dwordx4 v132, s[28:29]
	s_and_b64 vcc, exec, s[10:11]
	s_cbranch_vccnz .Lmy_skipw_39
	s_waitcnt vmcnt(8)

; #define PG8_STAGE(bufoff, gbase, voff) do { _Pragma("unroll") for (int _i = 0; _i < 2; ++_i) \
;         __builtin_amdgcn_global_load_lds((const unsigned*)((const char*)(gbase) + (voff)[_i]), (PG8_LAS unsigned*)(lds + (bufoff) + ldsw + _i * 8192), 16, 0, 0); } while (0)
; #define PG8_LDA(dst, b, h) do { _Pragma("unroll") for (int m = 0; m < 4; ++m) _Pragma("unroll") for (int k = 0; k < 2; ++k) dst[m][k] = *(const PG8_LAS bf16x8*)(lds + PG8_SA(b, h) + aoff + m * 2048 + k * 1024); } while (0)
; #define PG8_MMA(ai, bj, At, Bt) do { __builtin_amdgcn_s_setprio(1); _Pragma("unroll") for (int m = 0; m < 4; ++m) _Pragma("unroll") for (int n = 0; n < 2; ++n) _Pragma("unroll") for (int k = 0; k < 2; ++k) \
;         acc[ai][bj][m][n] = __builtin_amdgcn_mfma_f32_16x16x32_bf16(Bt[n][k], At[m][k], acc[ai][bj][m][n], 0, 0, 0); __builtin_amdgcn_s_setprio(0); } while (0)
; #define PG8_WAIT_V(n) asm volatile("s_waitcnt vmcnt(" #n ")" ::: "memory")
; #define PG8_WAIT_L(n) asm volatile("s_waitcnt lgkmcnt(" #n ")" ::: "memory")
; #define PG8_BAR __builtin_amdgcn_s_barrier()
; #define PG8_SCHED __builtin_amdgcn_sched_barrier(0)
; template <class Epi, class Sched, bool ALIGN_EPI = false, bool SP2 = false, bool A_TILED = false>
; __device__ __forceinline__ void gemm_phase(PG8_LAS unsigned char* lds, const Gemm g, const Sched& S, const Epi& E) {
;     ...
;             PG8_LDA(At, 1, 1); PG8_STAGE(PG8_SB(1, 0), b3, voffB); PG8_STAGE(PG8_SB(1, 1), b3 + hstepB, voffB); PG8_STAGE(PG8_SA(1, 0), a3, voffA);
;             PG8_WAIT_V(8); PG8_WAIT_L(0); PG8_BAR; PG8_MMA(1, 0, At, B0); PG8_MMA(1, 1, At, B1); PG8_BAR; PG8_SCHED;
.Lmy_skipw_40:
	s_waitcnt lgkmcnt(0)
	s_setprio 1
	s_barrier
	v_mfma_f32_16x16x32_bf16 v[62:65], v[142:145], v[180:183], v[62:65]
	v_mfma_f32_16x16x32_bf16 v[62:65], v[146:149], v[184:187], v[62:65]
	v_mfma_f32_16x16x32_bf16 v[58:61], v[150:153], v[180:183], v[58:61]
	v_mfma_f32_16x16x32_bf16 v[58:61], v[160:163], v[184:187], v[58:61]
	v_mfma_f32_16x16x32_bf16 v[50:53], v[164:167], v[180:183], v[50:53]
	v_mfma_f32_16x16x32_bf16 v[50:53], v[168:171], v[184:187], v[50:53]
	v_mfma_f32_16x16x32_bf16 v[42:45], v[172:175], v[180:183], v[42:45]
	v_mfma_f32_16x16x32_bf16 v[42:45], v[176:179], v[184:187], v[42:45]
	v_mfma_f32_16x16x32_bf16 v[54:57], v[142:145], v[188:191], v[54:57]
	v_mfma_f32_16x16x32_bf16 v[54:57], v[146:149], v[192:195], v[54:57]
	v_mfma_f32_16x16x32_bf16 v[46:49], v[150:153], v[188:191], v[46:49]
	v_mfma_f32_16x16x32_bf16 v[46:49], v[160:163], v[192:195], v[46:49]
	v_mfma_f32_16x16x32_bf16 v[34:37], v[164:167], v[188:191], v[34:37]
	v_mfma_f32_16x16x32_bf16 v[34:37], v[168:171], v[192:195], v[34:37]
	v_mfma_f32_16x16x32_bf16 v[26:29], v[172:175], v[188:191], v[26:29]
	v_mfma_f32_16x16x32_bf16 v[26:29], v[176:179], v[192:195], v[26:29]
	v_mfma_f32_16x16x32_bf16 v[38:41], v[142:145], v[196:199], v[38:41]
	v_mfma_f32_16x16x32_bf16 v[38:41], v[146:149], v[200:203], v[38:41]
	v_mfma_f32_16x16x32_bf16 v[30:33], v[150:153], v[196:199], v[30:33]
	v_mfma_f32_16x16x32_bf16 v[30:33], v[160:163], v[200:203], v[30:33]
	v_mfma_f32_16x16x32_bf16 v[18:21], v[164:167], v[196:199], v[18:21]
	v_mfma_f32_16x16x32_bf16 v[18:21], v[168:171], v[200:203], v[18:21]
	v_mfma_f32_16x16x32_bf16 v[10:13], v[172:175], v[196:199], v[10:13]
	v_mfma_f32_16x16x32_bf16 v[10:13], v[176:179], v[200:203], v[10:13]
	v_mfma_f32_16x16x32_bf16 v[22:25], v[142:145], v[204:207], v[22:25]
	v_mfma_f32_16x16x32_bf16 v[22:25], v[146:149], v[208:211], v[22:25]
	v_mfma_f32_16x16x32_bf16 v[14:17], v[150:153], v[204:207], v[14:17]
	v_mfma_f32_16x16x32_bf16 v[14:17], v[160:163], v[208:211], v[14:17]
	v_mfma_f32_16x16x32_bf16 v[6:9], v[164:167], v[204:207], v[6:9]
	v_mfma_f32_16x16x32_bf16 v[6:9], v[168:171], v[208:211], v[6:9]
	v_mfma_f32_16x16x32_bf16 v[2:5], v[172:175], v[204:207], v[2:5]
	v_mfma_f32_16x16x32_bf16 v[2:5], v[176:179], v[208:211], v[2:5]
	s_waitcnt vmcnt(8)
	s_barrier
	s_setprio 0
	s_add_i32 s58, s58, 2
	s_add_u32 s22, s22, 0x10000
	s_addc_u32 s23, s23, 0
	s_add_u32 s56, s56, 0x10000
	s_addc_u32 s57, s57, 0
	s_cmpk_gt_u32 s58, 0xa9
	s_cbranch_scc0 .LBB0_1247
	s_and_b64 vcc, exec, s[10:11]
	s_cbranch_vccz .LBB0_1250
	s_barrier
